# k-loops: one LDS-DMA piece per four MFMAs on the saddr form
# speedup vs baseline: 1.0039x; 1.0039x over previous
.Lg0_top:
	s_waitcnt lgkmcnt(0)
	s_waitcnt vmcnt(0)
	s_barrier
	v_xor_b32_e32 v143, 0x10000, v143
	v_xor_b32_e32 v180, 0x10000, v180
	v_xor_b32_e32 v155, 0x10000, v155
	v_xor_b32_e32 v222, 0x10000, v222
	s_xor_b32 s87, s87, 0x10000
	ds_read_b128 v[156:159], v143
	ds_read_b128 v[160:163], v143 offset:2048
	ds_read_b128 v[164:167], v143 offset:4096
	ds_read_b128 v[168:171], v143 offset:6144
	ds_read_b128 v[190:193], v180 offset:32768
	ds_read_b128 v[194:197], v180 offset:34816
	ds_read_b128 v[198:201], v180 offset:36864
	ds_read_b128 v[202:205], v180 offset:38912
	v_mfma_f32_16x16x32_bf16 v[60:63], v[172:175], v[206:209], v[60:63]
	v_mfma_f32_16x16x32_bf16 v[52:55], v[172:175], v[210:213], v[52:55]
	v_mfma_f32_16x16x32_bf16 v[56:59], v[172:175], v[214:217], v[56:59]
	v_mfma_f32_16x16x32_bf16 v[48:51], v[172:175], v[218:221], v[48:51]
	s_mov_b32 m0, s87
	s_add_u32 s88, s60, s16
	s_addc_u32 s89, s61, s17
	global_load_lds_dwordx4 v144, s[88:89]
	v_mfma_f32_16x16x32_bf16 v[44:47], v[176:179], v[206:209], v[44:47]
	v_mfma_f32_16x16x32_bf16 v[36:39], v[176:179], v[210:213], v[36:39]
	v_mfma_f32_16x16x32_bf16 v[40:43], v[176:179], v[214:217], v[40:43]
	v_mfma_f32_16x16x32_bf16 v[32:35], v[176:179], v[218:221], v[32:35]
	s_add_u32 m0, s87, 0x2000
	s_add_u32 s88, s60, s18
	s_addc_u32 s89, s61, s19
	global_load_lds_dwordx4 v144, s[88:89]
	v_mfma_f32_16x16x32_bf16 v[28:31], v[182:185], v[206:209], v[28:31]
	v_mfma_f32_16x16x32_bf16 v[16:19], v[182:185], v[210:213], v[16:19]
	v_mfma_f32_16x16x32_bf16 v[24:27], v[182:185], v[214:217], v[24:27]
	v_mfma_f32_16x16x32_bf16 v[12:15], v[182:185], v[218:221], v[12:15]
	s_add_u32 m0, s87, 0x4000
	s_add_u32 s88, s60, s22
	s_addc_u32 s89, s61, s23
	global_load_lds_dwordx4 v144, s[88:89]
	v_mfma_f32_16x16x32_bf16 v[4:7], v[186:189], v[206:209], v[4:7]
	v_mfma_f32_16x16x32_bf16 v[0:3], v[186:189], v[210:213], v[0:3]
	v_mfma_f32_16x16x32_bf16 v[20:23], v[186:189], v[214:217], v[20:23]
	v_mfma_f32_16x16x32_bf16 v[8:11], v[186:189], v[218:221], v[8:11]
	s_add_u32 m0, s87, 0x6000
	s_add_u32 s88, s60, s40
	s_addc_u32 s89, s61, s41
	global_load_lds_dwordx4 v144, s[88:89]
.Lg0_entry:
	ds_read_b128 v[172:175], v143 offset:8192
	ds_read_b128 v[176:179], v143 offset:10240
	ds_read_b128 v[182:185], v143 offset:12288
	ds_read_b128 v[186:189], v143 offset:14336
	s_waitcnt lgkmcnt(4)
	v_mfma_f32_16x16x32_bf16 v[124:127], v[156:159], v[190:193], v[124:127]
	v_mfma_f32_16x16x32_bf16 v[116:119], v[156:159], v[194:197], v[116:119]
	v_mfma_f32_16x16x32_bf16 v[120:123], v[156:159], v[198:201], v[120:123]
	v_mfma_f32_16x16x32_bf16 v[112:115], v[156:159], v[202:205], v[112:115]
	s_add_u32 m0, s87, 0x8000
	s_add_u32 s88, s60, s42
	s_addc_u32 s89, s61, s43
	global_load_lds_dwordx4 v145, s[88:89]
	v_mfma_f32_16x16x32_bf16 v[108:111], v[160:163], v[190:193], v[108:111]
	v_mfma_f32_16x16x32_bf16 v[100:103], v[160:163], v[194:197], v[100:103]
	v_mfma_f32_16x16x32_bf16 v[104:107], v[160:163], v[198:201], v[104:107]
	v_mfma_f32_16x16x32_bf16 v[96:99], v[160:163], v[202:205], v[96:99]
	s_add_u32 m0, s87, 0xa000
	s_add_u32 s88, s60, s52
	s_addc_u32 s89, s61, s53
	global_load_lds_dwordx4 v145, s[88:89]
	v_mfma_f32_16x16x32_bf16 v[92:95], v[164:167], v[190:193], v[92:95]
	v_mfma_f32_16x16x32_bf16 v[84:87], v[164:167], v[194:197], v[84:87]
	v_mfma_f32_16x16x32_bf16 v[88:91], v[164:167], v[198:201], v[88:91]
	v_mfma_f32_16x16x32_bf16 v[80:83], v[164:167], v[202:205], v[80:83]
	s_add_u32 m0, s87, 0xc000
	s_add_u32 s88, s60, s54
	s_addc_u32 s89, s61, s55
	global_load_lds_dwordx4 v145, s[88:89]
	v_mfma_f32_16x16x32_bf16 v[76:79], v[168:171], v[190:193], v[76:79]
	v_mfma_f32_16x16x32_bf16 v[68:71], v[168:171], v[194:197], v[68:71]
	v_mfma_f32_16x16x32_bf16 v[72:75], v[168:171], v[198:201], v[72:75]
	v_mfma_f32_16x16x32_bf16 v[64:67], v[168:171], v[202:205], v[64:67]
	s_add_u32 m0, s87, 0xe000
	s_add_u32 s88, s60, s56
	s_addc_u32 s89, s61, s57
	global_load_lds_dwordx4 v145, s[88:89]
	ds_read_b128 v[156:159], v155
	ds_read_b128 v[160:163], v155 offset:2048
	ds_read_b128 v[164:167], v155 offset:4096
	ds_read_b128 v[168:171], v155 offset:6144
	ds_read_b128 v[206:209], v222 offset:32768
	ds_read_b128 v[210:213], v222 offset:34816
	ds_read_b128 v[214:217], v222 offset:36864
	ds_read_b128 v[218:221], v222 offset:38912
	s_waitcnt lgkmcnt(8)
	v_mfma_f32_16x16x32_bf16 v[60:63], v[172:175], v[190:193], v[60:63]
	v_mfma_f32_16x16x32_bf16 v[52:55], v[172:175], v[194:197], v[52:55]
	v_mfma_f32_16x16x32_bf16 v[56:59], v[172:175], v[198:201], v[56:59]
	v_mfma_f32_16x16x32_bf16 v[48:51], v[172:175], v[202:205], v[48:51]
	v_mfma_f32_16x16x32_bf16 v[44:47], v[176:179], v[190:193], v[44:47]
	v_mfma_f32_16x16x32_bf16 v[36:39], v[176:179], v[194:197], v[36:39]
	v_mfma_f32_16x16x32_bf16 v[40:43], v[176:179], v[198:201], v[40:43]
	v_mfma_f32_16x16x32_bf16 v[32:35], v[176:179], v[202:205], v[32:35]
	v_mfma_f32_16x16x32_bf16 v[28:31], v[182:185], v[190:193], v[28:31]
	v_mfma_f32_16x16x32_bf16 v[16:19], v[182:185], v[194:197], v[16:19]
	v_mfma_f32_16x16x32_bf16 v[24:27], v[182:185], v[198:201], v[24:27]
	v_mfma_f32_16x16x32_bf16 v[12:15], v[182:185], v[202:205], v[12:15]
	v_mfma_f32_16x16x32_bf16 v[4:7], v[186:189], v[190:193], v[4:7]
	v_mfma_f32_16x16x32_bf16 v[0:3], v[186:189], v[194:197], v[0:3]
	v_mfma_f32_16x16x32_bf16 v[20:23], v[186:189], v[198:201], v[20:23]
	v_mfma_f32_16x16x32_bf16 v[8:11], v[186:189], v[202:205], v[8:11]
	ds_read_b128 v[172:175], v155 offset:8192
	ds_read_b128 v[176:179], v155 offset:10240
	ds_read_b128 v[182:185], v155 offset:12288
	ds_read_b128 v[186:189], v155 offset:14336
	s_waitcnt lgkmcnt(4)
	v_mfma_f32_16x16x32_bf16 v[124:127], v[156:159], v[206:209], v[124:127]
	v_mfma_f32_16x16x32_bf16 v[116:119], v[156:159], v[210:213], v[116:119]
	v_mfma_f32_16x16x32_bf16 v[120:123], v[156:159], v[214:217], v[120:123]
	v_mfma_f32_16x16x32_bf16 v[112:115], v[156:159], v[218:221], v[112:115]
	v_mfma_f32_16x16x32_bf16 v[108:111], v[160:163], v[206:209], v[108:111]
	v_mfma_f32_16x16x32_bf16 v[100:103], v[160:163], v[210:213], v[100:103]
	v_mfma_f32_16x16x32_bf16 v[104:107], v[160:163], v[214:217], v[104:107]
	v_mfma_f32_16x16x32_bf16 v[96:99], v[160:163], v[218:221], v[96:99]
	v_mfma_f32_16x16x32_bf16 v[92:95], v[164:167], v[206:209], v[92:95]
	v_mfma_f32_16x16x32_bf16 v[84:87], v[164:167], v[210:213], v[84:87]
	v_mfma_f32_16x16x32_bf16 v[88:91], v[164:167], v[214:217], v[88:91]
	v_mfma_f32_16x16x32_bf16 v[80:83], v[164:167], v[218:221], v[80:83]
	v_mfma_f32_16x16x32_bf16 v[76:79], v[168:171], v[206:209], v[76:79]
	v_mfma_f32_16x16x32_bf16 v[68:71], v[168:171], v[210:213], v[68:71]
	v_mfma_f32_16x16x32_bf16 v[72:75], v[168:171], v[214:217], v[72:75]
	v_mfma_f32_16x16x32_bf16 v[64:67], v[168:171], v[218:221], v[64:67]
	s_add_u32 s60, s60, 0x80
	s_addc_u32 s61, s61, 0
	s_add_i32 s59, s59, 1
	s_cmp_lt_u32 s59, 15
	s_cbranch_scc1 .Lg0_top
	s_waitcnt lgkmcnt(0)
	s_waitcnt vmcnt(0)
	s_barrier
	v_xor_b32_e32 v143, 0x10000, v143
	v_xor_b32_e32 v180, 0x10000, v180
	v_xor_b32_e32 v155, 0x10000, v155
	v_xor_b32_e32 v222, 0x10000, v222
	s_xor_b32 s87, s87, 0x10000
	ds_read_b128 v[156:159], v143
	ds_read_b128 v[160:163], v143 offset:2048
	ds_read_b128 v[164:167], v143 offset:4096
	ds_read_b128 v[168:171], v143 offset:6144
	ds_read_b128 v[190:193], v180 offset:32768
	ds_read_b128 v[194:197], v180 offset:34816
	ds_read_b128 v[198:201], v180 offset:36864
	ds_read_b128 v[202:205], v180 offset:38912
	v_mfma_f32_16x16x32_bf16 v[60:63], v[172:175], v[206:209], v[60:63]
	v_mfma_f32_16x16x32_bf16 v[52:55], v[172:175], v[210:213], v[52:55]
	v_mfma_f32_16x16x32_bf16 v[56:59], v[172:175], v[214:217], v[56:59]
	v_mfma_f32_16x16x32_bf16 v[48:51], v[172:175], v[218:221], v[48:51]
	v_mfma_f32_16x16x32_bf16 v[44:47], v[176:179], v[206:209], v[44:47]
	v_mfma_f32_16x16x32_bf16 v[36:39], v[176:179], v[210:213], v[36:39]
	v_mfma_f32_16x16x32_bf16 v[40:43], v[176:179], v[214:217], v[40:43]
	v_mfma_f32_16x16x32_bf16 v[32:35], v[176:179], v[218:221], v[32:35]
	v_mfma_f32_16x16x32_bf16 v[28:31], v[182:185], v[206:209], v[28:31]
	v_mfma_f32_16x16x32_bf16 v[16:19], v[182:185], v[210:213], v[16:19]
	v_mfma_f32_16x16x32_bf16 v[24:27], v[182:185], v[214:217], v[24:27]
	v_mfma_f32_16x16x32_bf16 v[12:15], v[182:185], v[218:221], v[12:15]
	v_mfma_f32_16x16x32_bf16 v[4:7], v[186:189], v[206:209], v[4:7]
	v_mfma_f32_16x16x32_bf16 v[0:3], v[186:189], v[210:213], v[0:3]
	v_mfma_f32_16x16x32_bf16 v[20:23], v[186:189], v[214:217], v[20:23]
	v_mfma_f32_16x16x32_bf16 v[8:11], v[186:189], v[218:221], v[8:11]
	ds_read_b128 v[172:175], v143 offset:8192
	ds_read_b128 v[176:179], v143 offset:10240
	ds_read_b128 v[182:185], v143 offset:12288
	ds_read_b128 v[186:189], v143 offset:14336
	s_waitcnt lgkmcnt(4)
	v_mfma_f32_16x16x32_bf16 v[124:127], v[156:159], v[190:193], v[124:127]
	v_mfma_f32_16x16x32_bf16 v[116:119], v[156:159], v[194:197], v[116:119]
	v_mfma_f32_16x16x32_bf16 v[120:123], v[156:159], v[198:201], v[120:123]
	v_mfma_f32_16x16x32_bf16 v[112:115], v[156:159], v[202:205], v[112:115]
	v_mfma_f32_16x16x32_bf16 v[108:111], v[160:163], v[190:193], v[108:111]
	v_mfma_f32_16x16x32_bf16 v[100:103], v[160:163], v[194:197], v[100:103]
	v_mfma_f32_16x16x32_bf16 v[104:107], v[160:163], v[198:201], v[104:107]
	v_mfma_f32_16x16x32_bf16 v[96:99], v[160:163], v[202:205], v[96:99]
	v_mfma_f32_16x16x32_bf16 v[92:95], v[164:167], v[190:193], v[92:95]
	v_mfma_f32_16x16x32_bf16 v[84:87], v[164:167], v[194:197], v[84:87]
	v_mfma_f32_16x16x32_bf16 v[88:91], v[164:167], v[198:201], v[88:91]
	v_mfma_f32_16x16x32_bf16 v[80:83], v[164:167], v[202:205], v[80:83]
	v_mfma_f32_16x16x32_bf16 v[76:79], v[168:171], v[190:193], v[76:79]
	v_mfma_f32_16x16x32_bf16 v[68:71], v[168:171], v[194:197], v[68:71]
	v_mfma_f32_16x16x32_bf16 v[72:75], v[168:171], v[198:201], v[72:75]
	v_mfma_f32_16x16x32_bf16 v[64:67], v[168:171], v[202:205], v[64:67]
	ds_read_b128 v[156:159], v155
	ds_read_b128 v[160:163], v155 offset:2048
	ds_read_b128 v[164:167], v155 offset:4096
	ds_read_b128 v[168:171], v155 offset:6144
	ds_read_b128 v[206:209], v222 offset:32768
	ds_read_b128 v[210:213], v222 offset:34816
	ds_read_b128 v[214:217], v222 offset:36864
	ds_read_b128 v[218:221], v222 offset:38912
	s_waitcnt lgkmcnt(8)
	v_mfma_f32_16x16x32_bf16 v[60:63], v[172:175], v[190:193], v[60:63]
	v_mfma_f32_16x16x32_bf16 v[52:55], v[172:175], v[194:197], v[52:55]
	v_mfma_f32_16x16x32_bf16 v[56:59], v[172:175], v[198:201], v[56:59]
	v_mfma_f32_16x16x32_bf16 v[48:51], v[172:175], v[202:205], v[48:51]
	v_mfma_f32_16x16x32_bf16 v[44:47], v[176:179], v[190:193], v[44:47]
	v_mfma_f32_16x16x32_bf16 v[36:39], v[176:179], v[194:197], v[36:39]
	v_mfma_f32_16x16x32_bf16 v[40:43], v[176:179], v[198:201], v[40:43]
	v_mfma_f32_16x16x32_bf16 v[32:35], v[176:179], v[202:205], v[32:35]
	v_mfma_f32_16x16x32_bf16 v[28:31], v[182:185], v[190:193], v[28:31]
	v_mfma_f32_16x16x32_bf16 v[16:19], v[182:185], v[194:197], v[16:19]
	v_mfma_f32_16x16x32_bf16 v[24:27], v[182:185], v[198:201], v[24:27]
	v_mfma_f32_16x16x32_bf16 v[12:15], v[182:185], v[202:205], v[12:15]
	v_mfma_f32_16x16x32_bf16 v[4:7], v[186:189], v[190:193], v[4:7]
	v_mfma_f32_16x16x32_bf16 v[0:3], v[186:189], v[194:197], v[0:3]
	v_mfma_f32_16x16x32_bf16 v[20:23], v[186:189], v[198:201], v[20:23]
	v_mfma_f32_16x16x32_bf16 v[8:11], v[186:189], v[202:205], v[8:11]
	ds_read_b128 v[172:175], v155 offset:8192
	ds_read_b128 v[176:179], v155 offset:10240
	ds_read_b128 v[182:185], v155 offset:12288
	ds_read_b128 v[186:189], v155 offset:14336
	s_waitcnt lgkmcnt(4)
	v_mfma_f32_16x16x32_bf16 v[124:127], v[156:159], v[206:209], v[124:127]
	v_mfma_f32_16x16x32_bf16 v[116:119], v[156:159], v[210:213], v[116:119]
	v_mfma_f32_16x16x32_bf16 v[120:123], v[156:159], v[214:217], v[120:123]
	v_mfma_f32_16x16x32_bf16 v[112:115], v[156:159], v[218:221], v[112:115]
	v_mfma_f32_16x16x32_bf16 v[108:111], v[160:163], v[206:209], v[108:111]
	v_mfma_f32_16x16x32_bf16 v[100:103], v[160:163], v[210:213], v[100:103]
	v_mfma_f32_16x16x32_bf16 v[104:107], v[160:163], v[214:217], v[104:107]
	v_mfma_f32_16x16x32_bf16 v[96:99], v[160:163], v[218:221], v[96:99]
	v_mfma_f32_16x16x32_bf16 v[92:95], v[164:167], v[206:209], v[92:95]
	v_mfma_f32_16x16x32_bf16 v[84:87], v[164:167], v[210:213], v[84:87]
	v_mfma_f32_16x16x32_bf16 v[88:91], v[164:167], v[214:217], v[88:91]
	v_mfma_f32_16x16x32_bf16 v[80:83], v[164:167], v[218:221], v[80:83]
	v_mfma_f32_16x16x32_bf16 v[76:79], v[168:171], v[206:209], v[76:79]
	v_mfma_f32_16x16x32_bf16 v[68:71], v[168:171], v[210:213], v[68:71]
	v_mfma_f32_16x16x32_bf16 v[72:75], v[168:171], v[214:217], v[72:75]
	v_mfma_f32_16x16x32_bf16 v[64:67], v[168:171], v[218:221], v[64:67]
	s_add_u32 s60, s60, 0x80
	s_addc_u32 s61, s61, 0
	s_add_i32 s59, s59, 1
	s_waitcnt lgkmcnt(0)
	s_waitcnt vmcnt(0)
	s_barrier
	v_mfma_f32_16x16x32_bf16 v[60:63], v[172:175], v[206:209], v[60:63]
	v_mfma_f32_16x16x32_bf16 v[52:55], v[172:175], v[210:213], v[52:55]
	v_mfma_f32_16x16x32_bf16 v[56:59], v[172:175], v[214:217], v[56:59]
	v_mfma_f32_16x16x32_bf16 v[48:51], v[172:175], v[218:221], v[48:51]
	v_mfma_f32_16x16x32_bf16 v[44:47], v[176:179], v[206:209], v[44:47]
	v_mfma_f32_16x16x32_bf16 v[36:39], v[176:179], v[210:213], v[36:39]
	v_mfma_f32_16x16x32_bf16 v[40:43], v[176:179], v[214:217], v[40:43]
	v_mfma_f32_16x16x32_bf16 v[32:35], v[176:179], v[218:221], v[32:35]
	v_mfma_f32_16x16x32_bf16 v[28:31], v[182:185], v[206:209], v[28:31]
	v_mfma_f32_16x16x32_bf16 v[16:19], v[182:185], v[210:213], v[16:19]
	v_mfma_f32_16x16x32_bf16 v[24:27], v[182:185], v[214:217], v[24:27]
	v_mfma_f32_16x16x32_bf16 v[12:15], v[182:185], v[218:221], v[12:15]
	v_mfma_f32_16x16x32_bf16 v[4:7], v[186:189], v[206:209], v[4:7]
	v_mfma_f32_16x16x32_bf16 v[0:3], v[186:189], v[210:213], v[0:3]
	v_mfma_f32_16x16x32_bf16 v[20:23], v[186:189], v[214:217], v[20:23]
	v_mfma_f32_16x16x32_bf16 v[8:11], v[186:189], v[218:221], v[8:11]
	s_nop 7
	s_nop 7
	s_sub_u32 s60, s60, s34
	s_subb_u32 s61, s61, s35
	s_mov_b32 s87, 0x80000
	s_mov_b32 s96, 0x80000
	s_mov_b64 s[88:89], 0
	s_mov_b64 vcc, exec
	s_branch .LBB0_120

.Lg1_top:
	s_waitcnt lgkmcnt(0)
	s_waitcnt vmcnt(0)
	s_barrier
	v_xor_b32_e32 v141, 0x10000, v141
	v_xor_b32_e32 v210, 0x10000, v210
	v_xor_b32_e32 v180, 0x10000, v180
	v_xor_b32_e32 v211, 0x10000, v211
	s_xor_b32 s59, s59, 0x10000
	ds_read_b128 v[142:145], v141
	ds_read_b128 v[146:149], v141 offset:2048
	ds_read_b128 v[150:153], v141 offset:4096
	ds_read_b128 v[154:157], v141 offset:6144
	ds_read_b128 v[174:177], v210 offset:32768
	ds_read_b128 v[182:185], v210 offset:34816
	ds_read_b128 v[186:189], v210 offset:36864
	ds_read_b128 v[190:193], v210 offset:38912
	v_mfma_f32_16x16x32_bf16 v[60:63], v[158:161], v[194:197], v[60:63]
	v_mfma_f32_16x16x32_bf16 v[56:59], v[158:161], v[198:201], v[56:59]
	v_mfma_f32_16x16x32_bf16 v[52:55], v[158:161], v[202:205], v[52:55]
	v_mfma_f32_16x16x32_bf16 v[48:51], v[158:161], v[206:209], v[48:51]
	s_mov_b32 m0, s59
	s_add_u32 s52, s50, s14
	s_addc_u32 s53, s51, s15
	global_load_lds_dwordx4 v178, s[52:53]
	v_mfma_f32_16x16x32_bf16 v[44:47], v[162:165], v[194:197], v[44:47]
	v_mfma_f32_16x16x32_bf16 v[40:43], v[162:165], v[198:201], v[40:43]
	v_mfma_f32_16x16x32_bf16 v[36:39], v[162:165], v[202:205], v[36:39]
	v_mfma_f32_16x16x32_bf16 v[32:35], v[162:165], v[206:209], v[32:35]
	s_add_u32 m0, s59, 0x2000
	s_add_u32 s52, s50, s16
	s_addc_u32 s53, s51, s17
	global_load_lds_dwordx4 v178, s[52:53]
	v_mfma_f32_16x16x32_bf16 v[28:31], v[166:169], v[194:197], v[28:31]
	v_mfma_f32_16x16x32_bf16 v[20:23], v[166:169], v[198:201], v[20:23]
	v_mfma_f32_16x16x32_bf16 v[16:19], v[166:169], v[202:205], v[16:19]
	v_mfma_f32_16x16x32_bf16 v[8:11], v[166:169], v[206:209], v[8:11]
	s_add_u32 m0, s59, 0x4000
	s_add_u32 s52, s50, s18
	s_addc_u32 s53, s51, s19
	global_load_lds_dwordx4 v178, s[52:53]
	v_mfma_f32_16x16x32_bf16 v[4:7], v[170:173], v[194:197], v[4:7]
	v_mfma_f32_16x16x32_bf16 v[0:3], v[170:173], v[198:201], v[0:3]
	v_mfma_f32_16x16x32_bf16 v[24:27], v[170:173], v[202:205], v[24:27]
	v_mfma_f32_16x16x32_bf16 v[12:15], v[170:173], v[206:209], v[12:15]
	s_add_u32 m0, s59, 0x6000
	s_add_u32 s52, s50, s22
	s_addc_u32 s53, s51, s23
	global_load_lds_dwordx4 v178, s[52:53]
.Lg1_entry:
	ds_read_b128 v[158:161], v141 offset:8192
	ds_read_b128 v[162:165], v141 offset:10240
	ds_read_b128 v[166:169], v141 offset:12288
	ds_read_b128 v[170:173], v141 offset:14336
	s_waitcnt lgkmcnt(4)
	v_mfma_f32_16x16x32_bf16 v[124:127], v[142:145], v[174:177], v[124:127]
	v_mfma_f32_16x16x32_bf16 v[120:123], v[142:145], v[182:185], v[120:123]
	v_mfma_f32_16x16x32_bf16 v[116:119], v[142:145], v[186:189], v[116:119]
	v_mfma_f32_16x16x32_bf16 v[112:115], v[142:145], v[190:193], v[112:115]
	s_add_u32 m0, s59, 0x8000
	s_add_u32 s52, s50, s40
	s_addc_u32 s53, s51, s41
	global_load_lds_dwordx4 v179, s[52:53]
	v_mfma_f32_16x16x32_bf16 v[108:111], v[146:149], v[174:177], v[108:111]
	v_mfma_f32_16x16x32_bf16 v[104:107], v[146:149], v[182:185], v[104:107]
	v_mfma_f32_16x16x32_bf16 v[100:103], v[146:149], v[186:189], v[100:103]
	v_mfma_f32_16x16x32_bf16 v[96:99], v[146:149], v[190:193], v[96:99]
	s_add_u32 m0, s59, 0xa000
	s_add_u32 s52, s50, s42
	s_addc_u32 s53, s51, s43
	global_load_lds_dwordx4 v179, s[52:53]
	v_mfma_f32_16x16x32_bf16 v[92:95], v[150:153], v[174:177], v[92:95]
	v_mfma_f32_16x16x32_bf16 v[88:91], v[150:153], v[182:185], v[88:91]
	v_mfma_f32_16x16x32_bf16 v[84:87], v[150:153], v[186:189], v[84:87]
	v_mfma_f32_16x16x32_bf16 v[80:83], v[150:153], v[190:193], v[80:83]
	s_add_u32 m0, s59, 0xc000
	s_add_u32 s52, s50, s44
	s_addc_u32 s53, s51, s45
	global_load_lds_dwordx4 v179, s[52:53]
	v_mfma_f32_16x16x32_bf16 v[76:79], v[154:157], v[174:177], v[76:79]
	v_mfma_f32_16x16x32_bf16 v[72:75], v[154:157], v[182:185], v[72:75]
	v_mfma_f32_16x16x32_bf16 v[68:71], v[154:157], v[186:189], v[68:71]
	v_mfma_f32_16x16x32_bf16 v[64:67], v[154:157], v[190:193], v[64:67]
	s_add_u32 m0, s59, 0xe000
	s_add_u32 s52, s50, s46
	s_addc_u32 s53, s51, s47
	global_load_lds_dwordx4 v179, s[52:53]
	ds_read_b128 v[142:145], v180
	ds_read_b128 v[146:149], v180 offset:2048
	ds_read_b128 v[150:153], v180 offset:4096
	ds_read_b128 v[154:157], v180 offset:6144
	ds_read_b128 v[194:197], v211 offset:32768
	ds_read_b128 v[198:201], v211 offset:34816
	ds_read_b128 v[202:205], v211 offset:36864
	ds_read_b128 v[206:209], v211 offset:38912
	s_waitcnt lgkmcnt(8)
	v_mfma_f32_16x16x32_bf16 v[60:63], v[158:161], v[174:177], v[60:63]
	v_mfma_f32_16x16x32_bf16 v[56:59], v[158:161], v[182:185], v[56:59]
	v_mfma_f32_16x16x32_bf16 v[52:55], v[158:161], v[186:189], v[52:55]
	v_mfma_f32_16x16x32_bf16 v[48:51], v[158:161], v[190:193], v[48:51]
	v_mfma_f32_16x16x32_bf16 v[44:47], v[162:165], v[174:177], v[44:47]
	v_mfma_f32_16x16x32_bf16 v[40:43], v[162:165], v[182:185], v[40:43]
	v_mfma_f32_16x16x32_bf16 v[36:39], v[162:165], v[186:189], v[36:39]
	v_mfma_f32_16x16x32_bf16 v[32:35], v[162:165], v[190:193], v[32:35]
	v_mfma_f32_16x16x32_bf16 v[28:31], v[166:169], v[174:177], v[28:31]
	v_mfma_f32_16x16x32_bf16 v[20:23], v[166:169], v[182:185], v[20:23]
	v_mfma_f32_16x16x32_bf16 v[16:19], v[166:169], v[186:189], v[16:19]
	v_mfma_f32_16x16x32_bf16 v[8:11], v[166:169], v[190:193], v[8:11]
	v_mfma_f32_16x16x32_bf16 v[4:7], v[170:173], v[174:177], v[4:7]
	v_mfma_f32_16x16x32_bf16 v[0:3], v[170:173], v[182:185], v[0:3]
	v_mfma_f32_16x16x32_bf16 v[24:27], v[170:173], v[186:189], v[24:27]
	v_mfma_f32_16x16x32_bf16 v[12:15], v[170:173], v[190:193], v[12:15]
	ds_read_b128 v[158:161], v180 offset:8192
	ds_read_b128 v[162:165], v180 offset:10240
	ds_read_b128 v[166:169], v180 offset:12288
	ds_read_b128 v[170:173], v180 offset:14336
	s_waitcnt lgkmcnt(4)
	v_mfma_f32_16x16x32_bf16 v[124:127], v[142:145], v[194:197], v[124:127]
	v_mfma_f32_16x16x32_bf16 v[120:123], v[142:145], v[198:201], v[120:123]
	v_mfma_f32_16x16x32_bf16 v[116:119], v[142:145], v[202:205], v[116:119]
	v_mfma_f32_16x16x32_bf16 v[112:115], v[142:145], v[206:209], v[112:115]
	v_mfma_f32_16x16x32_bf16 v[108:111], v[146:149], v[194:197], v[108:111]
	v_mfma_f32_16x16x32_bf16 v[104:107], v[146:149], v[198:201], v[104:107]
	v_mfma_f32_16x16x32_bf16 v[100:103], v[146:149], v[202:205], v[100:103]
	v_mfma_f32_16x16x32_bf16 v[96:99], v[146:149], v[206:209], v[96:99]
	v_mfma_f32_16x16x32_bf16 v[92:95], v[150:153], v[194:197], v[92:95]
	v_mfma_f32_16x16x32_bf16 v[88:91], v[150:153], v[198:201], v[88:91]
	v_mfma_f32_16x16x32_bf16 v[84:87], v[150:153], v[202:205], v[84:87]
	v_mfma_f32_16x16x32_bf16 v[80:83], v[150:153], v[206:209], v[80:83]
	v_mfma_f32_16x16x32_bf16 v[76:79], v[154:157], v[194:197], v[76:79]
	v_mfma_f32_16x16x32_bf16 v[72:75], v[154:157], v[198:201], v[72:75]
	v_mfma_f32_16x16x32_bf16 v[68:71], v[154:157], v[202:205], v[68:71]
	v_mfma_f32_16x16x32_bf16 v[64:67], v[154:157], v[206:209], v[64:67]
	s_add_u32 s50, s50, 0x80
	s_addc_u32 s51, s51, 0
	s_add_i32 s49, s49, 1
	s_cmp_lt_u32 s49, 31
	s_cbranch_scc1 .Lg1_top
	s_waitcnt lgkmcnt(0)
	s_waitcnt vmcnt(0)
	s_barrier
	v_xor_b32_e32 v141, 0x10000, v141
	v_xor_b32_e32 v210, 0x10000, v210
	v_xor_b32_e32 v180, 0x10000, v180
	v_xor_b32_e32 v211, 0x10000, v211
	s_xor_b32 s59, s59, 0x10000
	ds_read_b128 v[142:145], v141
	ds_read_b128 v[146:149], v141 offset:2048
	ds_read_b128 v[150:153], v141 offset:4096
	ds_read_b128 v[154:157], v141 offset:6144
	ds_read_b128 v[174:177], v210 offset:32768
	ds_read_b128 v[182:185], v210 offset:34816
	ds_read_b128 v[186:189], v210 offset:36864
	ds_read_b128 v[190:193], v210 offset:38912
	v_mfma_f32_16x16x32_bf16 v[60:63], v[158:161], v[194:197], v[60:63]
	v_mfma_f32_16x16x32_bf16 v[56:59], v[158:161], v[198:201], v[56:59]
	v_mfma_f32_16x16x32_bf16 v[52:55], v[158:161], v[202:205], v[52:55]
	v_mfma_f32_16x16x32_bf16 v[48:51], v[158:161], v[206:209], v[48:51]
	v_mfma_f32_16x16x32_bf16 v[44:47], v[162:165], v[194:197], v[44:47]
	v_mfma_f32_16x16x32_bf16 v[40:43], v[162:165], v[198:201], v[40:43]
	v_mfma_f32_16x16x32_bf16 v[36:39], v[162:165], v[202:205], v[36:39]
	v_mfma_f32_16x16x32_bf16 v[32:35], v[162:165], v[206:209], v[32:35]
	v_mfma_f32_16x16x32_bf16 v[28:31], v[166:169], v[194:197], v[28:31]
	v_mfma_f32_16x16x32_bf16 v[20:23], v[166:169], v[198:201], v[20:23]
	v_mfma_f32_16x16x32_bf16 v[16:19], v[166:169], v[202:205], v[16:19]
	v_mfma_f32_16x16x32_bf16 v[8:11], v[166:169], v[206:209], v[8:11]
	v_mfma_f32_16x16x32_bf16 v[4:7], v[170:173], v[194:197], v[4:7]
	v_mfma_f32_16x16x32_bf16 v[0:3], v[170:173], v[198:201], v[0:3]
	v_mfma_f32_16x16x32_bf16 v[24:27], v[170:173], v[202:205], v[24:27]
	v_mfma_f32_16x16x32_bf16 v[12:15], v[170:173], v[206:209], v[12:15]
	ds_read_b128 v[158:161], v141 offset:8192
	ds_read_b128 v[162:165], v141 offset:10240
	ds_read_b128 v[166:169], v141 offset:12288
	ds_read_b128 v[170:173], v141 offset:14336
	s_waitcnt lgkmcnt(4)
	v_mfma_f32_16x16x32_bf16 v[124:127], v[142:145], v[174:177], v[124:127]
	v_mfma_f32_16x16x32_bf16 v[120:123], v[142:145], v[182:185], v[120:123]
	v_mfma_f32_16x16x32_bf16 v[116:119], v[142:145], v[186:189], v[116:119]
	v_mfma_f32_16x16x32_bf16 v[112:115], v[142:145], v[190:193], v[112:115]
	v_mfma_f32_16x16x32_bf16 v[108:111], v[146:149], v[174:177], v[108:111]
	v_mfma_f32_16x16x32_bf16 v[104:107], v[146:149], v[182:185], v[104:107]
	v_mfma_f32_16x16x32_bf16 v[100:103], v[146:149], v[186:189], v[100:103]
	v_mfma_f32_16x16x32_bf16 v[96:99], v[146:149], v[190:193], v[96:99]
	v_mfma_f32_16x16x32_bf16 v[92:95], v[150:153], v[174:177], v[92:95]
	v_mfma_f32_16x16x32_bf16 v[88:91], v[150:153], v[182:185], v[88:91]
	v_mfma_f32_16x16x32_bf16 v[84:87], v[150:153], v[186:189], v[84:87]
	v_mfma_f32_16x16x32_bf16 v[80:83], v[150:153], v[190:193], v[80:83]
	v_mfma_f32_16x16x32_bf16 v[76:79], v[154:157], v[174:177], v[76:79]
	v_mfma_f32_16x16x32_bf16 v[72:75], v[154:157], v[182:185], v[72:75]
	v_mfma_f32_16x16x32_bf16 v[68:71], v[154:157], v[186:189], v[68:71]
	v_mfma_f32_16x16x32_bf16 v[64:67], v[154:157], v[190:193], v[64:67]
	ds_read_b128 v[142:145], v180
	ds_read_b128 v[146:149], v180 offset:2048
	ds_read_b128 v[150:153], v180 offset:4096
	ds_read_b128 v[154:157], v180 offset:6144
	ds_read_b128 v[194:197], v211 offset:32768
	ds_read_b128 v[198:201], v211 offset:34816
	ds_read_b128 v[202:205], v211 offset:36864
	ds_read_b128 v[206:209], v211 offset:38912
	s_waitcnt lgkmcnt(8)
	v_mfma_f32_16x16x32_bf16 v[60:63], v[158:161], v[174:177], v[60:63]
	v_mfma_f32_16x16x32_bf16 v[56:59], v[158:161], v[182:185], v[56:59]
	v_mfma_f32_16x16x32_bf16 v[52:55], v[158:161], v[186:189], v[52:55]
	v_mfma_f32_16x16x32_bf16 v[48:51], v[158:161], v[190:193], v[48:51]
	v_mfma_f32_16x16x32_bf16 v[44:47], v[162:165], v[174:177], v[44:47]
	v_mfma_f32_16x16x32_bf16 v[40:43], v[162:165], v[182:185], v[40:43]
	v_mfma_f32_16x16x32_bf16 v[36:39], v[162:165], v[186:189], v[36:39]
	v_mfma_f32_16x16x32_bf16 v[32:35], v[162:165], v[190:193], v[32:35]
	v_mfma_f32_16x16x32_bf16 v[28:31], v[166:169], v[174:177], v[28:31]
	v_mfma_f32_16x16x32_bf16 v[20:23], v[166:169], v[182:185], v[20:23]
	v_mfma_f32_16x16x32_bf16 v[16:19], v[166:169], v[186:189], v[16:19]
	v_mfma_f32_16x16x32_bf16 v[8:11], v[166:169], v[190:193], v[8:11]
	v_mfma_f32_16x16x32_bf16 v[4:7], v[170:173], v[174:177], v[4:7]
	v_mfma_f32_16x16x32_bf16 v[0:3], v[170:173], v[182:185], v[0:3]
	v_mfma_f32_16x16x32_bf16 v[24:27], v[170:173], v[186:189], v[24:27]
	v_mfma_f32_16x16x32_bf16 v[12:15], v[170:173], v[190:193], v[12:15]
	ds_read_b128 v[158:161], v180 offset:8192
	ds_read_b128 v[162:165], v180 offset:10240
	ds_read_b128 v[166:169], v180 offset:12288
	ds_read_b128 v[170:173], v180 offset:14336
	s_waitcnt lgkmcnt(4)
	v_mfma_f32_16x16x32_bf16 v[124:127], v[142:145], v[194:197], v[124:127]
	v_mfma_f32_16x16x32_bf16 v[120:123], v[142:145], v[198:201], v[120:123]
	v_mfma_f32_16x16x32_bf16 v[116:119], v[142:145], v[202:205], v[116:119]
	v_mfma_f32_16x16x32_bf16 v[112:115], v[142:145], v[206:209], v[112:115]
	v_mfma_f32_16x16x32_bf16 v[108:111], v[146:149], v[194:197], v[108:111]
	v_mfma_f32_16x16x32_bf16 v[104:107], v[146:149], v[198:201], v[104:107]
	v_mfma_f32_16x16x32_bf16 v[100:103], v[146:149], v[202:205], v[100:103]
	v_mfma_f32_16x16x32_bf16 v[96:99], v[146:149], v[206:209], v[96:99]
	v_mfma_f32_16x16x32_bf16 v[92:95], v[150:153], v[194:197], v[92:95]
	v_mfma_f32_16x16x32_bf16 v[88:91], v[150:153], v[198:201], v[88:91]
	v_mfma_f32_16x16x32_bf16 v[84:87], v[150:153], v[202:205], v[84:87]
	v_mfma_f32_16x16x32_bf16 v[80:83], v[150:153], v[206:209], v[80:83]
	v_mfma_f32_16x16x32_bf16 v[76:79], v[154:157], v[194:197], v[76:79]
	v_mfma_f32_16x16x32_bf16 v[72:75], v[154:157], v[198:201], v[72:75]
	v_mfma_f32_16x16x32_bf16 v[68:71], v[154:157], v[202:205], v[68:71]
	v_mfma_f32_16x16x32_bf16 v[64:67], v[154:157], v[206:209], v[64:67]
	s_add_u32 s50, s50, 0x80
	s_addc_u32 s51, s51, 0
	s_add_i32 s49, s49, 1
	s_waitcnt lgkmcnt(0)
	s_waitcnt vmcnt(0)
	s_barrier
	v_mfma_f32_16x16x32_bf16 v[60:63], v[158:161], v[194:197], v[60:63]
	v_mfma_f32_16x16x32_bf16 v[56:59], v[158:161], v[198:201], v[56:59]
	v_mfma_f32_16x16x32_bf16 v[52:55], v[158:161], v[202:205], v[52:55]
	v_mfma_f32_16x16x32_bf16 v[48:51], v[158:161], v[206:209], v[48:51]
	v_mfma_f32_16x16x32_bf16 v[44:47], v[162:165], v[194:197], v[44:47]
	v_mfma_f32_16x16x32_bf16 v[40:43], v[162:165], v[198:201], v[40:43]
	v_mfma_f32_16x16x32_bf16 v[36:39], v[162:165], v[202:205], v[36:39]
	v_mfma_f32_16x16x32_bf16 v[32:35], v[162:165], v[206:209], v[32:35]
	v_mfma_f32_16x16x32_bf16 v[28:31], v[166:169], v[194:197], v[28:31]
	v_mfma_f32_16x16x32_bf16 v[20:23], v[166:169], v[198:201], v[20:23]
	v_mfma_f32_16x16x32_bf16 v[16:19], v[166:169], v[202:205], v[16:19]
	v_mfma_f32_16x16x32_bf16 v[8:11], v[166:169], v[206:209], v[8:11]
	v_mfma_f32_16x16x32_bf16 v[4:7], v[170:173], v[194:197], v[4:7]
	v_mfma_f32_16x16x32_bf16 v[0:3], v[170:173], v[198:201], v[0:3]
	v_mfma_f32_16x16x32_bf16 v[24:27], v[170:173], v[202:205], v[24:27]
	v_mfma_f32_16x16x32_bf16 v[12:15], v[170:173], v[206:209], v[12:15]
	s_nop 7
	s_nop 7
	s_sub_u32 s50, s50, s34
	s_subb_u32 s51, s51, s35
	s_mov_b32 s59, 0x100000
	s_mov_b32 s60, 0x100000
	s_mov_b64 s[52:53], 0
	s_mov_b64 vcc, exec
	s_branch .LBB0_262

.Lg2_top:
	s_waitcnt lgkmcnt(0)
	s_waitcnt vmcnt(0)
	s_barrier
	v_xor_b32_e32 v180, 0x10000, v180
	v_xor_b32_e32 v215, 0x10000, v215
	v_xor_b32_e32 v214, 0x10000, v214
	v_xor_b32_e32 v216, 0x10000, v216
	s_xor_b32 s62, s62, 0x10000
	ds_read_b128 v[146:149], v180
	ds_read_b128 v[150:153], v180 offset:2048
	ds_read_b128 v[154:157], v180 offset:4096
	ds_read_b128 v[158:161], v180 offset:6144
	ds_read_b128 v[182:185], v215 offset:32768
	ds_read_b128 v[186:189], v215 offset:34816
	ds_read_b128 v[190:193], v215 offset:36864
	ds_read_b128 v[194:197], v215 offset:38912
	v_mfma_f32_16x16x32_bf16 v[60:63], v[162:165], v[198:201], v[60:63]
	v_mfma_f32_16x16x32_bf16 v[56:59], v[162:165], v[202:205], v[56:59]
	v_mfma_f32_16x16x32_bf16 v[52:55], v[162:165], v[206:209], v[52:55]
	v_mfma_f32_16x16x32_bf16 v[44:47], v[162:165], v[210:213], v[44:47]
	s_mov_b32 m0, s62
	s_add_u32 s50, s48, s12
	s_addc_u32 s51, s49, s13
	global_load_lds_dwordx4 v178, s[50:51]
	v_mfma_f32_16x16x32_bf16 v[36:39], v[166:169], v[198:201], v[36:39]
	v_mfma_f32_16x16x32_bf16 v[32:35], v[166:169], v[202:205], v[32:35]
	v_mfma_f32_16x16x32_bf16 v[28:31], v[166:169], v[206:209], v[28:31]
	v_mfma_f32_16x16x32_bf16 v[24:27], v[166:169], v[210:213], v[24:27]
	s_add_u32 m0, s62, 0x2000
	s_add_u32 s50, s48, s14
	s_addc_u32 s51, s49, s15
	global_load_lds_dwordx4 v178, s[50:51]
	v_mfma_f32_16x16x32_bf16 v[20:23], v[170:173], v[198:201], v[20:23]
	v_mfma_f32_16x16x32_bf16 v[16:19], v[170:173], v[202:205], v[16:19]
	v_mfma_f32_16x16x32_bf16 v[12:15], v[170:173], v[206:209], v[12:15]
	v_mfma_f32_16x16x32_bf16 v[8:11], v[170:173], v[210:213], v[8:11]
	s_add_u32 m0, s62, 0x4000
	s_add_u32 s50, s48, s16
	s_addc_u32 s51, s49, s17
	global_load_lds_dwordx4 v178, s[50:51]
	v_mfma_f32_16x16x32_bf16 v[4:7], v[174:177], v[198:201], v[4:7]
	v_mfma_f32_16x16x32_bf16 v[0:3], v[174:177], v[202:205], v[0:3]
	v_mfma_f32_16x16x32_bf16 v[48:51], v[174:177], v[206:209], v[48:51]
	v_mfma_f32_16x16x32_bf16 v[40:43], v[174:177], v[210:213], v[40:43]
	s_add_u32 m0, s62, 0x6000
	s_add_u32 s50, s48, s18
	s_addc_u32 s51, s49, s19
	global_load_lds_dwordx4 v178, s[50:51]
.Lg2_entry:
	ds_read_b128 v[162:165], v180 offset:8192
	ds_read_b128 v[166:169], v180 offset:10240
	ds_read_b128 v[170:173], v180 offset:12288
	ds_read_b128 v[174:177], v180 offset:14336
	s_waitcnt lgkmcnt(4)
	v_mfma_f32_16x16x32_bf16 v[124:127], v[146:149], v[182:185], v[124:127]
	v_mfma_f32_16x16x32_bf16 v[120:123], v[146:149], v[186:189], v[120:123]
	v_mfma_f32_16x16x32_bf16 v[116:119], v[146:149], v[190:193], v[116:119]
	v_mfma_f32_16x16x32_bf16 v[112:115], v[146:149], v[194:197], v[112:115]
	s_add_u32 m0, s62, 0x8000
	s_add_u32 s50, s48, s22
	s_addc_u32 s51, s49, s23
	global_load_lds_dwordx4 v179, s[50:51]
	v_mfma_f32_16x16x32_bf16 v[108:111], v[150:153], v[182:185], v[108:111]
	v_mfma_f32_16x16x32_bf16 v[104:107], v[150:153], v[186:189], v[104:107]
	v_mfma_f32_16x16x32_bf16 v[100:103], v[150:153], v[190:193], v[100:103]
	v_mfma_f32_16x16x32_bf16 v[96:99], v[150:153], v[194:197], v[96:99]
	s_add_u32 m0, s62, 0xa000
	s_add_u32 s50, s48, s36
	s_addc_u32 s51, s49, s37
	global_load_lds_dwordx4 v179, s[50:51]
	v_mfma_f32_16x16x32_bf16 v[92:95], v[154:157], v[182:185], v[92:95]
	v_mfma_f32_16x16x32_bf16 v[88:91], v[154:157], v[186:189], v[88:91]
	v_mfma_f32_16x16x32_bf16 v[84:87], v[154:157], v[190:193], v[84:87]
	v_mfma_f32_16x16x32_bf16 v[80:83], v[154:157], v[194:197], v[80:83]
	s_add_u32 m0, s62, 0xc000
	s_add_u32 s50, s48, s40
	s_addc_u32 s51, s49, s41
	global_load_lds_dwordx4 v179, s[50:51]
	v_mfma_f32_16x16x32_bf16 v[76:79], v[158:161], v[182:185], v[76:79]
	v_mfma_f32_16x16x32_bf16 v[72:75], v[158:161], v[186:189], v[72:75]
	v_mfma_f32_16x16x32_bf16 v[68:71], v[158:161], v[190:193], v[68:71]
	v_mfma_f32_16x16x32_bf16 v[64:67], v[158:161], v[194:197], v[64:67]
	s_add_u32 m0, s62, 0xe000
	s_add_u32 s50, s48, s42
	s_addc_u32 s51, s49, s43
	global_load_lds_dwordx4 v179, s[50:51]
	ds_read_b128 v[146:149], v214
	ds_read_b128 v[150:153], v214 offset:2048
	ds_read_b128 v[154:157], v214 offset:4096
	ds_read_b128 v[158:161], v214 offset:6144
	ds_read_b128 v[198:201], v216 offset:32768
	ds_read_b128 v[202:205], v216 offset:34816
	ds_read_b128 v[206:209], v216 offset:36864
	ds_read_b128 v[210:213], v216 offset:38912
	s_waitcnt lgkmcnt(8)
	v_mfma_f32_16x16x32_bf16 v[60:63], v[162:165], v[182:185], v[60:63]
	v_mfma_f32_16x16x32_bf16 v[56:59], v[162:165], v[186:189], v[56:59]
	v_mfma_f32_16x16x32_bf16 v[52:55], v[162:165], v[190:193], v[52:55]
	v_mfma_f32_16x16x32_bf16 v[44:47], v[162:165], v[194:197], v[44:47]
	v_mfma_f32_16x16x32_bf16 v[36:39], v[166:169], v[182:185], v[36:39]
	v_mfma_f32_16x16x32_bf16 v[32:35], v[166:169], v[186:189], v[32:35]
	v_mfma_f32_16x16x32_bf16 v[28:31], v[166:169], v[190:193], v[28:31]
	v_mfma_f32_16x16x32_bf16 v[24:27], v[166:169], v[194:197], v[24:27]
	v_mfma_f32_16x16x32_bf16 v[20:23], v[170:173], v[182:185], v[20:23]
	v_mfma_f32_16x16x32_bf16 v[16:19], v[170:173], v[186:189], v[16:19]
	v_mfma_f32_16x16x32_bf16 v[12:15], v[170:173], v[190:193], v[12:15]
	v_mfma_f32_16x16x32_bf16 v[8:11], v[170:173], v[194:197], v[8:11]
	v_mfma_f32_16x16x32_bf16 v[4:7], v[174:177], v[182:185], v[4:7]
	v_mfma_f32_16x16x32_bf16 v[0:3], v[174:177], v[186:189], v[0:3]
	v_mfma_f32_16x16x32_bf16 v[48:51], v[174:177], v[190:193], v[48:51]
	v_mfma_f32_16x16x32_bf16 v[40:43], v[174:177], v[194:197], v[40:43]
	ds_read_b128 v[162:165], v214 offset:8192
	ds_read_b128 v[166:169], v214 offset:10240
	ds_read_b128 v[170:173], v214 offset:12288
	ds_read_b128 v[174:177], v214 offset:14336
	s_waitcnt lgkmcnt(4)
	v_mfma_f32_16x16x32_bf16 v[124:127], v[146:149], v[198:201], v[124:127]
	v_mfma_f32_16x16x32_bf16 v[120:123], v[146:149], v[202:205], v[120:123]
	v_mfma_f32_16x16x32_bf16 v[116:119], v[146:149], v[206:209], v[116:119]
	v_mfma_f32_16x16x32_bf16 v[112:115], v[146:149], v[210:213], v[112:115]
	v_mfma_f32_16x16x32_bf16 v[108:111], v[150:153], v[198:201], v[108:111]
	v_mfma_f32_16x16x32_bf16 v[104:107], v[150:153], v[202:205], v[104:107]
	v_mfma_f32_16x16x32_bf16 v[100:103], v[150:153], v[206:209], v[100:103]
	v_mfma_f32_16x16x32_bf16 v[96:99], v[150:153], v[210:213], v[96:99]
	v_mfma_f32_16x16x32_bf16 v[92:95], v[154:157], v[198:201], v[92:95]
	v_mfma_f32_16x16x32_bf16 v[88:91], v[154:157], v[202:205], v[88:91]
	v_mfma_f32_16x16x32_bf16 v[84:87], v[154:157], v[206:209], v[84:87]
	v_mfma_f32_16x16x32_bf16 v[80:83], v[154:157], v[210:213], v[80:83]
	v_mfma_f32_16x16x32_bf16 v[76:79], v[158:161], v[198:201], v[76:79]
	v_mfma_f32_16x16x32_bf16 v[72:75], v[158:161], v[202:205], v[72:75]
	v_mfma_f32_16x16x32_bf16 v[68:71], v[158:161], v[206:209], v[68:71]
	v_mfma_f32_16x16x32_bf16 v[64:67], v[158:161], v[210:213], v[64:67]
	s_add_u32 s48, s48, 0x80
	s_addc_u32 s49, s49, 0
	s_add_i32 s47, s47, 1
	s_cmp_lt_u32 s47, 15
	s_cbranch_scc1 .Lg2_top
	s_waitcnt lgkmcnt(0)
	s_waitcnt vmcnt(0)
	s_barrier
	v_xor_b32_e32 v180, 0x10000, v180
	v_xor_b32_e32 v215, 0x10000, v215
	v_xor_b32_e32 v214, 0x10000, v214
	v_xor_b32_e32 v216, 0x10000, v216
	s_xor_b32 s62, s62, 0x10000
	ds_read_b128 v[146:149], v180
	ds_read_b128 v[150:153], v180 offset:2048
	ds_read_b128 v[154:157], v180 offset:4096
	ds_read_b128 v[158:161], v180 offset:6144
	ds_read_b128 v[182:185], v215 offset:32768
	ds_read_b128 v[186:189], v215 offset:34816
	ds_read_b128 v[190:193], v215 offset:36864
	ds_read_b128 v[194:197], v215 offset:38912
	v_mfma_f32_16x16x32_bf16 v[60:63], v[162:165], v[198:201], v[60:63]
	v_mfma_f32_16x16x32_bf16 v[56:59], v[162:165], v[202:205], v[56:59]
	v_mfma_f32_16x16x32_bf16 v[52:55], v[162:165], v[206:209], v[52:55]
	v_mfma_f32_16x16x32_bf16 v[44:47], v[162:165], v[210:213], v[44:47]
	v_mfma_f32_16x16x32_bf16 v[36:39], v[166:169], v[198:201], v[36:39]
	v_mfma_f32_16x16x32_bf16 v[32:35], v[166:169], v[202:205], v[32:35]
	v_mfma_f32_16x16x32_bf16 v[28:31], v[166:169], v[206:209], v[28:31]
	v_mfma_f32_16x16x32_bf16 v[24:27], v[166:169], v[210:213], v[24:27]
	v_mfma_f32_16x16x32_bf16 v[20:23], v[170:173], v[198:201], v[20:23]
	v_mfma_f32_16x16x32_bf16 v[16:19], v[170:173], v[202:205], v[16:19]
	v_mfma_f32_16x16x32_bf16 v[12:15], v[170:173], v[206:209], v[12:15]
	v_mfma_f32_16x16x32_bf16 v[8:11], v[170:173], v[210:213], v[8:11]
	v_mfma_f32_16x16x32_bf16 v[4:7], v[174:177], v[198:201], v[4:7]
	v_mfma_f32_16x16x32_bf16 v[0:3], v[174:177], v[202:205], v[0:3]
	v_mfma_f32_16x16x32_bf16 v[48:51], v[174:177], v[206:209], v[48:51]
	v_mfma_f32_16x16x32_bf16 v[40:43], v[174:177], v[210:213], v[40:43]
	ds_read_b128 v[162:165], v180 offset:8192
	ds_read_b128 v[166:169], v180 offset:10240
	ds_read_b128 v[170:173], v180 offset:12288
	ds_read_b128 v[174:177], v180 offset:14336
	s_waitcnt lgkmcnt(4)
	v_mfma_f32_16x16x32_bf16 v[124:127], v[146:149], v[182:185], v[124:127]
	v_mfma_f32_16x16x32_bf16 v[120:123], v[146:149], v[186:189], v[120:123]
	v_mfma_f32_16x16x32_bf16 v[116:119], v[146:149], v[190:193], v[116:119]
	v_mfma_f32_16x16x32_bf16 v[112:115], v[146:149], v[194:197], v[112:115]
	v_mfma_f32_16x16x32_bf16 v[108:111], v[150:153], v[182:185], v[108:111]
	v_mfma_f32_16x16x32_bf16 v[104:107], v[150:153], v[186:189], v[104:107]
	v_mfma_f32_16x16x32_bf16 v[100:103], v[150:153], v[190:193], v[100:103]
	v_mfma_f32_16x16x32_bf16 v[96:99], v[150:153], v[194:197], v[96:99]
	v_mfma_f32_16x16x32_bf16 v[92:95], v[154:157], v[182:185], v[92:95]
	v_mfma_f32_16x16x32_bf16 v[88:91], v[154:157], v[186:189], v[88:91]
	v_mfma_f32_16x16x32_bf16 v[84:87], v[154:157], v[190:193], v[84:87]
	v_mfma_f32_16x16x32_bf16 v[80:83], v[154:157], v[194:197], v[80:83]
	v_mfma_f32_16x16x32_bf16 v[76:79], v[158:161], v[182:185], v[76:79]
	v_mfma_f32_16x16x32_bf16 v[72:75], v[158:161], v[186:189], v[72:75]
	v_mfma_f32_16x16x32_bf16 v[68:71], v[158:161], v[190:193], v[68:71]
	v_mfma_f32_16x16x32_bf16 v[64:67], v[158:161], v[194:197], v[64:67]
	ds_read_b128 v[146:149], v214
	ds_read_b128 v[150:153], v214 offset:2048
	ds_read_b128 v[154:157], v214 offset:4096
	ds_read_b128 v[158:161], v214 offset:6144
	ds_read_b128 v[198:201], v216 offset:32768
	ds_read_b128 v[202:205], v216 offset:34816
	ds_read_b128 v[206:209], v216 offset:36864
	ds_read_b128 v[210:213], v216 offset:38912
	s_waitcnt lgkmcnt(8)
	v_mfma_f32_16x16x32_bf16 v[60:63], v[162:165], v[182:185], v[60:63]
	v_mfma_f32_16x16x32_bf16 v[56:59], v[162:165], v[186:189], v[56:59]
	v_mfma_f32_16x16x32_bf16 v[52:55], v[162:165], v[190:193], v[52:55]
	v_mfma_f32_16x16x32_bf16 v[44:47], v[162:165], v[194:197], v[44:47]
	v_mfma_f32_16x16x32_bf16 v[36:39], v[166:169], v[182:185], v[36:39]
	v_mfma_f32_16x16x32_bf16 v[32:35], v[166:169], v[186:189], v[32:35]
	v_mfma_f32_16x16x32_bf16 v[28:31], v[166:169], v[190:193], v[28:31]
	v_mfma_f32_16x16x32_bf16 v[24:27], v[166:169], v[194:197], v[24:27]
	v_mfma_f32_16x16x32_bf16 v[20:23], v[170:173], v[182:185], v[20:23]
	v_mfma_f32_16x16x32_bf16 v[16:19], v[170:173], v[186:189], v[16:19]
	v_mfma_f32_16x16x32_bf16 v[12:15], v[170:173], v[190:193], v[12:15]
	v_mfma_f32_16x16x32_bf16 v[8:11], v[170:173], v[194:197], v[8:11]
	v_mfma_f32_16x16x32_bf16 v[4:7], v[174:177], v[182:185], v[4:7]
	v_mfma_f32_16x16x32_bf16 v[0:3], v[174:177], v[186:189], v[0:3]
	v_mfma_f32_16x16x32_bf16 v[48:51], v[174:177], v[190:193], v[48:51]
	v_mfma_f32_16x16x32_bf16 v[40:43], v[174:177], v[194:197], v[40:43]
	ds_read_b128 v[162:165], v214 offset:8192
	ds_read_b128 v[166:169], v214 offset:10240
	ds_read_b128 v[170:173], v214 offset:12288
	ds_read_b128 v[174:177], v214 offset:14336
	s_waitcnt lgkmcnt(4)
	v_mfma_f32_16x16x32_bf16 v[124:127], v[146:149], v[198:201], v[124:127]
	v_mfma_f32_16x16x32_bf16 v[120:123], v[146:149], v[202:205], v[120:123]
	v_mfma_f32_16x16x32_bf16 v[116:119], v[146:149], v[206:209], v[116:119]
	v_mfma_f32_16x16x32_bf16 v[112:115], v[146:149], v[210:213], v[112:115]
	v_mfma_f32_16x16x32_bf16 v[108:111], v[150:153], v[198:201], v[108:111]
	v_mfma_f32_16x16x32_bf16 v[104:107], v[150:153], v[202:205], v[104:107]
	v_mfma_f32_16x16x32_bf16 v[100:103], v[150:153], v[206:209], v[100:103]
	v_mfma_f32_16x16x32_bf16 v[96:99], v[150:153], v[210:213], v[96:99]
	v_mfma_f32_16x16x32_bf16 v[92:95], v[154:157], v[198:201], v[92:95]
	v_mfma_f32_16x16x32_bf16 v[88:91], v[154:157], v[202:205], v[88:91]
	v_mfma_f32_16x16x32_bf16 v[84:87], v[154:157], v[206:209], v[84:87]
	v_mfma_f32_16x16x32_bf16 v[80:83], v[154:157], v[210:213], v[80:83]
	v_mfma_f32_16x16x32_bf16 v[76:79], v[158:161], v[198:201], v[76:79]
	v_mfma_f32_16x16x32_bf16 v[72:75], v[158:161], v[202:205], v[72:75]
	v_mfma_f32_16x16x32_bf16 v[68:71], v[158:161], v[206:209], v[68:71]
	v_mfma_f32_16x16x32_bf16 v[64:67], v[158:161], v[210:213], v[64:67]
	s_add_u32 s48, s48, 0x80
	s_addc_u32 s49, s49, 0
	s_add_i32 s47, s47, 1
	s_waitcnt lgkmcnt(0)
	s_waitcnt vmcnt(0)
	s_barrier
	v_mfma_f32_16x16x32_bf16 v[60:63], v[162:165], v[198:201], v[60:63]
	v_mfma_f32_16x16x32_bf16 v[56:59], v[162:165], v[202:205], v[56:59]
	v_mfma_f32_16x16x32_bf16 v[52:55], v[162:165], v[206:209], v[52:55]
	v_mfma_f32_16x16x32_bf16 v[44:47], v[162:165], v[210:213], v[44:47]
	v_mfma_f32_16x16x32_bf16 v[36:39], v[166:169], v[198:201], v[36:39]
	v_mfma_f32_16x16x32_bf16 v[32:35], v[166:169], v[202:205], v[32:35]
	v_mfma_f32_16x16x32_bf16 v[28:31], v[166:169], v[206:209], v[28:31]
	v_mfma_f32_16x16x32_bf16 v[24:27], v[166:169], v[210:213], v[24:27]
	v_mfma_f32_16x16x32_bf16 v[20:23], v[170:173], v[198:201], v[20:23]
	v_mfma_f32_16x16x32_bf16 v[16:19], v[170:173], v[202:205], v[16:19]
	v_mfma_f32_16x16x32_bf16 v[12:15], v[170:173], v[206:209], v[12:15]
	v_mfma_f32_16x16x32_bf16 v[8:11], v[170:173], v[210:213], v[8:11]
	v_mfma_f32_16x16x32_bf16 v[4:7], v[174:177], v[198:201], v[4:7]
	v_mfma_f32_16x16x32_bf16 v[0:3], v[174:177], v[202:205], v[0:3]
	v_mfma_f32_16x16x32_bf16 v[48:51], v[174:177], v[206:209], v[48:51]
	v_mfma_f32_16x16x32_bf16 v[40:43], v[174:177], v[210:213], v[40:43]
	s_nop 7
	s_nop 7
	s_sub_u32 s48, s48, s34
	s_subb_u32 s49, s49, s35
	s_mov_b32 s62, 0x80000
	s_mov_b32 s63, 0x80000
	s_mov_b64 s[50:51], 0
	s_mov_b64 vcc, exec
	s_branch .LBB0_458

.Lg5_top:
	s_waitcnt lgkmcnt(0)
	s_waitcnt vmcnt(0)
	s_barrier
	v_xor_b32_e32 v180, 0x10000, v180
	v_xor_b32_e32 v245, 0x10000, v245
	v_xor_b32_e32 v244, 0x10000, v244
	v_xor_b32_e32 v246, 0x10000, v246
	s_xor_b32 s87, s87, 0x10000
	ds_read_b128 v[176:179], v180
	ds_read_b128 v[182:185], v180 offset:2048
	ds_read_b128 v[186:189], v180 offset:4096
	ds_read_b128 v[190:193], v180 offset:6144
	ds_read_b128 v[210:213], v245 offset:32768
	ds_read_b128 v[214:217], v245 offset:34816
	ds_read_b128 v[218:221], v245 offset:36864
	ds_read_b128 v[222:225], v245 offset:38912
	v_mfma_f32_16x16x32_bf16 v[60:63], v[194:197], v[226:229], v[60:63]
	v_mfma_f32_16x16x32_bf16 v[56:59], v[194:197], v[230:233], v[56:59]
	v_mfma_f32_16x16x32_bf16 v[52:55], v[194:197], v[234:237], v[52:55]
	v_mfma_f32_16x16x32_bf16 v[48:51], v[194:197], v[238:241], v[48:51]
	s_mov_b32 m0, s87
	s_add_u32 s70, s68, 0x4000080
	s_addc_u32 s71, s69, 0
	global_load_lds_dwordx4 v242, s[70:71]
	v_mfma_f32_16x16x32_bf16 v[44:47], v[198:201], v[226:229], v[44:47]
	v_mfma_f32_16x16x32_bf16 v[40:43], v[198:201], v[230:233], v[40:43]
	v_mfma_f32_16x16x32_bf16 v[36:39], v[198:201], v[234:237], v[36:39]
	v_mfma_f32_16x16x32_bf16 v[32:35], v[198:201], v[238:241], v[32:35]
	s_add_u32 m0, s87, 0x2000
	s_add_u32 s70, s68, 0x4020080
	s_addc_u32 s71, s69, 0
	global_load_lds_dwordx4 v242, s[70:71]
	v_mfma_f32_16x16x32_bf16 v[28:31], v[202:205], v[226:229], v[28:31]
	v_mfma_f32_16x16x32_bf16 v[24:27], v[202:205], v[230:233], v[24:27]
	v_mfma_f32_16x16x32_bf16 v[20:23], v[202:205], v[234:237], v[20:23]
	v_mfma_f32_16x16x32_bf16 v[16:19], v[202:205], v[238:241], v[16:19]
	s_add_u32 m0, s87, 0x4000
	s_add_u32 s70, s68, 0x4040080
	s_addc_u32 s71, s69, 0
	global_load_lds_dwordx4 v242, s[70:71]
	v_mfma_f32_16x16x32_bf16 v[8:11], v[206:209], v[226:229], v[8:11]
	v_mfma_f32_16x16x32_bf16 v[0:3], v[206:209], v[230:233], v[0:3]
	v_mfma_f32_16x16x32_bf16 v[12:15], v[206:209], v[234:237], v[12:15]
	v_mfma_f32_16x16x32_bf16 v[4:7], v[206:209], v[238:241], v[4:7]
	s_add_u32 m0, s87, 0x6000
	s_add_u32 s70, s68, s14
	s_addc_u32 s71, s69, s15
	global_load_lds_dwordx4 v242, s[70:71]
.Lg5_entry:
	ds_read_b128 v[194:197], v180 offset:8192
	ds_read_b128 v[198:201], v180 offset:10240
	ds_read_b128 v[202:205], v180 offset:12288
	ds_read_b128 v[206:209], v180 offset:14336
	s_waitcnt lgkmcnt(4)
	v_mfma_f32_16x16x32_bf16 v[124:127], v[176:179], v[210:213], v[124:127]
	v_mfma_f32_16x16x32_bf16 v[120:123], v[176:179], v[214:217], v[120:123]
	v_mfma_f32_16x16x32_bf16 v[116:119], v[176:179], v[218:221], v[116:119]
	v_mfma_f32_16x16x32_bf16 v[112:115], v[176:179], v[222:225], v[112:115]
	s_add_u32 m0, s87, 0x8000
	s_add_u32 s70, s68, s16
	s_addc_u32 s71, s69, s17
	global_load_lds_dwordx4 v243, s[70:71]
	v_mfma_f32_16x16x32_bf16 v[108:111], v[182:185], v[210:213], v[108:111]
	v_mfma_f32_16x16x32_bf16 v[104:107], v[182:185], v[214:217], v[104:107]
	v_mfma_f32_16x16x32_bf16 v[100:103], v[182:185], v[218:221], v[100:103]
	v_mfma_f32_16x16x32_bf16 v[96:99], v[182:185], v[222:225], v[96:99]
	s_add_u32 m0, s87, 0xa000
	s_add_u32 s70, s68, s18
	s_addc_u32 s71, s69, s19
	global_load_lds_dwordx4 v243, s[70:71]
	v_mfma_f32_16x16x32_bf16 v[92:95], v[186:189], v[210:213], v[92:95]
	v_mfma_f32_16x16x32_bf16 v[88:91], v[186:189], v[214:217], v[88:91]
	v_mfma_f32_16x16x32_bf16 v[84:87], v[186:189], v[218:221], v[84:87]
	v_mfma_f32_16x16x32_bf16 v[80:83], v[186:189], v[222:225], v[80:83]
	s_add_u32 m0, s87, 0xc000
	s_add_u32 s70, s68, s22
	s_addc_u32 s71, s69, s23
	global_load_lds_dwordx4 v243, s[70:71]
	v_mfma_f32_16x16x32_bf16 v[76:79], v[190:193], v[210:213], v[76:79]
	v_mfma_f32_16x16x32_bf16 v[72:75], v[190:193], v[214:217], v[72:75]
	v_mfma_f32_16x16x32_bf16 v[68:71], v[190:193], v[218:221], v[68:71]
	v_mfma_f32_16x16x32_bf16 v[64:67], v[190:193], v[222:225], v[64:67]
	s_add_u32 m0, s87, 0xe000
	s_add_u32 s70, s68, s36
	s_addc_u32 s71, s69, s37
	global_load_lds_dwordx4 v243, s[70:71]
	ds_read_b128 v[176:179], v244
	ds_read_b128 v[182:185], v244 offset:2048
	ds_read_b128 v[186:189], v244 offset:4096
	ds_read_b128 v[190:193], v244 offset:6144
	ds_read_b128 v[226:229], v246 offset:32768
	ds_read_b128 v[230:233], v246 offset:34816
	ds_read_b128 v[234:237], v246 offset:36864
	ds_read_b128 v[238:241], v246 offset:38912
	s_waitcnt lgkmcnt(8)
	v_mfma_f32_16x16x32_bf16 v[60:63], v[194:197], v[210:213], v[60:63]
	v_mfma_f32_16x16x32_bf16 v[56:59], v[194:197], v[214:217], v[56:59]
	v_mfma_f32_16x16x32_bf16 v[52:55], v[194:197], v[218:221], v[52:55]
	v_mfma_f32_16x16x32_bf16 v[48:51], v[194:197], v[222:225], v[48:51]
	v_mfma_f32_16x16x32_bf16 v[44:47], v[198:201], v[210:213], v[44:47]
	v_mfma_f32_16x16x32_bf16 v[40:43], v[198:201], v[214:217], v[40:43]
	v_mfma_f32_16x16x32_bf16 v[36:39], v[198:201], v[218:221], v[36:39]
	v_mfma_f32_16x16x32_bf16 v[32:35], v[198:201], v[222:225], v[32:35]
	v_mfma_f32_16x16x32_bf16 v[28:31], v[202:205], v[210:213], v[28:31]
	v_mfma_f32_16x16x32_bf16 v[24:27], v[202:205], v[214:217], v[24:27]
	v_mfma_f32_16x16x32_bf16 v[20:23], v[202:205], v[218:221], v[20:23]
	v_mfma_f32_16x16x32_bf16 v[16:19], v[202:205], v[222:225], v[16:19]
	v_mfma_f32_16x16x32_bf16 v[8:11], v[206:209], v[210:213], v[8:11]
	v_mfma_f32_16x16x32_bf16 v[0:3], v[206:209], v[214:217], v[0:3]
	v_mfma_f32_16x16x32_bf16 v[12:15], v[206:209], v[218:221], v[12:15]
	v_mfma_f32_16x16x32_bf16 v[4:7], v[206:209], v[222:225], v[4:7]
	ds_read_b128 v[194:197], v244 offset:8192
	ds_read_b128 v[198:201], v244 offset:10240
	ds_read_b128 v[202:205], v244 offset:12288
	ds_read_b128 v[206:209], v244 offset:14336
	s_waitcnt lgkmcnt(4)
	v_mfma_f32_16x16x32_bf16 v[124:127], v[176:179], v[226:229], v[124:127]
	v_mfma_f32_16x16x32_bf16 v[120:123], v[176:179], v[230:233], v[120:123]
	v_mfma_f32_16x16x32_bf16 v[116:119], v[176:179], v[234:237], v[116:119]
	v_mfma_f32_16x16x32_bf16 v[112:115], v[176:179], v[238:241], v[112:115]
	v_mfma_f32_16x16x32_bf16 v[108:111], v[182:185], v[226:229], v[108:111]
	v_mfma_f32_16x16x32_bf16 v[104:107], v[182:185], v[230:233], v[104:107]
	v_mfma_f32_16x16x32_bf16 v[100:103], v[182:185], v[234:237], v[100:103]
	v_mfma_f32_16x16x32_bf16 v[96:99], v[182:185], v[238:241], v[96:99]
	v_mfma_f32_16x16x32_bf16 v[92:95], v[186:189], v[226:229], v[92:95]
	v_mfma_f32_16x16x32_bf16 v[88:91], v[186:189], v[230:233], v[88:91]
	v_mfma_f32_16x16x32_bf16 v[84:87], v[186:189], v[234:237], v[84:87]
	v_mfma_f32_16x16x32_bf16 v[80:83], v[186:189], v[238:241], v[80:83]
	v_mfma_f32_16x16x32_bf16 v[76:79], v[190:193], v[226:229], v[76:79]
	v_mfma_f32_16x16x32_bf16 v[72:75], v[190:193], v[230:233], v[72:75]
	v_mfma_f32_16x16x32_bf16 v[68:71], v[190:193], v[234:237], v[68:71]
	v_mfma_f32_16x16x32_bf16 v[64:67], v[190:193], v[238:241], v[64:67]
	s_add_u32 s68, s68, 0x80
	s_addc_u32 s69, s69, 0
	s_add_i32 s86, s86, 1
	s_cmp_lt_u32 s86, 15
	s_cbranch_scc1 .Lg5_top
	s_waitcnt lgkmcnt(0)
	s_waitcnt vmcnt(0)
	s_barrier
	v_xor_b32_e32 v180, 0x10000, v180
	v_xor_b32_e32 v245, 0x10000, v245
	v_xor_b32_e32 v244, 0x10000, v244
	v_xor_b32_e32 v246, 0x10000, v246
	s_xor_b32 s87, s87, 0x10000
	ds_read_b128 v[176:179], v180
	ds_read_b128 v[182:185], v180 offset:2048
	ds_read_b128 v[186:189], v180 offset:4096
	ds_read_b128 v[190:193], v180 offset:6144
	ds_read_b128 v[210:213], v245 offset:32768
	ds_read_b128 v[214:217], v245 offset:34816
	ds_read_b128 v[218:221], v245 offset:36864
	ds_read_b128 v[222:225], v245 offset:38912
	v_mfma_f32_16x16x32_bf16 v[60:63], v[194:197], v[226:229], v[60:63]
	v_mfma_f32_16x16x32_bf16 v[56:59], v[194:197], v[230:233], v[56:59]
	v_mfma_f32_16x16x32_bf16 v[52:55], v[194:197], v[234:237], v[52:55]
	v_mfma_f32_16x16x32_bf16 v[48:51], v[194:197], v[238:241], v[48:51]
	v_mfma_f32_16x16x32_bf16 v[44:47], v[198:201], v[226:229], v[44:47]
	v_mfma_f32_16x16x32_bf16 v[40:43], v[198:201], v[230:233], v[40:43]
	v_mfma_f32_16x16x32_bf16 v[36:39], v[198:201], v[234:237], v[36:39]
	v_mfma_f32_16x16x32_bf16 v[32:35], v[198:201], v[238:241], v[32:35]
	v_mfma_f32_16x16x32_bf16 v[28:31], v[202:205], v[226:229], v[28:31]
	v_mfma_f32_16x16x32_bf16 v[24:27], v[202:205], v[230:233], v[24:27]
	v_mfma_f32_16x16x32_bf16 v[20:23], v[202:205], v[234:237], v[20:23]
	v_mfma_f32_16x16x32_bf16 v[16:19], v[202:205], v[238:241], v[16:19]
	v_mfma_f32_16x16x32_bf16 v[8:11], v[206:209], v[226:229], v[8:11]
	v_mfma_f32_16x16x32_bf16 v[0:3], v[206:209], v[230:233], v[0:3]
	v_mfma_f32_16x16x32_bf16 v[12:15], v[206:209], v[234:237], v[12:15]
	v_mfma_f32_16x16x32_bf16 v[4:7], v[206:209], v[238:241], v[4:7]
	ds_read_b128 v[194:197], v180 offset:8192
	ds_read_b128 v[198:201], v180 offset:10240
	ds_read_b128 v[202:205], v180 offset:12288
	ds_read_b128 v[206:209], v180 offset:14336
	s_waitcnt lgkmcnt(4)
	v_mfma_f32_16x16x32_bf16 v[124:127], v[176:179], v[210:213], v[124:127]
	v_mfma_f32_16x16x32_bf16 v[120:123], v[176:179], v[214:217], v[120:123]
	v_mfma_f32_16x16x32_bf16 v[116:119], v[176:179], v[218:221], v[116:119]
	v_mfma_f32_16x16x32_bf16 v[112:115], v[176:179], v[222:225], v[112:115]
	v_mfma_f32_16x16x32_bf16 v[108:111], v[182:185], v[210:213], v[108:111]
	v_mfma_f32_16x16x32_bf16 v[104:107], v[182:185], v[214:217], v[104:107]
	v_mfma_f32_16x16x32_bf16 v[100:103], v[182:185], v[218:221], v[100:103]
	v_mfma_f32_16x16x32_bf16 v[96:99], v[182:185], v[222:225], v[96:99]
	v_mfma_f32_16x16x32_bf16 v[92:95], v[186:189], v[210:213], v[92:95]
	v_mfma_f32_16x16x32_bf16 v[88:91], v[186:189], v[214:217], v[88:91]
	v_mfma_f32_16x16x32_bf16 v[84:87], v[186:189], v[218:221], v[84:87]
	v_mfma_f32_16x16x32_bf16 v[80:83], v[186:189], v[222:225], v[80:83]
	v_mfma_f32_16x16x32_bf16 v[76:79], v[190:193], v[210:213], v[76:79]
	v_mfma_f32_16x16x32_bf16 v[72:75], v[190:193], v[214:217], v[72:75]
	v_mfma_f32_16x16x32_bf16 v[68:71], v[190:193], v[218:221], v[68:71]
	v_mfma_f32_16x16x32_bf16 v[64:67], v[190:193], v[222:225], v[64:67]
	ds_read_b128 v[176:179], v244
	ds_read_b128 v[182:185], v244 offset:2048
	ds_read_b128 v[186:189], v244 offset:4096
	ds_read_b128 v[190:193], v244 offset:6144
	ds_read_b128 v[226:229], v246 offset:32768
	ds_read_b128 v[230:233], v246 offset:34816
	ds_read_b128 v[234:237], v246 offset:36864
	ds_read_b128 v[238:241], v246 offset:38912
	s_waitcnt lgkmcnt(8)
	v_mfma_f32_16x16x32_bf16 v[60:63], v[194:197], v[210:213], v[60:63]
	v_mfma_f32_16x16x32_bf16 v[56:59], v[194:197], v[214:217], v[56:59]
	v_mfma_f32_16x16x32_bf16 v[52:55], v[194:197], v[218:221], v[52:55]
	v_mfma_f32_16x16x32_bf16 v[48:51], v[194:197], v[222:225], v[48:51]
	v_mfma_f32_16x16x32_bf16 v[44:47], v[198:201], v[210:213], v[44:47]
	v_mfma_f32_16x16x32_bf16 v[40:43], v[198:201], v[214:217], v[40:43]
	v_mfma_f32_16x16x32_bf16 v[36:39], v[198:201], v[218:221], v[36:39]
	v_mfma_f32_16x16x32_bf16 v[32:35], v[198:201], v[222:225], v[32:35]
	v_mfma_f32_16x16x32_bf16 v[28:31], v[202:205], v[210:213], v[28:31]
	v_mfma_f32_16x16x32_bf16 v[24:27], v[202:205], v[214:217], v[24:27]
	v_mfma_f32_16x16x32_bf16 v[20:23], v[202:205], v[218:221], v[20:23]
	v_mfma_f32_16x16x32_bf16 v[16:19], v[202:205], v[222:225], v[16:19]
	v_mfma_f32_16x16x32_bf16 v[8:11], v[206:209], v[210:213], v[8:11]
	v_mfma_f32_16x16x32_bf16 v[0:3], v[206:209], v[214:217], v[0:3]
	v_mfma_f32_16x16x32_bf16 v[12:15], v[206:209], v[218:221], v[12:15]
	v_mfma_f32_16x16x32_bf16 v[4:7], v[206:209], v[222:225], v[4:7]
	ds_read_b128 v[194:197], v244 offset:8192
	ds_read_b128 v[198:201], v244 offset:10240
	ds_read_b128 v[202:205], v244 offset:12288
	ds_read_b128 v[206:209], v244 offset:14336
	s_waitcnt lgkmcnt(4)
	v_mfma_f32_16x16x32_bf16 v[124:127], v[176:179], v[226:229], v[124:127]
	v_mfma_f32_16x16x32_bf16 v[120:123], v[176:179], v[230:233], v[120:123]
	v_mfma_f32_16x16x32_bf16 v[116:119], v[176:179], v[234:237], v[116:119]
	v_mfma_f32_16x16x32_bf16 v[112:115], v[176:179], v[238:241], v[112:115]
	v_mfma_f32_16x16x32_bf16 v[108:111], v[182:185], v[226:229], v[108:111]
	v_mfma_f32_16x16x32_bf16 v[104:107], v[182:185], v[230:233], v[104:107]
	v_mfma_f32_16x16x32_bf16 v[100:103], v[182:185], v[234:237], v[100:103]
	v_mfma_f32_16x16x32_bf16 v[96:99], v[182:185], v[238:241], v[96:99]
	v_mfma_f32_16x16x32_bf16 v[92:95], v[186:189], v[226:229], v[92:95]
	v_mfma_f32_16x16x32_bf16 v[88:91], v[186:189], v[230:233], v[88:91]
	v_mfma_f32_16x16x32_bf16 v[84:87], v[186:189], v[234:237], v[84:87]
	v_mfma_f32_16x16x32_bf16 v[80:83], v[186:189], v[238:241], v[80:83]
	v_mfma_f32_16x16x32_bf16 v[76:79], v[190:193], v[226:229], v[76:79]
	v_mfma_f32_16x16x32_bf16 v[72:75], v[190:193], v[230:233], v[72:75]
	v_mfma_f32_16x16x32_bf16 v[68:71], v[190:193], v[234:237], v[68:71]
	v_mfma_f32_16x16x32_bf16 v[64:67], v[190:193], v[238:241], v[64:67]
	s_add_u32 s68, s68, 0x80
	s_addc_u32 s69, s69, 0
	s_add_i32 s86, s86, 1
	s_waitcnt lgkmcnt(0)
	s_waitcnt vmcnt(0)
	s_barrier
	v_mfma_f32_16x16x32_bf16 v[60:63], v[194:197], v[226:229], v[60:63]
	v_mfma_f32_16x16x32_bf16 v[56:59], v[194:197], v[230:233], v[56:59]
	v_mfma_f32_16x16x32_bf16 v[52:55], v[194:197], v[234:237], v[52:55]
	v_mfma_f32_16x16x32_bf16 v[48:51], v[194:197], v[238:241], v[48:51]
	v_mfma_f32_16x16x32_bf16 v[44:47], v[198:201], v[226:229], v[44:47]
	v_mfma_f32_16x16x32_bf16 v[40:43], v[198:201], v[230:233], v[40:43]
	v_mfma_f32_16x16x32_bf16 v[36:39], v[198:201], v[234:237], v[36:39]
	v_mfma_f32_16x16x32_bf16 v[32:35], v[198:201], v[238:241], v[32:35]
	v_mfma_f32_16x16x32_bf16 v[28:31], v[202:205], v[226:229], v[28:31]
	v_mfma_f32_16x16x32_bf16 v[24:27], v[202:205], v[230:233], v[24:27]
	v_mfma_f32_16x16x32_bf16 v[20:23], v[202:205], v[234:237], v[20:23]
	v_mfma_f32_16x16x32_bf16 v[16:19], v[202:205], v[238:241], v[16:19]
	v_mfma_f32_16x16x32_bf16 v[8:11], v[206:209], v[226:229], v[8:11]
	v_mfma_f32_16x16x32_bf16 v[0:3], v[206:209], v[230:233], v[0:3]
	v_mfma_f32_16x16x32_bf16 v[12:15], v[206:209], v[234:237], v[12:15]
	v_mfma_f32_16x16x32_bf16 v[4:7], v[206:209], v[238:241], v[4:7]
	s_nop 7
	s_nop 7
	s_sub_u32 s68, s68, s34
	s_subb_u32 s69, s69, s35
	s_mov_b32 s87, 0x80000
	s_mov_b32 s87, 0x80000
	s_mov_b64 s[70:71], 0
	s_mov_b64 vcc, exec
	s_branch .LBB0_666

.Lg6_top:
	s_waitcnt lgkmcnt(0)
	s_waitcnt vmcnt(0)
	s_barrier
	v_xor_b32_e32 v180, 0x10000, v180
	v_xor_b32_e32 v249, 0x10000, v249
	v_xor_b32_e32 v248, 0x10000, v248
	v_xor_b32_e32 v250, 0x10000, v250
	s_xor_b32 s69, s69, 0x10000
	ds_read_b128 v[182:185], v180
	ds_read_b128 v[186:189], v180 offset:2048
	ds_read_b128 v[190:193], v180 offset:4096
	ds_read_b128 v[194:197], v180 offset:6144
	ds_read_b128 v[214:217], v249 offset:32768
	ds_read_b128 v[218:221], v249 offset:34816
	ds_read_b128 v[222:225], v249 offset:36864
	ds_read_b128 v[226:229], v249 offset:38912
	v_mfma_f32_16x16x32_bf16 v[60:63], v[198:201], v[230:233], v[60:63]
	v_mfma_f32_16x16x32_bf16 v[56:59], v[198:201], v[234:237], v[56:59]
	v_mfma_f32_16x16x32_bf16 v[52:55], v[198:201], v[238:241], v[52:55]
	v_mfma_f32_16x16x32_bf16 v[48:51], v[198:201], v[242:245], v[48:51]
	s_mov_b32 m0, s69
	s_add_u32 s66, s64, s44
	s_addc_u32 s67, s65, s45
	global_load_lds_dwordx4 v246, s[66:67]
	v_mfma_f32_16x16x32_bf16 v[44:47], v[202:205], v[230:233], v[44:47]
	v_mfma_f32_16x16x32_bf16 v[40:43], v[202:205], v[234:237], v[40:43]
	v_mfma_f32_16x16x32_bf16 v[36:39], v[202:205], v[238:241], v[36:39]
	v_mfma_f32_16x16x32_bf16 v[32:35], v[202:205], v[242:245], v[32:35]
	s_add_u32 m0, s69, 0x2000
	s_add_u32 s66, s64, s46
	s_addc_u32 s67, s65, s47
	global_load_lds_dwordx4 v246, s[66:67]
	v_mfma_f32_16x16x32_bf16 v[28:31], v[206:209], v[230:233], v[28:31]
	v_mfma_f32_16x16x32_bf16 v[24:27], v[206:209], v[234:237], v[24:27]
	v_mfma_f32_16x16x32_bf16 v[20:23], v[206:209], v[238:241], v[20:23]
	v_mfma_f32_16x16x32_bf16 v[16:19], v[206:209], v[242:245], v[16:19]
	s_add_u32 m0, s69, 0x4000
	s_add_u32 s66, s64, s48
	s_addc_u32 s67, s65, s49
	global_load_lds_dwordx4 v246, s[66:67]
	v_mfma_f32_16x16x32_bf16 v[12:15], v[210:213], v[230:233], v[12:15]
	v_mfma_f32_16x16x32_bf16 v[0:3], v[210:213], v[234:237], v[0:3]
	v_mfma_f32_16x16x32_bf16 v[8:11], v[210:213], v[238:241], v[8:11]
	v_mfma_f32_16x16x32_bf16 v[4:7], v[210:213], v[242:245], v[4:7]
	s_add_u32 m0, s69, 0x6000
	s_add_u32 s66, s64, s50
	s_addc_u32 s67, s65, s51
	global_load_lds_dwordx4 v246, s[66:67]
.Lg6_entry:
	ds_read_b128 v[198:201], v180 offset:8192
	ds_read_b128 v[202:205], v180 offset:10240
	ds_read_b128 v[206:209], v180 offset:12288
	ds_read_b128 v[210:213], v180 offset:14336
	s_waitcnt lgkmcnt(4)
	v_mfma_f32_16x16x32_bf16 v[124:127], v[182:185], v[214:217], v[124:127]
	v_mfma_f32_16x16x32_bf16 v[120:123], v[182:185], v[218:221], v[120:123]
	v_mfma_f32_16x16x32_bf16 v[116:119], v[182:185], v[222:225], v[116:119]
	v_mfma_f32_16x16x32_bf16 v[112:115], v[182:185], v[226:229], v[112:115]
	s_add_u32 m0, s69, 0x8000
	s_add_u32 s66, s64, s52
	s_addc_u32 s67, s65, s53
	global_load_lds_dwordx4 v247, s[66:67]
	v_mfma_f32_16x16x32_bf16 v[108:111], v[186:189], v[214:217], v[108:111]
	v_mfma_f32_16x16x32_bf16 v[104:107], v[186:189], v[218:221], v[104:107]
	v_mfma_f32_16x16x32_bf16 v[100:103], v[186:189], v[222:225], v[100:103]
	v_mfma_f32_16x16x32_bf16 v[96:99], v[186:189], v[226:229], v[96:99]
	s_add_u32 m0, s69, 0xa000
	s_add_u32 s66, s64, s54
	s_addc_u32 s67, s65, s55
	global_load_lds_dwordx4 v247, s[66:67]
	v_mfma_f32_16x16x32_bf16 v[92:95], v[190:193], v[214:217], v[92:95]
	v_mfma_f32_16x16x32_bf16 v[88:91], v[190:193], v[218:221], v[88:91]
	v_mfma_f32_16x16x32_bf16 v[84:87], v[190:193], v[222:225], v[84:87]
	v_mfma_f32_16x16x32_bf16 v[80:83], v[190:193], v[226:229], v[80:83]
	s_add_u32 m0, s69, 0xc000
	s_add_u32 s66, s64, s60
	s_addc_u32 s67, s65, s61
	global_load_lds_dwordx4 v247, s[66:67]
	v_mfma_f32_16x16x32_bf16 v[76:79], v[194:197], v[214:217], v[76:79]
	v_mfma_f32_16x16x32_bf16 v[72:75], v[194:197], v[218:221], v[72:75]
	v_mfma_f32_16x16x32_bf16 v[68:71], v[194:197], v[222:225], v[68:71]
	v_mfma_f32_16x16x32_bf16 v[64:67], v[194:197], v[226:229], v[64:67]
	s_add_u32 m0, s69, 0xe000
	s_add_u32 s66, s64, s62
	s_addc_u32 s67, s65, s63
	global_load_lds_dwordx4 v247, s[66:67]
	ds_read_b128 v[182:185], v248
	ds_read_b128 v[186:189], v248 offset:2048
	ds_read_b128 v[190:193], v248 offset:4096
	ds_read_b128 v[194:197], v248 offset:6144
	ds_read_b128 v[230:233], v250 offset:32768
	ds_read_b128 v[234:237], v250 offset:34816
	ds_read_b128 v[238:241], v250 offset:36864
	ds_read_b128 v[242:245], v250 offset:38912
	s_waitcnt lgkmcnt(8)
	v_mfma_f32_16x16x32_bf16 v[60:63], v[198:201], v[214:217], v[60:63]
	v_mfma_f32_16x16x32_bf16 v[56:59], v[198:201], v[218:221], v[56:59]
	v_mfma_f32_16x16x32_bf16 v[52:55], v[198:201], v[222:225], v[52:55]
	v_mfma_f32_16x16x32_bf16 v[48:51], v[198:201], v[226:229], v[48:51]
	v_mfma_f32_16x16x32_bf16 v[44:47], v[202:205], v[214:217], v[44:47]
	v_mfma_f32_16x16x32_bf16 v[40:43], v[202:205], v[218:221], v[40:43]
	v_mfma_f32_16x16x32_bf16 v[36:39], v[202:205], v[222:225], v[36:39]
	v_mfma_f32_16x16x32_bf16 v[32:35], v[202:205], v[226:229], v[32:35]
	v_mfma_f32_16x16x32_bf16 v[28:31], v[206:209], v[214:217], v[28:31]
	v_mfma_f32_16x16x32_bf16 v[24:27], v[206:209], v[218:221], v[24:27]
	v_mfma_f32_16x16x32_bf16 v[20:23], v[206:209], v[222:225], v[20:23]
	v_mfma_f32_16x16x32_bf16 v[16:19], v[206:209], v[226:229], v[16:19]
	v_mfma_f32_16x16x32_bf16 v[12:15], v[210:213], v[214:217], v[12:15]
	v_mfma_f32_16x16x32_bf16 v[0:3], v[210:213], v[218:221], v[0:3]
	v_mfma_f32_16x16x32_bf16 v[8:11], v[210:213], v[222:225], v[8:11]
	v_mfma_f32_16x16x32_bf16 v[4:7], v[210:213], v[226:229], v[4:7]
	ds_read_b128 v[198:201], v248 offset:8192
	ds_read_b128 v[202:205], v248 offset:10240
	ds_read_b128 v[206:209], v248 offset:12288
	ds_read_b128 v[210:213], v248 offset:14336
	s_waitcnt lgkmcnt(4)
	v_mfma_f32_16x16x32_bf16 v[124:127], v[182:185], v[230:233], v[124:127]
	v_mfma_f32_16x16x32_bf16 v[120:123], v[182:185], v[234:237], v[120:123]
	v_mfma_f32_16x16x32_bf16 v[116:119], v[182:185], v[238:241], v[116:119]
	v_mfma_f32_16x16x32_bf16 v[112:115], v[182:185], v[242:245], v[112:115]
	v_mfma_f32_16x16x32_bf16 v[108:111], v[186:189], v[230:233], v[108:111]
	v_mfma_f32_16x16x32_bf16 v[104:107], v[186:189], v[234:237], v[104:107]
	v_mfma_f32_16x16x32_bf16 v[100:103], v[186:189], v[238:241], v[100:103]
	v_mfma_f32_16x16x32_bf16 v[96:99], v[186:189], v[242:245], v[96:99]
	v_mfma_f32_16x16x32_bf16 v[92:95], v[190:193], v[230:233], v[92:95]
	v_mfma_f32_16x16x32_bf16 v[88:91], v[190:193], v[234:237], v[88:91]
	v_mfma_f32_16x16x32_bf16 v[84:87], v[190:193], v[238:241], v[84:87]
	v_mfma_f32_16x16x32_bf16 v[80:83], v[190:193], v[242:245], v[80:83]
	v_mfma_f32_16x16x32_bf16 v[76:79], v[194:197], v[230:233], v[76:79]
	v_mfma_f32_16x16x32_bf16 v[72:75], v[194:197], v[234:237], v[72:75]
	v_mfma_f32_16x16x32_bf16 v[68:71], v[194:197], v[238:241], v[68:71]
	v_mfma_f32_16x16x32_bf16 v[64:67], v[194:197], v[242:245], v[64:67]
	s_add_u32 s64, s64, 0x80
	s_addc_u32 s65, s65, 0
	s_add_i32 s68, s68, 1
	s_cmp_lt_u32 s68, 31
	s_cbranch_scc1 .Lg6_top
	s_waitcnt lgkmcnt(0)
	s_waitcnt vmcnt(0)
	s_barrier
	v_xor_b32_e32 v180, 0x10000, v180
	v_xor_b32_e32 v249, 0x10000, v249
	v_xor_b32_e32 v248, 0x10000, v248
	v_xor_b32_e32 v250, 0x10000, v250
	s_xor_b32 s69, s69, 0x10000
	ds_read_b128 v[182:185], v180
	ds_read_b128 v[186:189], v180 offset:2048
	ds_read_b128 v[190:193], v180 offset:4096
	ds_read_b128 v[194:197], v180 offset:6144
	ds_read_b128 v[214:217], v249 offset:32768
	ds_read_b128 v[218:221], v249 offset:34816
	ds_read_b128 v[222:225], v249 offset:36864
	ds_read_b128 v[226:229], v249 offset:38912
	v_mfma_f32_16x16x32_bf16 v[60:63], v[198:201], v[230:233], v[60:63]
	v_mfma_f32_16x16x32_bf16 v[56:59], v[198:201], v[234:237], v[56:59]
	v_mfma_f32_16x16x32_bf16 v[52:55], v[198:201], v[238:241], v[52:55]
	v_mfma_f32_16x16x32_bf16 v[48:51], v[198:201], v[242:245], v[48:51]
	v_mfma_f32_16x16x32_bf16 v[44:47], v[202:205], v[230:233], v[44:47]
	v_mfma_f32_16x16x32_bf16 v[40:43], v[202:205], v[234:237], v[40:43]
	v_mfma_f32_16x16x32_bf16 v[36:39], v[202:205], v[238:241], v[36:39]
	v_mfma_f32_16x16x32_bf16 v[32:35], v[202:205], v[242:245], v[32:35]
	v_mfma_f32_16x16x32_bf16 v[28:31], v[206:209], v[230:233], v[28:31]
	v_mfma_f32_16x16x32_bf16 v[24:27], v[206:209], v[234:237], v[24:27]
	v_mfma_f32_16x16x32_bf16 v[20:23], v[206:209], v[238:241], v[20:23]
	v_mfma_f32_16x16x32_bf16 v[16:19], v[206:209], v[242:245], v[16:19]
	v_mfma_f32_16x16x32_bf16 v[12:15], v[210:213], v[230:233], v[12:15]
	v_mfma_f32_16x16x32_bf16 v[0:3], v[210:213], v[234:237], v[0:3]
	v_mfma_f32_16x16x32_bf16 v[8:11], v[210:213], v[238:241], v[8:11]
	v_mfma_f32_16x16x32_bf16 v[4:7], v[210:213], v[242:245], v[4:7]
	ds_read_b128 v[198:201], v180 offset:8192
	ds_read_b128 v[202:205], v180 offset:10240
	ds_read_b128 v[206:209], v180 offset:12288
	ds_read_b128 v[210:213], v180 offset:14336
	s_waitcnt lgkmcnt(4)
	v_mfma_f32_16x16x32_bf16 v[124:127], v[182:185], v[214:217], v[124:127]
	v_mfma_f32_16x16x32_bf16 v[120:123], v[182:185], v[218:221], v[120:123]
	v_mfma_f32_16x16x32_bf16 v[116:119], v[182:185], v[222:225], v[116:119]
	v_mfma_f32_16x16x32_bf16 v[112:115], v[182:185], v[226:229], v[112:115]
	v_mfma_f32_16x16x32_bf16 v[108:111], v[186:189], v[214:217], v[108:111]
	v_mfma_f32_16x16x32_bf16 v[104:107], v[186:189], v[218:221], v[104:107]
	v_mfma_f32_16x16x32_bf16 v[100:103], v[186:189], v[222:225], v[100:103]
	v_mfma_f32_16x16x32_bf16 v[96:99], v[186:189], v[226:229], v[96:99]
	v_mfma_f32_16x16x32_bf16 v[92:95], v[190:193], v[214:217], v[92:95]
	v_mfma_f32_16x16x32_bf16 v[88:91], v[190:193], v[218:221], v[88:91]
	v_mfma_f32_16x16x32_bf16 v[84:87], v[190:193], v[222:225], v[84:87]
	v_mfma_f32_16x16x32_bf16 v[80:83], v[190:193], v[226:229], v[80:83]
	v_mfma_f32_16x16x32_bf16 v[76:79], v[194:197], v[214:217], v[76:79]
	v_mfma_f32_16x16x32_bf16 v[72:75], v[194:197], v[218:221], v[72:75]
	v_mfma_f32_16x16x32_bf16 v[68:71], v[194:197], v[222:225], v[68:71]
	v_mfma_f32_16x16x32_bf16 v[64:67], v[194:197], v[226:229], v[64:67]
	ds_read_b128 v[182:185], v248
	ds_read_b128 v[186:189], v248 offset:2048
	ds_read_b128 v[190:193], v248 offset:4096
	ds_read_b128 v[194:197], v248 offset:6144
	ds_read_b128 v[230:233], v250 offset:32768
	ds_read_b128 v[234:237], v250 offset:34816
	ds_read_b128 v[238:241], v250 offset:36864
	ds_read_b128 v[242:245], v250 offset:38912
	s_waitcnt lgkmcnt(8)
	v_mfma_f32_16x16x32_bf16 v[60:63], v[198:201], v[214:217], v[60:63]
	v_mfma_f32_16x16x32_bf16 v[56:59], v[198:201], v[218:221], v[56:59]
	v_mfma_f32_16x16x32_bf16 v[52:55], v[198:201], v[222:225], v[52:55]
	v_mfma_f32_16x16x32_bf16 v[48:51], v[198:201], v[226:229], v[48:51]
	v_mfma_f32_16x16x32_bf16 v[44:47], v[202:205], v[214:217], v[44:47]
	v_mfma_f32_16x16x32_bf16 v[40:43], v[202:205], v[218:221], v[40:43]
	v_mfma_f32_16x16x32_bf16 v[36:39], v[202:205], v[222:225], v[36:39]
	v_mfma_f32_16x16x32_bf16 v[32:35], v[202:205], v[226:229], v[32:35]
	v_mfma_f32_16x16x32_bf16 v[28:31], v[206:209], v[214:217], v[28:31]
	v_mfma_f32_16x16x32_bf16 v[24:27], v[206:209], v[218:221], v[24:27]
	v_mfma_f32_16x16x32_bf16 v[20:23], v[206:209], v[222:225], v[20:23]
	v_mfma_f32_16x16x32_bf16 v[16:19], v[206:209], v[226:229], v[16:19]
	v_mfma_f32_16x16x32_bf16 v[12:15], v[210:213], v[214:217], v[12:15]
	v_mfma_f32_16x16x32_bf16 v[0:3], v[210:213], v[218:221], v[0:3]
	v_mfma_f32_16x16x32_bf16 v[8:11], v[210:213], v[222:225], v[8:11]
	v_mfma_f32_16x16x32_bf16 v[4:7], v[210:213], v[226:229], v[4:7]
	ds_read_b128 v[198:201], v248 offset:8192
	ds_read_b128 v[202:205], v248 offset:10240
	ds_read_b128 v[206:209], v248 offset:12288
	ds_read_b128 v[210:213], v248 offset:14336
	s_waitcnt lgkmcnt(4)
	v_mfma_f32_16x16x32_bf16 v[124:127], v[182:185], v[230:233], v[124:127]
	v_mfma_f32_16x16x32_bf16 v[120:123], v[182:185], v[234:237], v[120:123]
	v_mfma_f32_16x16x32_bf16 v[116:119], v[182:185], v[238:241], v[116:119]
	v_mfma_f32_16x16x32_bf16 v[112:115], v[182:185], v[242:245], v[112:115]
	v_mfma_f32_16x16x32_bf16 v[108:111], v[186:189], v[230:233], v[108:111]
	v_mfma_f32_16x16x32_bf16 v[104:107], v[186:189], v[234:237], v[104:107]
	v_mfma_f32_16x16x32_bf16 v[100:103], v[186:189], v[238:241], v[100:103]
	v_mfma_f32_16x16x32_bf16 v[96:99], v[186:189], v[242:245], v[96:99]
	v_mfma_f32_16x16x32_bf16 v[92:95], v[190:193], v[230:233], v[92:95]
	v_mfma_f32_16x16x32_bf16 v[88:91], v[190:193], v[234:237], v[88:91]
	v_mfma_f32_16x16x32_bf16 v[84:87], v[190:193], v[238:241], v[84:87]
	v_mfma_f32_16x16x32_bf16 v[80:83], v[190:193], v[242:245], v[80:83]
	v_mfma_f32_16x16x32_bf16 v[76:79], v[194:197], v[230:233], v[76:79]
	v_mfma_f32_16x16x32_bf16 v[72:75], v[194:197], v[234:237], v[72:75]
	v_mfma_f32_16x16x32_bf16 v[68:71], v[194:197], v[238:241], v[68:71]
	v_mfma_f32_16x16x32_bf16 v[64:67], v[194:197], v[242:245], v[64:67]
	s_add_u32 s64, s64, 0x80
	s_addc_u32 s65, s65, 0
	s_add_i32 s68, s68, 1
	s_waitcnt lgkmcnt(0)
	s_waitcnt vmcnt(0)
	s_barrier
	v_mfma_f32_16x16x32_bf16 v[60:63], v[198:201], v[230:233], v[60:63]
	v_mfma_f32_16x16x32_bf16 v[56:59], v[198:201], v[234:237], v[56:59]
	v_mfma_f32_16x16x32_bf16 v[52:55], v[198:201], v[238:241], v[52:55]
	v_mfma_f32_16x16x32_bf16 v[48:51], v[198:201], v[242:245], v[48:51]
	v_mfma_f32_16x16x32_bf16 v[44:47], v[202:205], v[230:233], v[44:47]
	v_mfma_f32_16x16x32_bf16 v[40:43], v[202:205], v[234:237], v[40:43]
	v_mfma_f32_16x16x32_bf16 v[36:39], v[202:205], v[238:241], v[36:39]
	v_mfma_f32_16x16x32_bf16 v[32:35], v[202:205], v[242:245], v[32:35]
	v_mfma_f32_16x16x32_bf16 v[28:31], v[206:209], v[230:233], v[28:31]
	v_mfma_f32_16x16x32_bf16 v[24:27], v[206:209], v[234:237], v[24:27]
	v_mfma_f32_16x16x32_bf16 v[20:23], v[206:209], v[238:241], v[20:23]
	v_mfma_f32_16x16x32_bf16 v[16:19], v[206:209], v[242:245], v[16:19]
	v_mfma_f32_16x16x32_bf16 v[12:15], v[210:213], v[230:233], v[12:15]
	v_mfma_f32_16x16x32_bf16 v[0:3], v[210:213], v[234:237], v[0:3]
	v_mfma_f32_16x16x32_bf16 v[8:11], v[210:213], v[238:241], v[8:11]
	v_mfma_f32_16x16x32_bf16 v[4:7], v[210:213], v[242:245], v[4:7]
	s_nop 7
	s_nop 7
	s_sub_u32 s64, s64, s34
	s_subb_u32 s65, s65, s35
	s_mov_b32 s69, 0x100000
	s_mov_b32 s70, 0x100000
	s_mov_b64 s[66:67], 0
	s_mov_b64 vcc, exec
	s_branch .LBB0_674

.Lg7_top:
	s_waitcnt lgkmcnt(0)
	s_waitcnt vmcnt(0)
	s_barrier
	v_xor_b32_e32 v141, 0x10000, v141
	v_xor_b32_e32 v210, 0x10000, v210
	v_xor_b32_e32 v180, 0x10000, v180
	v_xor_b32_e32 v211, 0x10000, v211
	s_xor_b32 s61, s61, 0x10000
	ds_read_b128 v[142:145], v141
	ds_read_b128 v[146:149], v141 offset:2048
	ds_read_b128 v[150:153], v141 offset:4096
	ds_read_b128 v[154:157], v141 offset:6144
	ds_read_b128 v[174:177], v210 offset:32768
	ds_read_b128 v[182:185], v210 offset:34816
	ds_read_b128 v[186:189], v210 offset:36864
	ds_read_b128 v[190:193], v210 offset:38912
	v_mfma_f32_16x16x32_bf16 v[60:63], v[158:161], v[194:197], v[60:63]
	v_mfma_f32_16x16x32_bf16 v[56:59], v[158:161], v[198:201], v[56:59]
	v_mfma_f32_16x16x32_bf16 v[52:55], v[158:161], v[202:205], v[52:55]
	v_mfma_f32_16x16x32_bf16 v[48:51], v[158:161], v[206:209], v[48:51]
	s_mov_b32 m0, s61
	s_add_u32 s50, s48, s14
	s_addc_u32 s51, s49, s15
	global_load_lds_dwordx4 v178, s[50:51]
	v_mfma_f32_16x16x32_bf16 v[44:47], v[162:165], v[194:197], v[44:47]
	v_mfma_f32_16x16x32_bf16 v[32:35], v[162:165], v[198:201], v[32:35]
	v_mfma_f32_16x16x32_bf16 v[28:31], v[162:165], v[202:205], v[28:31]
	v_mfma_f32_16x16x32_bf16 v[24:27], v[162:165], v[206:209], v[24:27]
	s_add_u32 m0, s61, 0x2000
	s_add_u32 s50, s48, s16
	s_addc_u32 s51, s49, s17
	global_load_lds_dwordx4 v178, s[50:51]
	v_mfma_f32_16x16x32_bf16 v[20:23], v[166:169], v[194:197], v[20:23]
	v_mfma_f32_16x16x32_bf16 v[16:19], v[166:169], v[198:201], v[16:19]
	v_mfma_f32_16x16x32_bf16 v[12:15], v[166:169], v[202:205], v[12:15]
	v_mfma_f32_16x16x32_bf16 v[8:11], v[166:169], v[206:209], v[8:11]
	s_add_u32 m0, s61, 0x4000
	s_add_u32 s50, s48, s18
	s_addc_u32 s51, s49, s19
	global_load_lds_dwordx4 v178, s[50:51]
	v_mfma_f32_16x16x32_bf16 v[4:7], v[170:173], v[194:197], v[4:7]
	v_mfma_f32_16x16x32_bf16 v[0:3], v[170:173], v[198:201], v[0:3]
	v_mfma_f32_16x16x32_bf16 v[40:43], v[170:173], v[202:205], v[40:43]
	v_mfma_f32_16x16x32_bf16 v[36:39], v[170:173], v[206:209], v[36:39]
	s_add_u32 m0, s61, 0x6000
	s_add_u32 s50, s48, s22
	s_addc_u32 s51, s49, s23
	global_load_lds_dwordx4 v178, s[50:51]
.Lg7_entry:
	ds_read_b128 v[158:161], v141 offset:8192
	ds_read_b128 v[162:165], v141 offset:10240
	ds_read_b128 v[166:169], v141 offset:12288
	ds_read_b128 v[170:173], v141 offset:14336
	s_waitcnt lgkmcnt(4)
	v_mfma_f32_16x16x32_bf16 v[124:127], v[142:145], v[174:177], v[124:127]
	v_mfma_f32_16x16x32_bf16 v[120:123], v[142:145], v[182:185], v[120:123]
	v_mfma_f32_16x16x32_bf16 v[116:119], v[142:145], v[186:189], v[116:119]
	v_mfma_f32_16x16x32_bf16 v[112:115], v[142:145], v[190:193], v[112:115]
	s_add_u32 m0, s61, 0x8000
	s_add_u32 s50, s48, s36
	s_addc_u32 s51, s49, s37
	global_load_lds_dwordx4 v179, s[50:51]
	v_mfma_f32_16x16x32_bf16 v[108:111], v[146:149], v[174:177], v[108:111]
	v_mfma_f32_16x16x32_bf16 v[104:107], v[146:149], v[182:185], v[104:107]
	v_mfma_f32_16x16x32_bf16 v[100:103], v[146:149], v[186:189], v[100:103]
	v_mfma_f32_16x16x32_bf16 v[96:99], v[146:149], v[190:193], v[96:99]
	s_add_u32 m0, s61, 0xa000
	s_add_u32 s50, s48, s40
	s_addc_u32 s51, s49, s41
	global_load_lds_dwordx4 v179, s[50:51]
	v_mfma_f32_16x16x32_bf16 v[92:95], v[150:153], v[174:177], v[92:95]
	v_mfma_f32_16x16x32_bf16 v[88:91], v[150:153], v[182:185], v[88:91]
	v_mfma_f32_16x16x32_bf16 v[84:87], v[150:153], v[186:189], v[84:87]
	v_mfma_f32_16x16x32_bf16 v[80:83], v[150:153], v[190:193], v[80:83]
	s_add_u32 m0, s61, 0xc000
	s_add_u32 s50, s48, s42
	s_addc_u32 s51, s49, s43
	global_load_lds_dwordx4 v179, s[50:51]
	v_mfma_f32_16x16x32_bf16 v[76:79], v[154:157], v[174:177], v[76:79]
	v_mfma_f32_16x16x32_bf16 v[72:75], v[154:157], v[182:185], v[72:75]
	v_mfma_f32_16x16x32_bf16 v[68:71], v[154:157], v[186:189], v[68:71]
	v_mfma_f32_16x16x32_bf16 v[64:67], v[154:157], v[190:193], v[64:67]
	s_add_u32 m0, s61, 0xe000
	s_add_u32 s50, s48, s44
	s_addc_u32 s51, s49, s45
	global_load_lds_dwordx4 v179, s[50:51]
	ds_read_b128 v[142:145], v180
	ds_read_b128 v[146:149], v180 offset:2048
	ds_read_b128 v[150:153], v180 offset:4096
	ds_read_b128 v[154:157], v180 offset:6144
	ds_read_b128 v[194:197], v211 offset:32768
	ds_read_b128 v[198:201], v211 offset:34816
	ds_read_b128 v[202:205], v211 offset:36864
	ds_read_b128 v[206:209], v211 offset:38912
	s_waitcnt lgkmcnt(8)
	v_mfma_f32_16x16x32_bf16 v[60:63], v[158:161], v[174:177], v[60:63]
	v_mfma_f32_16x16x32_bf16 v[56:59], v[158:161], v[182:185], v[56:59]
	v_mfma_f32_16x16x32_bf16 v[52:55], v[158:161], v[186:189], v[52:55]
	v_mfma_f32_16x16x32_bf16 v[48:51], v[158:161], v[190:193], v[48:51]
	v_mfma_f32_16x16x32_bf16 v[44:47], v[162:165], v[174:177], v[44:47]
	v_mfma_f32_16x16x32_bf16 v[32:35], v[162:165], v[182:185], v[32:35]
	v_mfma_f32_16x16x32_bf16 v[28:31], v[162:165], v[186:189], v[28:31]
	v_mfma_f32_16x16x32_bf16 v[24:27], v[162:165], v[190:193], v[24:27]
	v_mfma_f32_16x16x32_bf16 v[20:23], v[166:169], v[174:177], v[20:23]
	v_mfma_f32_16x16x32_bf16 v[16:19], v[166:169], v[182:185], v[16:19]
	v_mfma_f32_16x16x32_bf16 v[12:15], v[166:169], v[186:189], v[12:15]
	v_mfma_f32_16x16x32_bf16 v[8:11], v[166:169], v[190:193], v[8:11]
	v_mfma_f32_16x16x32_bf16 v[4:7], v[170:173], v[174:177], v[4:7]
	v_mfma_f32_16x16x32_bf16 v[0:3], v[170:173], v[182:185], v[0:3]
	v_mfma_f32_16x16x32_bf16 v[40:43], v[170:173], v[186:189], v[40:43]
	v_mfma_f32_16x16x32_bf16 v[36:39], v[170:173], v[190:193], v[36:39]
	ds_read_b128 v[158:161], v180 offset:8192
	ds_read_b128 v[162:165], v180 offset:10240
	ds_read_b128 v[166:169], v180 offset:12288
	ds_read_b128 v[170:173], v180 offset:14336
	s_waitcnt lgkmcnt(4)
	v_mfma_f32_16x16x32_bf16 v[124:127], v[142:145], v[194:197], v[124:127]
	v_mfma_f32_16x16x32_bf16 v[120:123], v[142:145], v[198:201], v[120:123]
	v_mfma_f32_16x16x32_bf16 v[116:119], v[142:145], v[202:205], v[116:119]
	v_mfma_f32_16x16x32_bf16 v[112:115], v[142:145], v[206:209], v[112:115]
	v_mfma_f32_16x16x32_bf16 v[108:111], v[146:149], v[194:197], v[108:111]
	v_mfma_f32_16x16x32_bf16 v[104:107], v[146:149], v[198:201], v[104:107]
	v_mfma_f32_16x16x32_bf16 v[100:103], v[146:149], v[202:205], v[100:103]
	v_mfma_f32_16x16x32_bf16 v[96:99], v[146:149], v[206:209], v[96:99]
	v_mfma_f32_16x16x32_bf16 v[92:95], v[150:153], v[194:197], v[92:95]
	v_mfma_f32_16x16x32_bf16 v[88:91], v[150:153], v[198:201], v[88:91]
	v_mfma_f32_16x16x32_bf16 v[84:87], v[150:153], v[202:205], v[84:87]
	v_mfma_f32_16x16x32_bf16 v[80:83], v[150:153], v[206:209], v[80:83]
	v_mfma_f32_16x16x32_bf16 v[76:79], v[154:157], v[194:197], v[76:79]
	v_mfma_f32_16x16x32_bf16 v[72:75], v[154:157], v[198:201], v[72:75]
	v_mfma_f32_16x16x32_bf16 v[68:71], v[154:157], v[202:205], v[68:71]
	v_mfma_f32_16x16x32_bf16 v[64:67], v[154:157], v[206:209], v[64:67]
	s_add_u32 s48, s48, 0x80
	s_addc_u32 s49, s49, 0
	s_add_i32 s47, s47, 1
	s_cmp_lt_u32 s47, 31
	s_cbranch_scc1 .Lg7_top
	s_waitcnt lgkmcnt(0)
	s_waitcnt vmcnt(0)
	s_barrier
	v_xor_b32_e32 v141, 0x10000, v141
	v_xor_b32_e32 v210, 0x10000, v210
	v_xor_b32_e32 v180, 0x10000, v180
	v_xor_b32_e32 v211, 0x10000, v211
	s_xor_b32 s61, s61, 0x10000
	ds_read_b128 v[142:145], v141
	ds_read_b128 v[146:149], v141 offset:2048
	ds_read_b128 v[150:153], v141 offset:4096
	ds_read_b128 v[154:157], v141 offset:6144
	ds_read_b128 v[174:177], v210 offset:32768
	ds_read_b128 v[182:185], v210 offset:34816
	ds_read_b128 v[186:189], v210 offset:36864
	ds_read_b128 v[190:193], v210 offset:38912
	v_mfma_f32_16x16x32_bf16 v[60:63], v[158:161], v[194:197], v[60:63]
	v_mfma_f32_16x16x32_bf16 v[56:59], v[158:161], v[198:201], v[56:59]
	v_mfma_f32_16x16x32_bf16 v[52:55], v[158:161], v[202:205], v[52:55]
	v_mfma_f32_16x16x32_bf16 v[48:51], v[158:161], v[206:209], v[48:51]
	v_mfma_f32_16x16x32_bf16 v[44:47], v[162:165], v[194:197], v[44:47]
	v_mfma_f32_16x16x32_bf16 v[32:35], v[162:165], v[198:201], v[32:35]
	v_mfma_f32_16x16x32_bf16 v[28:31], v[162:165], v[202:205], v[28:31]
	v_mfma_f32_16x16x32_bf16 v[24:27], v[162:165], v[206:209], v[24:27]
	v_mfma_f32_16x16x32_bf16 v[20:23], v[166:169], v[194:197], v[20:23]
	v_mfma_f32_16x16x32_bf16 v[16:19], v[166:169], v[198:201], v[16:19]
	v_mfma_f32_16x16x32_bf16 v[12:15], v[166:169], v[202:205], v[12:15]
	v_mfma_f32_16x16x32_bf16 v[8:11], v[166:169], v[206:209], v[8:11]
	v_mfma_f32_16x16x32_bf16 v[4:7], v[170:173], v[194:197], v[4:7]
	v_mfma_f32_16x16x32_bf16 v[0:3], v[170:173], v[198:201], v[0:3]
	v_mfma_f32_16x16x32_bf16 v[40:43], v[170:173], v[202:205], v[40:43]
	v_mfma_f32_16x16x32_bf16 v[36:39], v[170:173], v[206:209], v[36:39]
	ds_read_b128 v[158:161], v141 offset:8192
	ds_read_b128 v[162:165], v141 offset:10240
	ds_read_b128 v[166:169], v141 offset:12288
	ds_read_b128 v[170:173], v141 offset:14336
	s_waitcnt lgkmcnt(4)
	v_mfma_f32_16x16x32_bf16 v[124:127], v[142:145], v[174:177], v[124:127]
	v_mfma_f32_16x16x32_bf16 v[120:123], v[142:145], v[182:185], v[120:123]
	v_mfma_f32_16x16x32_bf16 v[116:119], v[142:145], v[186:189], v[116:119]
	v_mfma_f32_16x16x32_bf16 v[112:115], v[142:145], v[190:193], v[112:115]
	v_mfma_f32_16x16x32_bf16 v[108:111], v[146:149], v[174:177], v[108:111]
	v_mfma_f32_16x16x32_bf16 v[104:107], v[146:149], v[182:185], v[104:107]
	v_mfma_f32_16x16x32_bf16 v[100:103], v[146:149], v[186:189], v[100:103]
	v_mfma_f32_16x16x32_bf16 v[96:99], v[146:149], v[190:193], v[96:99]
	v_mfma_f32_16x16x32_bf16 v[92:95], v[150:153], v[174:177], v[92:95]
	v_mfma_f32_16x16x32_bf16 v[88:91], v[150:153], v[182:185], v[88:91]
	v_mfma_f32_16x16x32_bf16 v[84:87], v[150:153], v[186:189], v[84:87]
	v_mfma_f32_16x16x32_bf16 v[80:83], v[150:153], v[190:193], v[80:83]
	v_mfma_f32_16x16x32_bf16 v[76:79], v[154:157], v[174:177], v[76:79]
	v_mfma_f32_16x16x32_bf16 v[72:75], v[154:157], v[182:185], v[72:75]
	v_mfma_f32_16x16x32_bf16 v[68:71], v[154:157], v[186:189], v[68:71]
	v_mfma_f32_16x16x32_bf16 v[64:67], v[154:157], v[190:193], v[64:67]
	ds_read_b128 v[142:145], v180
	ds_read_b128 v[146:149], v180 offset:2048
	ds_read_b128 v[150:153], v180 offset:4096
	ds_read_b128 v[154:157], v180 offset:6144
	ds_read_b128 v[194:197], v211 offset:32768
	ds_read_b128 v[198:201], v211 offset:34816
	ds_read_b128 v[202:205], v211 offset:36864
	ds_read_b128 v[206:209], v211 offset:38912
	s_waitcnt lgkmcnt(8)
	v_mfma_f32_16x16x32_bf16 v[60:63], v[158:161], v[174:177], v[60:63]
	v_mfma_f32_16x16x32_bf16 v[56:59], v[158:161], v[182:185], v[56:59]
	v_mfma_f32_16x16x32_bf16 v[52:55], v[158:161], v[186:189], v[52:55]
	v_mfma_f32_16x16x32_bf16 v[48:51], v[158:161], v[190:193], v[48:51]
	v_mfma_f32_16x16x32_bf16 v[44:47], v[162:165], v[174:177], v[44:47]
	v_mfma_f32_16x16x32_bf16 v[32:35], v[162:165], v[182:185], v[32:35]
	v_mfma_f32_16x16x32_bf16 v[28:31], v[162:165], v[186:189], v[28:31]
	v_mfma_f32_16x16x32_bf16 v[24:27], v[162:165], v[190:193], v[24:27]
	v_mfma_f32_16x16x32_bf16 v[20:23], v[166:169], v[174:177], v[20:23]
	v_mfma_f32_16x16x32_bf16 v[16:19], v[166:169], v[182:185], v[16:19]
	v_mfma_f32_16x16x32_bf16 v[12:15], v[166:169], v[186:189], v[12:15]
	v_mfma_f32_16x16x32_bf16 v[8:11], v[166:169], v[190:193], v[8:11]
	v_mfma_f32_16x16x32_bf16 v[4:7], v[170:173], v[174:177], v[4:7]
	v_mfma_f32_16x16x32_bf16 v[0:3], v[170:173], v[182:185], v[0:3]
	v_mfma_f32_16x16x32_bf16 v[40:43], v[170:173], v[186:189], v[40:43]
	v_mfma_f32_16x16x32_bf16 v[36:39], v[170:173], v[190:193], v[36:39]
	ds_read_b128 v[158:161], v180 offset:8192
	ds_read_b128 v[162:165], v180 offset:10240
	ds_read_b128 v[166:169], v180 offset:12288
	ds_read_b128 v[170:173], v180 offset:14336
	s_waitcnt lgkmcnt(4)
	v_mfma_f32_16x16x32_bf16 v[124:127], v[142:145], v[194:197], v[124:127]
	v_mfma_f32_16x16x32_bf16 v[120:123], v[142:145], v[198:201], v[120:123]
	v_mfma_f32_16x16x32_bf16 v[116:119], v[142:145], v[202:205], v[116:119]
	v_mfma_f32_16x16x32_bf16 v[112:115], v[142:145], v[206:209], v[112:115]
	v_mfma_f32_16x16x32_bf16 v[108:111], v[146:149], v[194:197], v[108:111]
	v_mfma_f32_16x16x32_bf16 v[104:107], v[146:149], v[198:201], v[104:107]
	v_mfma_f32_16x16x32_bf16 v[100:103], v[146:149], v[202:205], v[100:103]
	v_mfma_f32_16x16x32_bf16 v[96:99], v[146:149], v[206:209], v[96:99]
	v_mfma_f32_16x16x32_bf16 v[92:95], v[150:153], v[194:197], v[92:95]
	v_mfma_f32_16x16x32_bf16 v[88:91], v[150:153], v[198:201], v[88:91]
	v_mfma_f32_16x16x32_bf16 v[84:87], v[150:153], v[202:205], v[84:87]
	v_mfma_f32_16x16x32_bf16 v[80:83], v[150:153], v[206:209], v[80:83]
	v_mfma_f32_16x16x32_bf16 v[76:79], v[154:157], v[194:197], v[76:79]
	v_mfma_f32_16x16x32_bf16 v[72:75], v[154:157], v[198:201], v[72:75]
	v_mfma_f32_16x16x32_bf16 v[68:71], v[154:157], v[202:205], v[68:71]
	v_mfma_f32_16x16x32_bf16 v[64:67], v[154:157], v[206:209], v[64:67]
	s_add_u32 s48, s48, 0x80
	s_addc_u32 s49, s49, 0
	s_add_i32 s47, s47, 1
	s_waitcnt lgkmcnt(0)
	s_waitcnt vmcnt(0)
	s_barrier
	v_mfma_f32_16x16x32_bf16 v[60:63], v[158:161], v[194:197], v[60:63]
	v_mfma_f32_16x16x32_bf16 v[56:59], v[158:161], v[198:201], v[56:59]
	v_mfma_f32_16x16x32_bf16 v[52:55], v[158:161], v[202:205], v[52:55]
	v_mfma_f32_16x16x32_bf16 v[48:51], v[158:161], v[206:209], v[48:51]
	v_mfma_f32_16x16x32_bf16 v[44:47], v[162:165], v[194:197], v[44:47]
	v_mfma_f32_16x16x32_bf16 v[32:35], v[162:165], v[198:201], v[32:35]
	v_mfma_f32_16x16x32_bf16 v[28:31], v[162:165], v[202:205], v[28:31]
	v_mfma_f32_16x16x32_bf16 v[24:27], v[162:165], v[206:209], v[24:27]
	v_mfma_f32_16x16x32_bf16 v[20:23], v[166:169], v[194:197], v[20:23]
	v_mfma_f32_16x16x32_bf16 v[16:19], v[166:169], v[198:201], v[16:19]
	v_mfma_f32_16x16x32_bf16 v[12:15], v[166:169], v[202:205], v[12:15]
	v_mfma_f32_16x16x32_bf16 v[8:11], v[166:169], v[206:209], v[8:11]
	v_mfma_f32_16x16x32_bf16 v[4:7], v[170:173], v[194:197], v[4:7]
	v_mfma_f32_16x16x32_bf16 v[0:3], v[170:173], v[198:201], v[0:3]
	v_mfma_f32_16x16x32_bf16 v[40:43], v[170:173], v[202:205], v[40:43]
	v_mfma_f32_16x16x32_bf16 v[36:39], v[170:173], v[206:209], v[36:39]
	s_nop 7
	s_nop 7
	s_sub_u32 s48, s48, s34
	s_subb_u32 s49, s49, s35
	s_mov_b32 s61, 0x100000
	s_mov_b32 s62, 0x100000
	s_mov_b64 s[50:51], 0
	s_mov_b64 vcc, exec
	s_branch .LBB0_745

.Lg8_top:
	s_waitcnt lgkmcnt(0)
	s_waitcnt vmcnt(0)
	s_barrier
	v_xor_b32_e32 v180, 0x10000, v180
	v_xor_b32_e32 v223, 0x10000, v223
	v_xor_b32_e32 v222, 0x10000, v222
	v_xor_b32_e32 v224, 0x10000, v224
	s_xor_b32 s59, s59, 0x10000
	ds_read_b128 v[154:157], v180
	ds_read_b128 v[158:161], v180 offset:2048
	ds_read_b128 v[162:165], v180 offset:4096
	ds_read_b128 v[166:169], v180 offset:6144
	ds_read_b128 v[190:193], v223 offset:32768
	ds_read_b128 v[194:197], v223 offset:34816
	ds_read_b128 v[198:201], v223 offset:36864
	ds_read_b128 v[202:205], v223 offset:38912
	v_mfma_f32_16x16x32_bf16 v[60:63], v[170:173], v[206:209], v[60:63]
	v_mfma_f32_16x16x32_bf16 v[56:59], v[170:173], v[210:213], v[56:59]
	v_mfma_f32_16x16x32_bf16 v[52:55], v[170:173], v[214:217], v[52:55]
	v_mfma_f32_16x16x32_bf16 v[44:47], v[170:173], v[218:221], v[44:47]
	s_mov_b32 m0, s59
	s_add_u32 s62, s60, s22
	s_addc_u32 s63, s61, s23
	global_load_lds_dwordx4 v178, s[62:63]
	v_mfma_f32_16x16x32_bf16 v[36:39], v[174:177], v[206:209], v[36:39]
	v_mfma_f32_16x16x32_bf16 v[32:35], v[174:177], v[210:213], v[32:35]
	v_mfma_f32_16x16x32_bf16 v[28:31], v[174:177], v[214:217], v[28:31]
	v_mfma_f32_16x16x32_bf16 v[24:27], v[174:177], v[218:221], v[24:27]
	s_add_u32 m0, s59, 0x2000
	s_add_u32 s62, s60, s36
	s_addc_u32 s63, s61, s37
	global_load_lds_dwordx4 v178, s[62:63]
	v_mfma_f32_16x16x32_bf16 v[20:23], v[182:185], v[206:209], v[20:23]
	v_mfma_f32_16x16x32_bf16 v[16:19], v[182:185], v[210:213], v[16:19]
	v_mfma_f32_16x16x32_bf16 v[12:15], v[182:185], v[214:217], v[12:15]
	v_mfma_f32_16x16x32_bf16 v[8:11], v[182:185], v[218:221], v[8:11]
	s_add_u32 m0, s59, 0x4000
	s_add_u32 s62, s60, s38
	s_addc_u32 s63, s61, s39
	global_load_lds_dwordx4 v178, s[62:63]
	v_mfma_f32_16x16x32_bf16 v[4:7], v[186:189], v[206:209], v[4:7]
	v_mfma_f32_16x16x32_bf16 v[0:3], v[186:189], v[210:213], v[0:3]
	v_mfma_f32_16x16x32_bf16 v[48:51], v[186:189], v[214:217], v[48:51]
	v_mfma_f32_16x16x32_bf16 v[40:43], v[186:189], v[218:221], v[40:43]
	s_add_u32 m0, s59, 0x6000
	s_add_u32 s62, s60, s40
	s_addc_u32 s63, s61, s41
	global_load_lds_dwordx4 v178, s[62:63]
.Lg8_entry:
	ds_read_b128 v[170:173], v180 offset:8192
	ds_read_b128 v[174:177], v180 offset:10240
	ds_read_b128 v[182:185], v180 offset:12288
	ds_read_b128 v[186:189], v180 offset:14336
	s_waitcnt lgkmcnt(4)
	v_mfma_f32_16x16x32_bf16 v[124:127], v[154:157], v[190:193], v[124:127]
	v_mfma_f32_16x16x32_bf16 v[120:123], v[154:157], v[194:197], v[120:123]
	v_mfma_f32_16x16x32_bf16 v[116:119], v[154:157], v[198:201], v[116:119]
	v_mfma_f32_16x16x32_bf16 v[112:115], v[154:157], v[202:205], v[112:115]
	s_add_u32 m0, s59, 0x8000
	s_add_u32 s62, s60, s42
	s_addc_u32 s63, s61, s43
	global_load_lds_dwordx4 v179, s[62:63]
	v_mfma_f32_16x16x32_bf16 v[108:111], v[158:161], v[190:193], v[108:111]
	v_mfma_f32_16x16x32_bf16 v[104:107], v[158:161], v[194:197], v[104:107]
	v_mfma_f32_16x16x32_bf16 v[100:103], v[158:161], v[198:201], v[100:103]
	v_mfma_f32_16x16x32_bf16 v[96:99], v[158:161], v[202:205], v[96:99]
	s_add_u32 m0, s59, 0xa000
	s_add_u32 s62, s60, s44
	s_addc_u32 s63, s61, s45
	global_load_lds_dwordx4 v179, s[62:63]
	v_mfma_f32_16x16x32_bf16 v[92:95], v[162:165], v[190:193], v[92:95]
	v_mfma_f32_16x16x32_bf16 v[88:91], v[162:165], v[194:197], v[88:91]
	v_mfma_f32_16x16x32_bf16 v[84:87], v[162:165], v[198:201], v[84:87]
	v_mfma_f32_16x16x32_bf16 v[80:83], v[162:165], v[202:205], v[80:83]
	s_add_u32 m0, s59, 0xc000
	s_add_u32 s62, s60, s46
	s_addc_u32 s63, s61, s47
	global_load_lds_dwordx4 v179, s[62:63]
	v_mfma_f32_16x16x32_bf16 v[76:79], v[166:169], v[190:193], v[76:79]
	v_mfma_f32_16x16x32_bf16 v[72:75], v[166:169], v[194:197], v[72:75]
	v_mfma_f32_16x16x32_bf16 v[68:71], v[166:169], v[198:201], v[68:71]
	v_mfma_f32_16x16x32_bf16 v[64:67], v[166:169], v[202:205], v[64:67]
	s_add_u32 m0, s59, 0xe000
	s_add_u32 s62, s60, s48
	s_addc_u32 s63, s61, s49
	global_load_lds_dwordx4 v179, s[62:63]
	ds_read_b128 v[154:157], v222
	ds_read_b128 v[158:161], v222 offset:2048
	ds_read_b128 v[162:165], v222 offset:4096
	ds_read_b128 v[166:169], v222 offset:6144
	ds_read_b128 v[206:209], v224 offset:32768
	ds_read_b128 v[210:213], v224 offset:34816
	ds_read_b128 v[214:217], v224 offset:36864
	ds_read_b128 v[218:221], v224 offset:38912
	s_waitcnt lgkmcnt(8)
	v_mfma_f32_16x16x32_bf16 v[60:63], v[170:173], v[190:193], v[60:63]
	v_mfma_f32_16x16x32_bf16 v[56:59], v[170:173], v[194:197], v[56:59]
	v_mfma_f32_16x16x32_bf16 v[52:55], v[170:173], v[198:201], v[52:55]
	v_mfma_f32_16x16x32_bf16 v[44:47], v[170:173], v[202:205], v[44:47]
	v_mfma_f32_16x16x32_bf16 v[36:39], v[174:177], v[190:193], v[36:39]
	v_mfma_f32_16x16x32_bf16 v[32:35], v[174:177], v[194:197], v[32:35]
	v_mfma_f32_16x16x32_bf16 v[28:31], v[174:177], v[198:201], v[28:31]
	v_mfma_f32_16x16x32_bf16 v[24:27], v[174:177], v[202:205], v[24:27]
	v_mfma_f32_16x16x32_bf16 v[20:23], v[182:185], v[190:193], v[20:23]
	v_mfma_f32_16x16x32_bf16 v[16:19], v[182:185], v[194:197], v[16:19]
	v_mfma_f32_16x16x32_bf16 v[12:15], v[182:185], v[198:201], v[12:15]
	v_mfma_f32_16x16x32_bf16 v[8:11], v[182:185], v[202:205], v[8:11]
	v_mfma_f32_16x16x32_bf16 v[4:7], v[186:189], v[190:193], v[4:7]
	v_mfma_f32_16x16x32_bf16 v[0:3], v[186:189], v[194:197], v[0:3]
	v_mfma_f32_16x16x32_bf16 v[48:51], v[186:189], v[198:201], v[48:51]
	v_mfma_f32_16x16x32_bf16 v[40:43], v[186:189], v[202:205], v[40:43]
	ds_read_b128 v[170:173], v222 offset:8192
	ds_read_b128 v[174:177], v222 offset:10240
	ds_read_b128 v[182:185], v222 offset:12288
	ds_read_b128 v[186:189], v222 offset:14336
	s_waitcnt lgkmcnt(4)
	v_mfma_f32_16x16x32_bf16 v[124:127], v[154:157], v[206:209], v[124:127]
	v_mfma_f32_16x16x32_bf16 v[120:123], v[154:157], v[210:213], v[120:123]
	v_mfma_f32_16x16x32_bf16 v[116:119], v[154:157], v[214:217], v[116:119]
	v_mfma_f32_16x16x32_bf16 v[112:115], v[154:157], v[218:221], v[112:115]
	v_mfma_f32_16x16x32_bf16 v[108:111], v[158:161], v[206:209], v[108:111]
	v_mfma_f32_16x16x32_bf16 v[104:107], v[158:161], v[210:213], v[104:107]
	v_mfma_f32_16x16x32_bf16 v[100:103], v[158:161], v[214:217], v[100:103]
	v_mfma_f32_16x16x32_bf16 v[96:99], v[158:161], v[218:221], v[96:99]
	v_mfma_f32_16x16x32_bf16 v[92:95], v[162:165], v[206:209], v[92:95]
	v_mfma_f32_16x16x32_bf16 v[88:91], v[162:165], v[210:213], v[88:91]
	v_mfma_f32_16x16x32_bf16 v[84:87], v[162:165], v[214:217], v[84:87]
	v_mfma_f32_16x16x32_bf16 v[80:83], v[162:165], v[218:221], v[80:83]
	v_mfma_f32_16x16x32_bf16 v[76:79], v[166:169], v[206:209], v[76:79]
	v_mfma_f32_16x16x32_bf16 v[72:75], v[166:169], v[210:213], v[72:75]
	v_mfma_f32_16x16x32_bf16 v[68:71], v[166:169], v[214:217], v[68:71]
	v_mfma_f32_16x16x32_bf16 v[64:67], v[166:169], v[218:221], v[64:67]
	s_add_u32 s60, s60, 0x80
	s_addc_u32 s61, s61, 0
	s_add_i32 s57, s57, 1
	s_cmp_lt_u32 s57, 15
	s_cbranch_scc1 .Lg8_top
	s_waitcnt lgkmcnt(0)
	s_waitcnt vmcnt(0)
	s_barrier
	v_xor_b32_e32 v180, 0x10000, v180
	v_xor_b32_e32 v223, 0x10000, v223
	v_xor_b32_e32 v222, 0x10000, v222
	v_xor_b32_e32 v224, 0x10000, v224
	s_xor_b32 s59, s59, 0x10000
	ds_read_b128 v[154:157], v180
	ds_read_b128 v[158:161], v180 offset:2048
	ds_read_b128 v[162:165], v180 offset:4096
	ds_read_b128 v[166:169], v180 offset:6144
	ds_read_b128 v[190:193], v223 offset:32768
	ds_read_b128 v[194:197], v223 offset:34816
	ds_read_b128 v[198:201], v223 offset:36864
	ds_read_b128 v[202:205], v223 offset:38912
	v_mfma_f32_16x16x32_bf16 v[60:63], v[170:173], v[206:209], v[60:63]
	v_mfma_f32_16x16x32_bf16 v[56:59], v[170:173], v[210:213], v[56:59]
	v_mfma_f32_16x16x32_bf16 v[52:55], v[170:173], v[214:217], v[52:55]
	v_mfma_f32_16x16x32_bf16 v[44:47], v[170:173], v[218:221], v[44:47]
	v_mfma_f32_16x16x32_bf16 v[36:39], v[174:177], v[206:209], v[36:39]
	v_mfma_f32_16x16x32_bf16 v[32:35], v[174:177], v[210:213], v[32:35]
	v_mfma_f32_16x16x32_bf16 v[28:31], v[174:177], v[214:217], v[28:31]
	v_mfma_f32_16x16x32_bf16 v[24:27], v[174:177], v[218:221], v[24:27]
	v_mfma_f32_16x16x32_bf16 v[20:23], v[182:185], v[206:209], v[20:23]
	v_mfma_f32_16x16x32_bf16 v[16:19], v[182:185], v[210:213], v[16:19]
	v_mfma_f32_16x16x32_bf16 v[12:15], v[182:185], v[214:217], v[12:15]
	v_mfma_f32_16x16x32_bf16 v[8:11], v[182:185], v[218:221], v[8:11]
	v_mfma_f32_16x16x32_bf16 v[4:7], v[186:189], v[206:209], v[4:7]
	v_mfma_f32_16x16x32_bf16 v[0:3], v[186:189], v[210:213], v[0:3]
	v_mfma_f32_16x16x32_bf16 v[48:51], v[186:189], v[214:217], v[48:51]
	v_mfma_f32_16x16x32_bf16 v[40:43], v[186:189], v[218:221], v[40:43]
	ds_read_b128 v[170:173], v180 offset:8192
	ds_read_b128 v[174:177], v180 offset:10240
	ds_read_b128 v[182:185], v180 offset:12288
	ds_read_b128 v[186:189], v180 offset:14336
	s_waitcnt lgkmcnt(4)
	v_mfma_f32_16x16x32_bf16 v[124:127], v[154:157], v[190:193], v[124:127]
	v_mfma_f32_16x16x32_bf16 v[120:123], v[154:157], v[194:197], v[120:123]
	v_mfma_f32_16x16x32_bf16 v[116:119], v[154:157], v[198:201], v[116:119]
	v_mfma_f32_16x16x32_bf16 v[112:115], v[154:157], v[202:205], v[112:115]
	v_mfma_f32_16x16x32_bf16 v[108:111], v[158:161], v[190:193], v[108:111]
	v_mfma_f32_16x16x32_bf16 v[104:107], v[158:161], v[194:197], v[104:107]
	v_mfma_f32_16x16x32_bf16 v[100:103], v[158:161], v[198:201], v[100:103]
	v_mfma_f32_16x16x32_bf16 v[96:99], v[158:161], v[202:205], v[96:99]
	v_mfma_f32_16x16x32_bf16 v[92:95], v[162:165], v[190:193], v[92:95]
	v_mfma_f32_16x16x32_bf16 v[88:91], v[162:165], v[194:197], v[88:91]
	v_mfma_f32_16x16x32_bf16 v[84:87], v[162:165], v[198:201], v[84:87]
	v_mfma_f32_16x16x32_bf16 v[80:83], v[162:165], v[202:205], v[80:83]
	v_mfma_f32_16x16x32_bf16 v[76:79], v[166:169], v[190:193], v[76:79]
	v_mfma_f32_16x16x32_bf16 v[72:75], v[166:169], v[194:197], v[72:75]
	v_mfma_f32_16x16x32_bf16 v[68:71], v[166:169], v[198:201], v[68:71]
	v_mfma_f32_16x16x32_bf16 v[64:67], v[166:169], v[202:205], v[64:67]
	ds_read_b128 v[154:157], v222
	ds_read_b128 v[158:161], v222 offset:2048
	ds_read_b128 v[162:165], v222 offset:4096
	ds_read_b128 v[166:169], v222 offset:6144
	ds_read_b128 v[206:209], v224 offset:32768
	ds_read_b128 v[210:213], v224 offset:34816
	ds_read_b128 v[214:217], v224 offset:36864
	ds_read_b128 v[218:221], v224 offset:38912
	s_waitcnt lgkmcnt(8)
	v_mfma_f32_16x16x32_bf16 v[60:63], v[170:173], v[190:193], v[60:63]
	v_mfma_f32_16x16x32_bf16 v[56:59], v[170:173], v[194:197], v[56:59]
	v_mfma_f32_16x16x32_bf16 v[52:55], v[170:173], v[198:201], v[52:55]
	v_mfma_f32_16x16x32_bf16 v[44:47], v[170:173], v[202:205], v[44:47]
	v_mfma_f32_16x16x32_bf16 v[36:39], v[174:177], v[190:193], v[36:39]
	v_mfma_f32_16x16x32_bf16 v[32:35], v[174:177], v[194:197], v[32:35]
	v_mfma_f32_16x16x32_bf16 v[28:31], v[174:177], v[198:201], v[28:31]
	v_mfma_f32_16x16x32_bf16 v[24:27], v[174:177], v[202:205], v[24:27]
	v_mfma_f32_16x16x32_bf16 v[20:23], v[182:185], v[190:193], v[20:23]
	v_mfma_f32_16x16x32_bf16 v[16:19], v[182:185], v[194:197], v[16:19]
	v_mfma_f32_16x16x32_bf16 v[12:15], v[182:185], v[198:201], v[12:15]
	v_mfma_f32_16x16x32_bf16 v[8:11], v[182:185], v[202:205], v[8:11]
	v_mfma_f32_16x16x32_bf16 v[4:7], v[186:189], v[190:193], v[4:7]
	v_mfma_f32_16x16x32_bf16 v[0:3], v[186:189], v[194:197], v[0:3]
	v_mfma_f32_16x16x32_bf16 v[48:51], v[186:189], v[198:201], v[48:51]
	v_mfma_f32_16x16x32_bf16 v[40:43], v[186:189], v[202:205], v[40:43]
	ds_read_b128 v[170:173], v222 offset:8192
	ds_read_b128 v[174:177], v222 offset:10240
	ds_read_b128 v[182:185], v222 offset:12288
	ds_read_b128 v[186:189], v222 offset:14336
	s_waitcnt lgkmcnt(4)
	v_mfma_f32_16x16x32_bf16 v[124:127], v[154:157], v[206:209], v[124:127]
	v_mfma_f32_16x16x32_bf16 v[120:123], v[154:157], v[210:213], v[120:123]
	v_mfma_f32_16x16x32_bf16 v[116:119], v[154:157], v[214:217], v[116:119]
	v_mfma_f32_16x16x32_bf16 v[112:115], v[154:157], v[218:221], v[112:115]
	v_mfma_f32_16x16x32_bf16 v[108:111], v[158:161], v[206:209], v[108:111]
	v_mfma_f32_16x16x32_bf16 v[104:107], v[158:161], v[210:213], v[104:107]
	v_mfma_f32_16x16x32_bf16 v[100:103], v[158:161], v[214:217], v[100:103]
	v_mfma_f32_16x16x32_bf16 v[96:99], v[158:161], v[218:221], v[96:99]
	v_mfma_f32_16x16x32_bf16 v[92:95], v[162:165], v[206:209], v[92:95]
	v_mfma_f32_16x16x32_bf16 v[88:91], v[162:165], v[210:213], v[88:91]
	v_mfma_f32_16x16x32_bf16 v[84:87], v[162:165], v[214:217], v[84:87]
	v_mfma_f32_16x16x32_bf16 v[80:83], v[162:165], v[218:221], v[80:83]
	v_mfma_f32_16x16x32_bf16 v[76:79], v[166:169], v[206:209], v[76:79]
	v_mfma_f32_16x16x32_bf16 v[72:75], v[166:169], v[210:213], v[72:75]
	v_mfma_f32_16x16x32_bf16 v[68:71], v[166:169], v[214:217], v[68:71]
	v_mfma_f32_16x16x32_bf16 v[64:67], v[166:169], v[218:221], v[64:67]
	s_add_u32 s60, s60, 0x80
	s_addc_u32 s61, s61, 0
	s_add_i32 s57, s57, 1
	s_waitcnt lgkmcnt(0)
	s_waitcnt vmcnt(0)
	s_barrier
	v_mfma_f32_16x16x32_bf16 v[60:63], v[170:173], v[206:209], v[60:63]
	v_mfma_f32_16x16x32_bf16 v[56:59], v[170:173], v[210:213], v[56:59]
	v_mfma_f32_16x16x32_bf16 v[52:55], v[170:173], v[214:217], v[52:55]
	v_mfma_f32_16x16x32_bf16 v[44:47], v[170:173], v[218:221], v[44:47]
	v_mfma_f32_16x16x32_bf16 v[36:39], v[174:177], v[206:209], v[36:39]
	v_mfma_f32_16x16x32_bf16 v[32:35], v[174:177], v[210:213], v[32:35]
	v_mfma_f32_16x16x32_bf16 v[28:31], v[174:177], v[214:217], v[28:31]
	v_mfma_f32_16x16x32_bf16 v[24:27], v[174:177], v[218:221], v[24:27]
	v_mfma_f32_16x16x32_bf16 v[20:23], v[182:185], v[206:209], v[20:23]
	v_mfma_f32_16x16x32_bf16 v[16:19], v[182:185], v[210:213], v[16:19]
	v_mfma_f32_16x16x32_bf16 v[12:15], v[182:185], v[214:217], v[12:15]
	v_mfma_f32_16x16x32_bf16 v[8:11], v[182:185], v[218:221], v[8:11]
	v_mfma_f32_16x16x32_bf16 v[4:7], v[186:189], v[206:209], v[4:7]
	v_mfma_f32_16x16x32_bf16 v[0:3], v[186:189], v[210:213], v[0:3]
	v_mfma_f32_16x16x32_bf16 v[48:51], v[186:189], v[214:217], v[48:51]
	v_mfma_f32_16x16x32_bf16 v[40:43], v[186:189], v[218:221], v[40:43]
	s_nop 7
	s_nop 7
	s_sub_u32 s60, s60, s34
	s_subb_u32 s61, s61, s35
	s_mov_b32 s59, 0x80000
	s_mov_b32 s65, 0x80000
	s_mov_b64 s[62:63], 0
	s_mov_b64 vcc, exec
	s_branch .LBB0_939

.Lg9_top:
	s_waitcnt lgkmcnt(0)
	s_waitcnt vmcnt(0)
	s_barrier
	v_xor_b32_e32 v141, 0x10000, v141
	v_xor_b32_e32 v210, 0x10000, v210
	v_xor_b32_e32 v180, 0x10000, v180
	v_xor_b32_e32 v211, 0x10000, v211
	s_xor_b32 s59, s59, 0x10000
	ds_read_b128 v[142:145], v141
	ds_read_b128 v[146:149], v141 offset:2048
	ds_read_b128 v[150:153], v141 offset:4096
	ds_read_b128 v[154:157], v141 offset:6144
	ds_read_b128 v[174:177], v210 offset:32768
	ds_read_b128 v[182:185], v210 offset:34816
	ds_read_b128 v[186:189], v210 offset:36864
	ds_read_b128 v[190:193], v210 offset:38912
	v_mfma_f32_16x16x32_bf16 v[60:63], v[158:161], v[194:197], v[60:63]
	v_mfma_f32_16x16x32_bf16 v[56:59], v[158:161], v[198:201], v[56:59]
	v_mfma_f32_16x16x32_bf16 v[52:55], v[158:161], v[202:205], v[52:55]
	v_mfma_f32_16x16x32_bf16 v[48:51], v[158:161], v[206:209], v[48:51]
	s_mov_b32 m0, s59
	s_add_u32 s46, s44, s12
	s_addc_u32 s47, s45, s13
	global_load_lds_dwordx4 v178, s[46:47]
	v_mfma_f32_16x16x32_bf16 v[44:47], v[162:165], v[194:197], v[44:47]
	v_mfma_f32_16x16x32_bf16 v[32:35], v[162:165], v[198:201], v[32:35]
	v_mfma_f32_16x16x32_bf16 v[28:31], v[162:165], v[202:205], v[28:31]
	v_mfma_f32_16x16x32_bf16 v[24:27], v[162:165], v[206:209], v[24:27]
	s_add_u32 m0, s59, 0x2000
	s_add_u32 s46, s44, s14
	s_addc_u32 s47, s45, s15
	global_load_lds_dwordx4 v178, s[46:47]
	v_mfma_f32_16x16x32_bf16 v[20:23], v[166:169], v[194:197], v[20:23]
	v_mfma_f32_16x16x32_bf16 v[16:19], v[166:169], v[198:201], v[16:19]
	v_mfma_f32_16x16x32_bf16 v[12:15], v[166:169], v[202:205], v[12:15]
	v_mfma_f32_16x16x32_bf16 v[8:11], v[166:169], v[206:209], v[8:11]
	s_add_u32 m0, s59, 0x4000
	s_add_u32 s46, s44, s16
	s_addc_u32 s47, s45, s17
	global_load_lds_dwordx4 v178, s[46:47]
	v_mfma_f32_16x16x32_bf16 v[4:7], v[170:173], v[194:197], v[4:7]
	v_mfma_f32_16x16x32_bf16 v[0:3], v[170:173], v[198:201], v[0:3]
	v_mfma_f32_16x16x32_bf16 v[40:43], v[170:173], v[202:205], v[40:43]
	v_mfma_f32_16x16x32_bf16 v[36:39], v[170:173], v[206:209], v[36:39]
	s_add_u32 m0, s59, 0x6000
	s_add_u32 s46, s44, s18
	s_addc_u32 s47, s45, s19
	global_load_lds_dwordx4 v178, s[46:47]
.Lg9_entry:
	ds_read_b128 v[158:161], v141 offset:8192
	ds_read_b128 v[162:165], v141 offset:10240
	ds_read_b128 v[166:169], v141 offset:12288
	ds_read_b128 v[170:173], v141 offset:14336
	s_waitcnt lgkmcnt(4)
	v_mfma_f32_16x16x32_bf16 v[124:127], v[142:145], v[174:177], v[124:127]
	v_mfma_f32_16x16x32_bf16 v[120:123], v[142:145], v[182:185], v[120:123]
	v_mfma_f32_16x16x32_bf16 v[116:119], v[142:145], v[186:189], v[116:119]
	v_mfma_f32_16x16x32_bf16 v[112:115], v[142:145], v[190:193], v[112:115]
	s_add_u32 m0, s59, 0x8000
	s_add_u32 s46, s44, s22
	s_addc_u32 s47, s45, s23
	global_load_lds_dwordx4 v179, s[46:47]
	v_mfma_f32_16x16x32_bf16 v[108:111], v[146:149], v[174:177], v[108:111]
	v_mfma_f32_16x16x32_bf16 v[104:107], v[146:149], v[182:185], v[104:107]
	v_mfma_f32_16x16x32_bf16 v[100:103], v[146:149], v[186:189], v[100:103]
	v_mfma_f32_16x16x32_bf16 v[96:99], v[146:149], v[190:193], v[96:99]
	s_add_u32 m0, s59, 0xa000
	s_add_u32 s46, s44, s36
	s_addc_u32 s47, s45, s37
	global_load_lds_dwordx4 v179, s[46:47]
	v_mfma_f32_16x16x32_bf16 v[92:95], v[150:153], v[174:177], v[92:95]
	v_mfma_f32_16x16x32_bf16 v[88:91], v[150:153], v[182:185], v[88:91]
	v_mfma_f32_16x16x32_bf16 v[84:87], v[150:153], v[186:189], v[84:87]
	v_mfma_f32_16x16x32_bf16 v[80:83], v[150:153], v[190:193], v[80:83]
	s_add_u32 m0, s59, 0xc000
	s_add_u32 s46, s44, s38
	s_addc_u32 s47, s45, s39
	global_load_lds_dwordx4 v179, s[46:47]
	v_mfma_f32_16x16x32_bf16 v[76:79], v[154:157], v[174:177], v[76:79]
	v_mfma_f32_16x16x32_bf16 v[72:75], v[154:157], v[182:185], v[72:75]
	v_mfma_f32_16x16x32_bf16 v[68:71], v[154:157], v[186:189], v[68:71]
	v_mfma_f32_16x16x32_bf16 v[64:67], v[154:157], v[190:193], v[64:67]
	s_add_u32 m0, s59, 0xe000
	s_add_u32 s46, s44, s40
	s_addc_u32 s47, s45, s41
	global_load_lds_dwordx4 v179, s[46:47]
	ds_read_b128 v[142:145], v180
	ds_read_b128 v[146:149], v180 offset:2048
	ds_read_b128 v[150:153], v180 offset:4096
	ds_read_b128 v[154:157], v180 offset:6144
	ds_read_b128 v[194:197], v211 offset:32768
	ds_read_b128 v[198:201], v211 offset:34816
	ds_read_b128 v[202:205], v211 offset:36864
	ds_read_b128 v[206:209], v211 offset:38912
	s_waitcnt lgkmcnt(8)
	v_mfma_f32_16x16x32_bf16 v[60:63], v[158:161], v[174:177], v[60:63]
	v_mfma_f32_16x16x32_bf16 v[56:59], v[158:161], v[182:185], v[56:59]
	v_mfma_f32_16x16x32_bf16 v[52:55], v[158:161], v[186:189], v[52:55]
	v_mfma_f32_16x16x32_bf16 v[48:51], v[158:161], v[190:193], v[48:51]
	v_mfma_f32_16x16x32_bf16 v[44:47], v[162:165], v[174:177], v[44:47]
	v_mfma_f32_16x16x32_bf16 v[32:35], v[162:165], v[182:185], v[32:35]
	v_mfma_f32_16x16x32_bf16 v[28:31], v[162:165], v[186:189], v[28:31]
	v_mfma_f32_16x16x32_bf16 v[24:27], v[162:165], v[190:193], v[24:27]
	v_mfma_f32_16x16x32_bf16 v[20:23], v[166:169], v[174:177], v[20:23]
	v_mfma_f32_16x16x32_bf16 v[16:19], v[166:169], v[182:185], v[16:19]
	v_mfma_f32_16x16x32_bf16 v[12:15], v[166:169], v[186:189], v[12:15]
	v_mfma_f32_16x16x32_bf16 v[8:11], v[166:169], v[190:193], v[8:11]
	v_mfma_f32_16x16x32_bf16 v[4:7], v[170:173], v[174:177], v[4:7]
	v_mfma_f32_16x16x32_bf16 v[0:3], v[170:173], v[182:185], v[0:3]
	v_mfma_f32_16x16x32_bf16 v[40:43], v[170:173], v[186:189], v[40:43]
	v_mfma_f32_16x16x32_bf16 v[36:39], v[170:173], v[190:193], v[36:39]
	ds_read_b128 v[158:161], v180 offset:8192
	ds_read_b128 v[162:165], v180 offset:10240
	ds_read_b128 v[166:169], v180 offset:12288
	ds_read_b128 v[170:173], v180 offset:14336
	s_waitcnt lgkmcnt(4)
	v_mfma_f32_16x16x32_bf16 v[124:127], v[142:145], v[194:197], v[124:127]
	v_mfma_f32_16x16x32_bf16 v[120:123], v[142:145], v[198:201], v[120:123]
	v_mfma_f32_16x16x32_bf16 v[116:119], v[142:145], v[202:205], v[116:119]
	v_mfma_f32_16x16x32_bf16 v[112:115], v[142:145], v[206:209], v[112:115]
	v_mfma_f32_16x16x32_bf16 v[108:111], v[146:149], v[194:197], v[108:111]
	v_mfma_f32_16x16x32_bf16 v[104:107], v[146:149], v[198:201], v[104:107]
	v_mfma_f32_16x16x32_bf16 v[100:103], v[146:149], v[202:205], v[100:103]
	v_mfma_f32_16x16x32_bf16 v[96:99], v[146:149], v[206:209], v[96:99]
	v_mfma_f32_16x16x32_bf16 v[92:95], v[150:153], v[194:197], v[92:95]
	v_mfma_f32_16x16x32_bf16 v[88:91], v[150:153], v[198:201], v[88:91]
	v_mfma_f32_16x16x32_bf16 v[84:87], v[150:153], v[202:205], v[84:87]
	v_mfma_f32_16x16x32_bf16 v[80:83], v[150:153], v[206:209], v[80:83]
	v_mfma_f32_16x16x32_bf16 v[76:79], v[154:157], v[194:197], v[76:79]
	v_mfma_f32_16x16x32_bf16 v[72:75], v[154:157], v[198:201], v[72:75]
	v_mfma_f32_16x16x32_bf16 v[68:71], v[154:157], v[202:205], v[68:71]
	v_mfma_f32_16x16x32_bf16 v[64:67], v[154:157], v[206:209], v[64:67]
	s_add_u32 s44, s44, 0x80
	s_addc_u32 s45, s45, 0
	s_add_i32 s43, s43, 1
	s_cmp_lt_u32 s43, 31
	s_cbranch_scc1 .Lg9_top
	s_waitcnt lgkmcnt(0)
	s_waitcnt vmcnt(0)
	s_barrier
	v_xor_b32_e32 v141, 0x10000, v141
	v_xor_b32_e32 v210, 0x10000, v210
	v_xor_b32_e32 v180, 0x10000, v180
	v_xor_b32_e32 v211, 0x10000, v211
	s_xor_b32 s59, s59, 0x10000
	ds_read_b128 v[142:145], v141
	ds_read_b128 v[146:149], v141 offset:2048
	ds_read_b128 v[150:153], v141 offset:4096
	ds_read_b128 v[154:157], v141 offset:6144
	ds_read_b128 v[174:177], v210 offset:32768
	ds_read_b128 v[182:185], v210 offset:34816
	ds_read_b128 v[186:189], v210 offset:36864
	ds_read_b128 v[190:193], v210 offset:38912
	v_mfma_f32_16x16x32_bf16 v[60:63], v[158:161], v[194:197], v[60:63]
	v_mfma_f32_16x16x32_bf16 v[56:59], v[158:161], v[198:201], v[56:59]
	v_mfma_f32_16x16x32_bf16 v[52:55], v[158:161], v[202:205], v[52:55]
	v_mfma_f32_16x16x32_bf16 v[48:51], v[158:161], v[206:209], v[48:51]
	v_mfma_f32_16x16x32_bf16 v[44:47], v[162:165], v[194:197], v[44:47]
	v_mfma_f32_16x16x32_bf16 v[32:35], v[162:165], v[198:201], v[32:35]
	v_mfma_f32_16x16x32_bf16 v[28:31], v[162:165], v[202:205], v[28:31]
	v_mfma_f32_16x16x32_bf16 v[24:27], v[162:165], v[206:209], v[24:27]
	v_mfma_f32_16x16x32_bf16 v[20:23], v[166:169], v[194:197], v[20:23]
	v_mfma_f32_16x16x32_bf16 v[16:19], v[166:169], v[198:201], v[16:19]
	v_mfma_f32_16x16x32_bf16 v[12:15], v[166:169], v[202:205], v[12:15]
	v_mfma_f32_16x16x32_bf16 v[8:11], v[166:169], v[206:209], v[8:11]
	v_mfma_f32_16x16x32_bf16 v[4:7], v[170:173], v[194:197], v[4:7]
	v_mfma_f32_16x16x32_bf16 v[0:3], v[170:173], v[198:201], v[0:3]
	v_mfma_f32_16x16x32_bf16 v[40:43], v[170:173], v[202:205], v[40:43]
	v_mfma_f32_16x16x32_bf16 v[36:39], v[170:173], v[206:209], v[36:39]
	ds_read_b128 v[158:161], v141 offset:8192
	ds_read_b128 v[162:165], v141 offset:10240
	ds_read_b128 v[166:169], v141 offset:12288
	ds_read_b128 v[170:173], v141 offset:14336
	s_waitcnt lgkmcnt(4)
	v_mfma_f32_16x16x32_bf16 v[124:127], v[142:145], v[174:177], v[124:127]
	v_mfma_f32_16x16x32_bf16 v[120:123], v[142:145], v[182:185], v[120:123]
	v_mfma_f32_16x16x32_bf16 v[116:119], v[142:145], v[186:189], v[116:119]
	v_mfma_f32_16x16x32_bf16 v[112:115], v[142:145], v[190:193], v[112:115]
	v_mfma_f32_16x16x32_bf16 v[108:111], v[146:149], v[174:177], v[108:111]
	v_mfma_f32_16x16x32_bf16 v[104:107], v[146:149], v[182:185], v[104:107]
	v_mfma_f32_16x16x32_bf16 v[100:103], v[146:149], v[186:189], v[100:103]
	v_mfma_f32_16x16x32_bf16 v[96:99], v[146:149], v[190:193], v[96:99]
	v_mfma_f32_16x16x32_bf16 v[92:95], v[150:153], v[174:177], v[92:95]
	v_mfma_f32_16x16x32_bf16 v[88:91], v[150:153], v[182:185], v[88:91]
	v_mfma_f32_16x16x32_bf16 v[84:87], v[150:153], v[186:189], v[84:87]
	v_mfma_f32_16x16x32_bf16 v[80:83], v[150:153], v[190:193], v[80:83]
	v_mfma_f32_16x16x32_bf16 v[76:79], v[154:157], v[174:177], v[76:79]
	v_mfma_f32_16x16x32_bf16 v[72:75], v[154:157], v[182:185], v[72:75]
	v_mfma_f32_16x16x32_bf16 v[68:71], v[154:157], v[186:189], v[68:71]
	v_mfma_f32_16x16x32_bf16 v[64:67], v[154:157], v[190:193], v[64:67]
	ds_read_b128 v[142:145], v180
	ds_read_b128 v[146:149], v180 offset:2048
	ds_read_b128 v[150:153], v180 offset:4096
	ds_read_b128 v[154:157], v180 offset:6144
	ds_read_b128 v[194:197], v211 offset:32768
	ds_read_b128 v[198:201], v211 offset:34816
	ds_read_b128 v[202:205], v211 offset:36864
	ds_read_b128 v[206:209], v211 offset:38912
	s_waitcnt lgkmcnt(8)
	v_mfma_f32_16x16x32_bf16 v[60:63], v[158:161], v[174:177], v[60:63]
	v_mfma_f32_16x16x32_bf16 v[56:59], v[158:161], v[182:185], v[56:59]
	v_mfma_f32_16x16x32_bf16 v[52:55], v[158:161], v[186:189], v[52:55]
	v_mfma_f32_16x16x32_bf16 v[48:51], v[158:161], v[190:193], v[48:51]
	v_mfma_f32_16x16x32_bf16 v[44:47], v[162:165], v[174:177], v[44:47]
	v_mfma_f32_16x16x32_bf16 v[32:35], v[162:165], v[182:185], v[32:35]
	v_mfma_f32_16x16x32_bf16 v[28:31], v[162:165], v[186:189], v[28:31]
	v_mfma_f32_16x16x32_bf16 v[24:27], v[162:165], v[190:193], v[24:27]
	v_mfma_f32_16x16x32_bf16 v[20:23], v[166:169], v[174:177], v[20:23]
	v_mfma_f32_16x16x32_bf16 v[16:19], v[166:169], v[182:185], v[16:19]
	v_mfma_f32_16x16x32_bf16 v[12:15], v[166:169], v[186:189], v[12:15]
	v_mfma_f32_16x16x32_bf16 v[8:11], v[166:169], v[190:193], v[8:11]
	v_mfma_f32_16x16x32_bf16 v[4:7], v[170:173], v[174:177], v[4:7]
	v_mfma_f32_16x16x32_bf16 v[0:3], v[170:173], v[182:185], v[0:3]
	v_mfma_f32_16x16x32_bf16 v[40:43], v[170:173], v[186:189], v[40:43]
	v_mfma_f32_16x16x32_bf16 v[36:39], v[170:173], v[190:193], v[36:39]
	ds_read_b128 v[158:161], v180 offset:8192
	ds_read_b128 v[162:165], v180 offset:10240
	ds_read_b128 v[166:169], v180 offset:12288
	ds_read_b128 v[170:173], v180 offset:14336
	s_waitcnt lgkmcnt(4)
	v_mfma_f32_16x16x32_bf16 v[124:127], v[142:145], v[194:197], v[124:127]
	v_mfma_f32_16x16x32_bf16 v[120:123], v[142:145], v[198:201], v[120:123]
	v_mfma_f32_16x16x32_bf16 v[116:119], v[142:145], v[202:205], v[116:119]
	v_mfma_f32_16x16x32_bf16 v[112:115], v[142:145], v[206:209], v[112:115]
	v_mfma_f32_16x16x32_bf16 v[108:111], v[146:149], v[194:197], v[108:111]
	v_mfma_f32_16x16x32_bf16 v[104:107], v[146:149], v[198:201], v[104:107]
	v_mfma_f32_16x16x32_bf16 v[100:103], v[146:149], v[202:205], v[100:103]
	v_mfma_f32_16x16x32_bf16 v[96:99], v[146:149], v[206:209], v[96:99]
	v_mfma_f32_16x16x32_bf16 v[92:95], v[150:153], v[194:197], v[92:95]
	v_mfma_f32_16x16x32_bf16 v[88:91], v[150:153], v[198:201], v[88:91]
	v_mfma_f32_16x16x32_bf16 v[84:87], v[150:153], v[202:205], v[84:87]
	v_mfma_f32_16x16x32_bf16 v[80:83], v[150:153], v[206:209], v[80:83]
	v_mfma_f32_16x16x32_bf16 v[76:79], v[154:157], v[194:197], v[76:79]
	v_mfma_f32_16x16x32_bf16 v[72:75], v[154:157], v[198:201], v[72:75]
	v_mfma_f32_16x16x32_bf16 v[68:71], v[154:157], v[202:205], v[68:71]
	v_mfma_f32_16x16x32_bf16 v[64:67], v[154:157], v[206:209], v[64:67]
	s_add_u32 s44, s44, 0x80
	s_addc_u32 s45, s45, 0
	s_add_i32 s43, s43, 1
	s_waitcnt lgkmcnt(0)
	s_waitcnt vmcnt(0)
	s_barrier
	v_mfma_f32_16x16x32_bf16 v[60:63], v[158:161], v[194:197], v[60:63]
	v_mfma_f32_16x16x32_bf16 v[56:59], v[158:161], v[198:201], v[56:59]
	v_mfma_f32_16x16x32_bf16 v[52:55], v[158:161], v[202:205], v[52:55]
	v_mfma_f32_16x16x32_bf16 v[48:51], v[158:161], v[206:209], v[48:51]
	v_mfma_f32_16x16x32_bf16 v[44:47], v[162:165], v[194:197], v[44:47]
	v_mfma_f32_16x16x32_bf16 v[32:35], v[162:165], v[198:201], v[32:35]
	v_mfma_f32_16x16x32_bf16 v[28:31], v[162:165], v[202:205], v[28:31]
	v_mfma_f32_16x16x32_bf16 v[24:27], v[162:165], v[206:209], v[24:27]
	v_mfma_f32_16x16x32_bf16 v[20:23], v[166:169], v[194:197], v[20:23]
	v_mfma_f32_16x16x32_bf16 v[16:19], v[166:169], v[198:201], v[16:19]
	v_mfma_f32_16x16x32_bf16 v[12:15], v[166:169], v[202:205], v[12:15]
	v_mfma_f32_16x16x32_bf16 v[8:11], v[166:169], v[206:209], v[8:11]
	v_mfma_f32_16x16x32_bf16 v[4:7], v[170:173], v[194:197], v[4:7]
	v_mfma_f32_16x16x32_bf16 v[0:3], v[170:173], v[198:201], v[0:3]
	v_mfma_f32_16x16x32_bf16 v[40:43], v[170:173], v[202:205], v[40:43]
	v_mfma_f32_16x16x32_bf16 v[36:39], v[170:173], v[206:209], v[36:39]
	s_nop 7
	s_nop 7
	s_sub_u32 s44, s44, s34
	s_subb_u32 s45, s45, s35
	s_mov_b32 s59, 0x100000
	s_mov_b32 s60, 0x100000
	s_mov_b64 s[46:47], 0
	s_mov_b64 vcc, exec
	s_branch .LBB0_1330

.Lg10_top:
	s_waitcnt lgkmcnt(0)
	s_waitcnt vmcnt(0)
	s_barrier
	v_xor_b32_e32 v143, 0x10000, v143
	v_xor_b32_e32 v180, 0x10000, v180
	v_xor_b32_e32 v155, 0x10000, v155
	v_xor_b32_e32 v222, 0x10000, v222
	s_xor_b32 s57, s57, 0x10000
	ds_read_b128 v[156:159], v143
	ds_read_b128 v[160:163], v143 offset:2048
	ds_read_b128 v[164:167], v143 offset:4096
	ds_read_b128 v[168:171], v143 offset:6144
	ds_read_b128 v[190:193], v180 offset:32768
	ds_read_b128 v[194:197], v180 offset:34816
	ds_read_b128 v[198:201], v180 offset:36864
	ds_read_b128 v[202:205], v180 offset:38912
	v_mfma_f32_16x16x32_bf16 v[60:63], v[172:175], v[206:209], v[60:63]
	v_mfma_f32_16x16x32_bf16 v[52:55], v[172:175], v[210:213], v[52:55]
	v_mfma_f32_16x16x32_bf16 v[56:59], v[172:175], v[214:217], v[56:59]
	v_mfma_f32_16x16x32_bf16 v[48:51], v[172:175], v[218:221], v[48:51]
	s_mov_b32 m0, s57
	s_add_u32 s46, s44, s14
	s_addc_u32 s47, s45, s15
	global_load_lds_dwordx4 v144, s[46:47]
	v_mfma_f32_16x16x32_bf16 v[44:47], v[176:179], v[206:209], v[44:47]
	v_mfma_f32_16x16x32_bf16 v[36:39], v[176:179], v[210:213], v[36:39]
	v_mfma_f32_16x16x32_bf16 v[40:43], v[176:179], v[214:217], v[40:43]
	v_mfma_f32_16x16x32_bf16 v[32:35], v[176:179], v[218:221], v[32:35]
	s_add_u32 m0, s57, 0x2000
	s_add_u32 s46, s44, s16
	s_addc_u32 s47, s45, s17
	global_load_lds_dwordx4 v144, s[46:47]
	v_mfma_f32_16x16x32_bf16 v[28:31], v[182:185], v[206:209], v[28:31]
	v_mfma_f32_16x16x32_bf16 v[16:19], v[182:185], v[210:213], v[16:19]
	v_mfma_f32_16x16x32_bf16 v[24:27], v[182:185], v[214:217], v[24:27]
	v_mfma_f32_16x16x32_bf16 v[12:15], v[182:185], v[218:221], v[12:15]
	s_add_u32 m0, s57, 0x4000
	s_add_u32 s46, s44, s18
	s_addc_u32 s47, s45, s19
	global_load_lds_dwordx4 v144, s[46:47]
	v_mfma_f32_16x16x32_bf16 v[4:7], v[186:189], v[206:209], v[4:7]
	v_mfma_f32_16x16x32_bf16 v[0:3], v[186:189], v[210:213], v[0:3]
	v_mfma_f32_16x16x32_bf16 v[20:23], v[186:189], v[214:217], v[20:23]
	v_mfma_f32_16x16x32_bf16 v[8:11], v[186:189], v[218:221], v[8:11]
	s_add_u32 m0, s57, 0x6000
	s_add_u32 s46, s44, s22
	s_addc_u32 s47, s45, s23
	global_load_lds_dwordx4 v144, s[46:47]
.Lg10_entry:
	ds_read_b128 v[172:175], v143 offset:8192
	ds_read_b128 v[176:179], v143 offset:10240
	ds_read_b128 v[182:185], v143 offset:12288
	ds_read_b128 v[186:189], v143 offset:14336
	s_waitcnt lgkmcnt(4)
	v_mfma_f32_16x16x32_bf16 v[124:127], v[156:159], v[190:193], v[124:127]
	v_mfma_f32_16x16x32_bf16 v[116:119], v[156:159], v[194:197], v[116:119]
	v_mfma_f32_16x16x32_bf16 v[120:123], v[156:159], v[198:201], v[120:123]
	v_mfma_f32_16x16x32_bf16 v[112:115], v[156:159], v[202:205], v[112:115]
	s_add_u32 m0, s57, 0x8000
	s_add_u32 s46, s44, s30
	s_addc_u32 s47, s45, s31
	global_load_lds_dwordx4 v145, s[46:47]
	v_mfma_f32_16x16x32_bf16 v[108:111], v[160:163], v[190:193], v[108:111]
	v_mfma_f32_16x16x32_bf16 v[100:103], v[160:163], v[194:197], v[100:103]
	v_mfma_f32_16x16x32_bf16 v[104:107], v[160:163], v[198:201], v[104:107]
	v_mfma_f32_16x16x32_bf16 v[96:99], v[160:163], v[202:205], v[96:99]
	s_add_u32 m0, s57, 0xa000
	s_add_u32 s46, s44, s36
	s_addc_u32 s47, s45, s37
	global_load_lds_dwordx4 v145, s[46:47]
	v_mfma_f32_16x16x32_bf16 v[92:95], v[164:167], v[190:193], v[92:95]
	v_mfma_f32_16x16x32_bf16 v[84:87], v[164:167], v[194:197], v[84:87]
	v_mfma_f32_16x16x32_bf16 v[88:91], v[164:167], v[198:201], v[88:91]
	v_mfma_f32_16x16x32_bf16 v[80:83], v[164:167], v[202:205], v[80:83]
	s_add_u32 m0, s57, 0xc000
	s_add_u32 s46, s44, s38
	s_addc_u32 s47, s45, s39
	global_load_lds_dwordx4 v145, s[46:47]
	v_mfma_f32_16x16x32_bf16 v[76:79], v[168:171], v[190:193], v[76:79]
	v_mfma_f32_16x16x32_bf16 v[68:71], v[168:171], v[194:197], v[68:71]
	v_mfma_f32_16x16x32_bf16 v[72:75], v[168:171], v[198:201], v[72:75]
	v_mfma_f32_16x16x32_bf16 v[64:67], v[168:171], v[202:205], v[64:67]
	s_add_u32 m0, s57, 0xe000
	s_add_u32 s46, s44, s40
	s_addc_u32 s47, s45, s41
	global_load_lds_dwordx4 v145, s[46:47]
	ds_read_b128 v[156:159], v155
	ds_read_b128 v[160:163], v155 offset:2048
	ds_read_b128 v[164:167], v155 offset:4096
	ds_read_b128 v[168:171], v155 offset:6144
	ds_read_b128 v[206:209], v222 offset:32768
	ds_read_b128 v[210:213], v222 offset:34816
	ds_read_b128 v[214:217], v222 offset:36864
	ds_read_b128 v[218:221], v222 offset:38912
	s_waitcnt lgkmcnt(8)
	v_mfma_f32_16x16x32_bf16 v[60:63], v[172:175], v[190:193], v[60:63]
	v_mfma_f32_16x16x32_bf16 v[52:55], v[172:175], v[194:197], v[52:55]
	v_mfma_f32_16x16x32_bf16 v[56:59], v[172:175], v[198:201], v[56:59]
	v_mfma_f32_16x16x32_bf16 v[48:51], v[172:175], v[202:205], v[48:51]
	v_mfma_f32_16x16x32_bf16 v[44:47], v[176:179], v[190:193], v[44:47]
	v_mfma_f32_16x16x32_bf16 v[36:39], v[176:179], v[194:197], v[36:39]
	v_mfma_f32_16x16x32_bf16 v[40:43], v[176:179], v[198:201], v[40:43]
	v_mfma_f32_16x16x32_bf16 v[32:35], v[176:179], v[202:205], v[32:35]
	v_mfma_f32_16x16x32_bf16 v[28:31], v[182:185], v[190:193], v[28:31]
	v_mfma_f32_16x16x32_bf16 v[16:19], v[182:185], v[194:197], v[16:19]
	v_mfma_f32_16x16x32_bf16 v[24:27], v[182:185], v[198:201], v[24:27]
	v_mfma_f32_16x16x32_bf16 v[12:15], v[182:185], v[202:205], v[12:15]
	v_mfma_f32_16x16x32_bf16 v[4:7], v[186:189], v[190:193], v[4:7]
	v_mfma_f32_16x16x32_bf16 v[0:3], v[186:189], v[194:197], v[0:3]
	v_mfma_f32_16x16x32_bf16 v[20:23], v[186:189], v[198:201], v[20:23]
	v_mfma_f32_16x16x32_bf16 v[8:11], v[186:189], v[202:205], v[8:11]
	ds_read_b128 v[172:175], v155 offset:8192
	ds_read_b128 v[176:179], v155 offset:10240
	ds_read_b128 v[182:185], v155 offset:12288
	ds_read_b128 v[186:189], v155 offset:14336
	s_waitcnt lgkmcnt(4)
	v_mfma_f32_16x16x32_bf16 v[124:127], v[156:159], v[206:209], v[124:127]
	v_mfma_f32_16x16x32_bf16 v[116:119], v[156:159], v[210:213], v[116:119]
	v_mfma_f32_16x16x32_bf16 v[120:123], v[156:159], v[214:217], v[120:123]
	v_mfma_f32_16x16x32_bf16 v[112:115], v[156:159], v[218:221], v[112:115]
	v_mfma_f32_16x16x32_bf16 v[108:111], v[160:163], v[206:209], v[108:111]
	v_mfma_f32_16x16x32_bf16 v[100:103], v[160:163], v[210:213], v[100:103]
	v_mfma_f32_16x16x32_bf16 v[104:107], v[160:163], v[214:217], v[104:107]
	v_mfma_f32_16x16x32_bf16 v[96:99], v[160:163], v[218:221], v[96:99]
	v_mfma_f32_16x16x32_bf16 v[92:95], v[164:167], v[206:209], v[92:95]
	v_mfma_f32_16x16x32_bf16 v[84:87], v[164:167], v[210:213], v[84:87]
	v_mfma_f32_16x16x32_bf16 v[88:91], v[164:167], v[214:217], v[88:91]
	v_mfma_f32_16x16x32_bf16 v[80:83], v[164:167], v[218:221], v[80:83]
	v_mfma_f32_16x16x32_bf16 v[76:79], v[168:171], v[206:209], v[76:79]
	v_mfma_f32_16x16x32_bf16 v[68:71], v[168:171], v[210:213], v[68:71]
	v_mfma_f32_16x16x32_bf16 v[72:75], v[168:171], v[214:217], v[72:75]
	v_mfma_f32_16x16x32_bf16 v[64:67], v[168:171], v[218:221], v[64:67]
	s_add_u32 s44, s44, 0x80
	s_addc_u32 s45, s45, 0
	s_add_i32 s43, s43, 1
	s_cmp_lt_u32 s43, 15
	s_cbranch_scc1 .Lg10_top
	s_waitcnt lgkmcnt(0)
	s_waitcnt vmcnt(0)
	s_barrier
	v_xor_b32_e32 v143, 0x10000, v143
	v_xor_b32_e32 v180, 0x10000, v180
	v_xor_b32_e32 v155, 0x10000, v155
	v_xor_b32_e32 v222, 0x10000, v222
	s_xor_b32 s57, s57, 0x10000
	ds_read_b128 v[156:159], v143
	ds_read_b128 v[160:163], v143 offset:2048
	ds_read_b128 v[164:167], v143 offset:4096
	ds_read_b128 v[168:171], v143 offset:6144
	ds_read_b128 v[190:193], v180 offset:32768
	ds_read_b128 v[194:197], v180 offset:34816
	ds_read_b128 v[198:201], v180 offset:36864
	ds_read_b128 v[202:205], v180 offset:38912
	v_mfma_f32_16x16x32_bf16 v[60:63], v[172:175], v[206:209], v[60:63]
	v_mfma_f32_16x16x32_bf16 v[52:55], v[172:175], v[210:213], v[52:55]
	v_mfma_f32_16x16x32_bf16 v[56:59], v[172:175], v[214:217], v[56:59]
	v_mfma_f32_16x16x32_bf16 v[48:51], v[172:175], v[218:221], v[48:51]
	v_mfma_f32_16x16x32_bf16 v[44:47], v[176:179], v[206:209], v[44:47]
	v_mfma_f32_16x16x32_bf16 v[36:39], v[176:179], v[210:213], v[36:39]
	v_mfma_f32_16x16x32_bf16 v[40:43], v[176:179], v[214:217], v[40:43]
	v_mfma_f32_16x16x32_bf16 v[32:35], v[176:179], v[218:221], v[32:35]
	v_mfma_f32_16x16x32_bf16 v[28:31], v[182:185], v[206:209], v[28:31]
	v_mfma_f32_16x16x32_bf16 v[16:19], v[182:185], v[210:213], v[16:19]
	v_mfma_f32_16x16x32_bf16 v[24:27], v[182:185], v[214:217], v[24:27]
	v_mfma_f32_16x16x32_bf16 v[12:15], v[182:185], v[218:221], v[12:15]
	v_mfma_f32_16x16x32_bf16 v[4:7], v[186:189], v[206:209], v[4:7]
	v_mfma_f32_16x16x32_bf16 v[0:3], v[186:189], v[210:213], v[0:3]
	v_mfma_f32_16x16x32_bf16 v[20:23], v[186:189], v[214:217], v[20:23]
	v_mfma_f32_16x16x32_bf16 v[8:11], v[186:189], v[218:221], v[8:11]
	ds_read_b128 v[172:175], v143 offset:8192
	ds_read_b128 v[176:179], v143 offset:10240
	ds_read_b128 v[182:185], v143 offset:12288
	ds_read_b128 v[186:189], v143 offset:14336
	s_waitcnt lgkmcnt(4)
	v_mfma_f32_16x16x32_bf16 v[124:127], v[156:159], v[190:193], v[124:127]
	v_mfma_f32_16x16x32_bf16 v[116:119], v[156:159], v[194:197], v[116:119]
	v_mfma_f32_16x16x32_bf16 v[120:123], v[156:159], v[198:201], v[120:123]
	v_mfma_f32_16x16x32_bf16 v[112:115], v[156:159], v[202:205], v[112:115]
	v_mfma_f32_16x16x32_bf16 v[108:111], v[160:163], v[190:193], v[108:111]
	v_mfma_f32_16x16x32_bf16 v[100:103], v[160:163], v[194:197], v[100:103]
	v_mfma_f32_16x16x32_bf16 v[104:107], v[160:163], v[198:201], v[104:107]
	v_mfma_f32_16x16x32_bf16 v[96:99], v[160:163], v[202:205], v[96:99]
	v_mfma_f32_16x16x32_bf16 v[92:95], v[164:167], v[190:193], v[92:95]
	v_mfma_f32_16x16x32_bf16 v[84:87], v[164:167], v[194:197], v[84:87]
	v_mfma_f32_16x16x32_bf16 v[88:91], v[164:167], v[198:201], v[88:91]
	v_mfma_f32_16x16x32_bf16 v[80:83], v[164:167], v[202:205], v[80:83]
	v_mfma_f32_16x16x32_bf16 v[76:79], v[168:171], v[190:193], v[76:79]
	v_mfma_f32_16x16x32_bf16 v[68:71], v[168:171], v[194:197], v[68:71]
	v_mfma_f32_16x16x32_bf16 v[72:75], v[168:171], v[198:201], v[72:75]
	v_mfma_f32_16x16x32_bf16 v[64:67], v[168:171], v[202:205], v[64:67]
	ds_read_b128 v[156:159], v155
	ds_read_b128 v[160:163], v155 offset:2048
	ds_read_b128 v[164:167], v155 offset:4096
	ds_read_b128 v[168:171], v155 offset:6144
	ds_read_b128 v[206:209], v222 offset:32768
	ds_read_b128 v[210:213], v222 offset:34816
	ds_read_b128 v[214:217], v222 offset:36864
	ds_read_b128 v[218:221], v222 offset:38912
	s_waitcnt lgkmcnt(8)
	v_mfma_f32_16x16x32_bf16 v[60:63], v[172:175], v[190:193], v[60:63]
	v_mfma_f32_16x16x32_bf16 v[52:55], v[172:175], v[194:197], v[52:55]
	v_mfma_f32_16x16x32_bf16 v[56:59], v[172:175], v[198:201], v[56:59]
	v_mfma_f32_16x16x32_bf16 v[48:51], v[172:175], v[202:205], v[48:51]
	v_mfma_f32_16x16x32_bf16 v[44:47], v[176:179], v[190:193], v[44:47]
	v_mfma_f32_16x16x32_bf16 v[36:39], v[176:179], v[194:197], v[36:39]
	v_mfma_f32_16x16x32_bf16 v[40:43], v[176:179], v[198:201], v[40:43]
	v_mfma_f32_16x16x32_bf16 v[32:35], v[176:179], v[202:205], v[32:35]
	v_mfma_f32_16x16x32_bf16 v[28:31], v[182:185], v[190:193], v[28:31]
	v_mfma_f32_16x16x32_bf16 v[16:19], v[182:185], v[194:197], v[16:19]
	v_mfma_f32_16x16x32_bf16 v[24:27], v[182:185], v[198:201], v[24:27]
	v_mfma_f32_16x16x32_bf16 v[12:15], v[182:185], v[202:205], v[12:15]
	v_mfma_f32_16x16x32_bf16 v[4:7], v[186:189], v[190:193], v[4:7]
	v_mfma_f32_16x16x32_bf16 v[0:3], v[186:189], v[194:197], v[0:3]
	v_mfma_f32_16x16x32_bf16 v[20:23], v[186:189], v[198:201], v[20:23]
	v_mfma_f32_16x16x32_bf16 v[8:11], v[186:189], v[202:205], v[8:11]
	ds_read_b128 v[172:175], v155 offset:8192
	ds_read_b128 v[176:179], v155 offset:10240
	ds_read_b128 v[182:185], v155 offset:12288
	ds_read_b128 v[186:189], v155 offset:14336
	s_waitcnt lgkmcnt(4)
	v_mfma_f32_16x16x32_bf16 v[124:127], v[156:159], v[206:209], v[124:127]
	v_mfma_f32_16x16x32_bf16 v[116:119], v[156:159], v[210:213], v[116:119]
	v_mfma_f32_16x16x32_bf16 v[120:123], v[156:159], v[214:217], v[120:123]
	v_mfma_f32_16x16x32_bf16 v[112:115], v[156:159], v[218:221], v[112:115]
	v_mfma_f32_16x16x32_bf16 v[108:111], v[160:163], v[206:209], v[108:111]
	v_mfma_f32_16x16x32_bf16 v[100:103], v[160:163], v[210:213], v[100:103]
	v_mfma_f32_16x16x32_bf16 v[104:107], v[160:163], v[214:217], v[104:107]
	v_mfma_f32_16x16x32_bf16 v[96:99], v[160:163], v[218:221], v[96:99]
	v_mfma_f32_16x16x32_bf16 v[92:95], v[164:167], v[206:209], v[92:95]
	v_mfma_f32_16x16x32_bf16 v[84:87], v[164:167], v[210:213], v[84:87]
	v_mfma_f32_16x16x32_bf16 v[88:91], v[164:167], v[214:217], v[88:91]
	v_mfma_f32_16x16x32_bf16 v[80:83], v[164:167], v[218:221], v[80:83]
	v_mfma_f32_16x16x32_bf16 v[76:79], v[168:171], v[206:209], v[76:79]
	v_mfma_f32_16x16x32_bf16 v[68:71], v[168:171], v[210:213], v[68:71]
	v_mfma_f32_16x16x32_bf16 v[72:75], v[168:171], v[214:217], v[72:75]
	v_mfma_f32_16x16x32_bf16 v[64:67], v[168:171], v[218:221], v[64:67]
	s_add_u32 s44, s44, 0x80
	s_addc_u32 s45, s45, 0
	s_add_i32 s43, s43, 1
	s_waitcnt lgkmcnt(0)
	s_waitcnt vmcnt(0)
	s_barrier
	v_mfma_f32_16x16x32_bf16 v[60:63], v[172:175], v[206:209], v[60:63]
	v_mfma_f32_16x16x32_bf16 v[52:55], v[172:175], v[210:213], v[52:55]
	v_mfma_f32_16x16x32_bf16 v[56:59], v[172:175], v[214:217], v[56:59]
	v_mfma_f32_16x16x32_bf16 v[48:51], v[172:175], v[218:221], v[48:51]
	v_mfma_f32_16x16x32_bf16 v[44:47], v[176:179], v[206:209], v[44:47]
	v_mfma_f32_16x16x32_bf16 v[36:39], v[176:179], v[210:213], v[36:39]
	v_mfma_f32_16x16x32_bf16 v[40:43], v[176:179], v[214:217], v[40:43]
	v_mfma_f32_16x16x32_bf16 v[32:35], v[176:179], v[218:221], v[32:35]
	v_mfma_f32_16x16x32_bf16 v[28:31], v[182:185], v[206:209], v[28:31]
	v_mfma_f32_16x16x32_bf16 v[16:19], v[182:185], v[210:213], v[16:19]
	v_mfma_f32_16x16x32_bf16 v[24:27], v[182:185], v[214:217], v[24:27]
	v_mfma_f32_16x16x32_bf16 v[12:15], v[182:185], v[218:221], v[12:15]
	v_mfma_f32_16x16x32_bf16 v[4:7], v[186:189], v[206:209], v[4:7]
	v_mfma_f32_16x16x32_bf16 v[0:3], v[186:189], v[210:213], v[0:3]
	v_mfma_f32_16x16x32_bf16 v[20:23], v[186:189], v[214:217], v[20:23]
	v_mfma_f32_16x16x32_bf16 v[8:11], v[186:189], v[218:221], v[8:11]
	s_nop 7
	s_nop 7
	s_sub_u32 s44, s44, s34
	s_subb_u32 s45, s45, s35
	s_mov_b32 s57, 0x80000
	s_mov_b32 s58, 0x80000
	s_mov_b64 s[46:47], 0
	s_mov_b64 vcc, exec
	s_branch .LBB0_1494

.Lg11_top:
	s_waitcnt lgkmcnt(0)
	s_waitcnt vmcnt(0)
	s_barrier
	v_xor_b32_e32 v141, 0x10000, v141
	v_xor_b32_e32 v210, 0x10000, v210
	v_xor_b32_e32 v180, 0x10000, v180
	v_xor_b32_e32 v211, 0x10000, v211
	s_xor_b32 s45, s45, 0x10000
	ds_read_b128 v[142:145], v141
	ds_read_b128 v[146:149], v141 offset:2048
	ds_read_b128 v[150:153], v141 offset:4096
	ds_read_b128 v[154:157], v141 offset:6144
	ds_read_b128 v[174:177], v210 offset:32768
	ds_read_b128 v[182:185], v210 offset:34816
	ds_read_b128 v[186:189], v210 offset:36864
	ds_read_b128 v[190:193], v210 offset:38912
	v_mfma_f32_16x16x32_bf16 v[60:63], v[158:161], v[194:197], v[60:63]
	v_mfma_f32_16x16x32_bf16 v[56:59], v[158:161], v[198:201], v[56:59]
	v_mfma_f32_16x16x32_bf16 v[52:55], v[158:161], v[202:205], v[52:55]
	v_mfma_f32_16x16x32_bf16 v[48:51], v[158:161], v[206:209], v[48:51]
	s_mov_b32 m0, s45
	s_add_u32 s38, s36, s12
	s_addc_u32 s39, s37, s13
	global_load_lds_dwordx4 v178, s[38:39]
	v_mfma_f32_16x16x32_bf16 v[44:47], v[162:165], v[194:197], v[44:47]
	v_mfma_f32_16x16x32_bf16 v[32:35], v[162:165], v[198:201], v[32:35]
	v_mfma_f32_16x16x32_bf16 v[28:31], v[162:165], v[202:205], v[28:31]
	v_mfma_f32_16x16x32_bf16 v[24:27], v[162:165], v[206:209], v[24:27]
	s_add_u32 m0, s45, 0x2000
	s_add_u32 s38, s36, s14
	s_addc_u32 s39, s37, s15
	global_load_lds_dwordx4 v178, s[38:39]
	v_mfma_f32_16x16x32_bf16 v[20:23], v[166:169], v[194:197], v[20:23]
	v_mfma_f32_16x16x32_bf16 v[16:19], v[166:169], v[198:201], v[16:19]
	v_mfma_f32_16x16x32_bf16 v[12:15], v[166:169], v[202:205], v[12:15]
	v_mfma_f32_16x16x32_bf16 v[8:11], v[166:169], v[206:209], v[8:11]
	s_add_u32 m0, s45, 0x4000
	s_add_u32 s38, s36, s16
	s_addc_u32 s39, s37, s17
	global_load_lds_dwordx4 v178, s[38:39]
	v_mfma_f32_16x16x32_bf16 v[4:7], v[170:173], v[194:197], v[4:7]
	v_mfma_f32_16x16x32_bf16 v[0:3], v[170:173], v[198:201], v[0:3]
	v_mfma_f32_16x16x32_bf16 v[40:43], v[170:173], v[202:205], v[40:43]
	v_mfma_f32_16x16x32_bf16 v[36:39], v[170:173], v[206:209], v[36:39]
	s_add_u32 m0, s45, 0x6000
	s_add_u32 s38, s36, s18
	s_addc_u32 s39, s37, s19
	global_load_lds_dwordx4 v178, s[38:39]
.Lg11_entry:
	ds_read_b128 v[158:161], v141 offset:8192
	ds_read_b128 v[162:165], v141 offset:10240
	ds_read_b128 v[166:169], v141 offset:12288
	ds_read_b128 v[170:173], v141 offset:14336
	s_waitcnt lgkmcnt(4)
	v_mfma_f32_16x16x32_bf16 v[124:127], v[142:145], v[174:177], v[124:127]
	v_mfma_f32_16x16x32_bf16 v[120:123], v[142:145], v[182:185], v[120:123]
	v_mfma_f32_16x16x32_bf16 v[116:119], v[142:145], v[186:189], v[116:119]
	v_mfma_f32_16x16x32_bf16 v[112:115], v[142:145], v[190:193], v[112:115]
	s_add_u32 m0, s45, 0x8000
	s_add_u32 s38, s36, s22
	s_addc_u32 s39, s37, s23
	global_load_lds_dwordx4 v179, s[38:39]
	v_mfma_f32_16x16x32_bf16 v[108:111], v[146:149], v[174:177], v[108:111]
	v_mfma_f32_16x16x32_bf16 v[104:107], v[146:149], v[182:185], v[104:107]
	v_mfma_f32_16x16x32_bf16 v[100:103], v[146:149], v[186:189], v[100:103]
	v_mfma_f32_16x16x32_bf16 v[96:99], v[146:149], v[190:193], v[96:99]
	s_add_u32 m0, s45, 0xa000
	s_add_u32 s38, s36, s24
	s_addc_u32 s39, s37, s25
	global_load_lds_dwordx4 v179, s[38:39]
	v_mfma_f32_16x16x32_bf16 v[92:95], v[150:153], v[174:177], v[92:95]
	v_mfma_f32_16x16x32_bf16 v[88:91], v[150:153], v[182:185], v[88:91]
	v_mfma_f32_16x16x32_bf16 v[84:87], v[150:153], v[186:189], v[84:87]
	v_mfma_f32_16x16x32_bf16 v[80:83], v[150:153], v[190:193], v[80:83]
	s_add_u32 m0, s45, 0xc000
	s_add_u32 s38, s36, s26
	s_addc_u32 s39, s37, s27
	global_load_lds_dwordx4 v179, s[38:39]
	v_mfma_f32_16x16x32_bf16 v[76:79], v[154:157], v[174:177], v[76:79]
	v_mfma_f32_16x16x32_bf16 v[72:75], v[154:157], v[182:185], v[72:75]
	v_mfma_f32_16x16x32_bf16 v[68:71], v[154:157], v[186:189], v[68:71]
	v_mfma_f32_16x16x32_bf16 v[64:67], v[154:157], v[190:193], v[64:67]
	s_add_u32 m0, s45, 0xe000
	s_add_u32 s38, s36, s28
	s_addc_u32 s39, s37, s29
	global_load_lds_dwordx4 v179, s[38:39]
	ds_read_b128 v[142:145], v180
	ds_read_b128 v[146:149], v180 offset:2048
	ds_read_b128 v[150:153], v180 offset:4096
	ds_read_b128 v[154:157], v180 offset:6144
	ds_read_b128 v[194:197], v211 offset:32768
	ds_read_b128 v[198:201], v211 offset:34816
	ds_read_b128 v[202:205], v211 offset:36864
	ds_read_b128 v[206:209], v211 offset:38912
	s_waitcnt lgkmcnt(8)
	v_mfma_f32_16x16x32_bf16 v[60:63], v[158:161], v[174:177], v[60:63]
	v_mfma_f32_16x16x32_bf16 v[56:59], v[158:161], v[182:185], v[56:59]
	v_mfma_f32_16x16x32_bf16 v[52:55], v[158:161], v[186:189], v[52:55]
	v_mfma_f32_16x16x32_bf16 v[48:51], v[158:161], v[190:193], v[48:51]
	v_mfma_f32_16x16x32_bf16 v[44:47], v[162:165], v[174:177], v[44:47]
	v_mfma_f32_16x16x32_bf16 v[32:35], v[162:165], v[182:185], v[32:35]
	v_mfma_f32_16x16x32_bf16 v[28:31], v[162:165], v[186:189], v[28:31]
	v_mfma_f32_16x16x32_bf16 v[24:27], v[162:165], v[190:193], v[24:27]
	v_mfma_f32_16x16x32_bf16 v[20:23], v[166:169], v[174:177], v[20:23]
	v_mfma_f32_16x16x32_bf16 v[16:19], v[166:169], v[182:185], v[16:19]
	v_mfma_f32_16x16x32_bf16 v[12:15], v[166:169], v[186:189], v[12:15]
	v_mfma_f32_16x16x32_bf16 v[8:11], v[166:169], v[190:193], v[8:11]
	v_mfma_f32_16x16x32_bf16 v[4:7], v[170:173], v[174:177], v[4:7]
	v_mfma_f32_16x16x32_bf16 v[0:3], v[170:173], v[182:185], v[0:3]
	v_mfma_f32_16x16x32_bf16 v[40:43], v[170:173], v[186:189], v[40:43]
	v_mfma_f32_16x16x32_bf16 v[36:39], v[170:173], v[190:193], v[36:39]
	ds_read_b128 v[158:161], v180 offset:8192
	ds_read_b128 v[162:165], v180 offset:10240
	ds_read_b128 v[166:169], v180 offset:12288
	ds_read_b128 v[170:173], v180 offset:14336
	s_waitcnt lgkmcnt(4)
	v_mfma_f32_16x16x32_bf16 v[124:127], v[142:145], v[194:197], v[124:127]
	v_mfma_f32_16x16x32_bf16 v[120:123], v[142:145], v[198:201], v[120:123]
	v_mfma_f32_16x16x32_bf16 v[116:119], v[142:145], v[202:205], v[116:119]
	v_mfma_f32_16x16x32_bf16 v[112:115], v[142:145], v[206:209], v[112:115]
	v_mfma_f32_16x16x32_bf16 v[108:111], v[146:149], v[194:197], v[108:111]
	v_mfma_f32_16x16x32_bf16 v[104:107], v[146:149], v[198:201], v[104:107]
	v_mfma_f32_16x16x32_bf16 v[100:103], v[146:149], v[202:205], v[100:103]
	v_mfma_f32_16x16x32_bf16 v[96:99], v[146:149], v[206:209], v[96:99]
	v_mfma_f32_16x16x32_bf16 v[92:95], v[150:153], v[194:197], v[92:95]
	v_mfma_f32_16x16x32_bf16 v[88:91], v[150:153], v[198:201], v[88:91]
	v_mfma_f32_16x16x32_bf16 v[84:87], v[150:153], v[202:205], v[84:87]
	v_mfma_f32_16x16x32_bf16 v[80:83], v[150:153], v[206:209], v[80:83]
	v_mfma_f32_16x16x32_bf16 v[76:79], v[154:157], v[194:197], v[76:79]
	v_mfma_f32_16x16x32_bf16 v[72:75], v[154:157], v[198:201], v[72:75]
	v_mfma_f32_16x16x32_bf16 v[68:71], v[154:157], v[202:205], v[68:71]
	v_mfma_f32_16x16x32_bf16 v[64:67], v[154:157], v[206:209], v[64:67]
	s_add_u32 s36, s36, 0x80
	s_addc_u32 s37, s37, 0
	s_add_i32 s31, s31, 1
	s_cmp_lt_u32 s31, 31
	s_cbranch_scc1 .Lg11_top
	s_waitcnt lgkmcnt(0)
	s_waitcnt vmcnt(0)
	s_barrier
	v_xor_b32_e32 v141, 0x10000, v141
	v_xor_b32_e32 v210, 0x10000, v210
	v_xor_b32_e32 v180, 0x10000, v180
	v_xor_b32_e32 v211, 0x10000, v211
	s_xor_b32 s45, s45, 0x10000
	ds_read_b128 v[142:145], v141
	ds_read_b128 v[146:149], v141 offset:2048
	ds_read_b128 v[150:153], v141 offset:4096
	ds_read_b128 v[154:157], v141 offset:6144
	ds_read_b128 v[174:177], v210 offset:32768
	ds_read_b128 v[182:185], v210 offset:34816
	ds_read_b128 v[186:189], v210 offset:36864
	ds_read_b128 v[190:193], v210 offset:38912
	v_mfma_f32_16x16x32_bf16 v[60:63], v[158:161], v[194:197], v[60:63]
	v_mfma_f32_16x16x32_bf16 v[56:59], v[158:161], v[198:201], v[56:59]
	v_mfma_f32_16x16x32_bf16 v[52:55], v[158:161], v[202:205], v[52:55]
	v_mfma_f32_16x16x32_bf16 v[48:51], v[158:161], v[206:209], v[48:51]
	v_mfma_f32_16x16x32_bf16 v[44:47], v[162:165], v[194:197], v[44:47]
	v_mfma_f32_16x16x32_bf16 v[32:35], v[162:165], v[198:201], v[32:35]
	v_mfma_f32_16x16x32_bf16 v[28:31], v[162:165], v[202:205], v[28:31]
	v_mfma_f32_16x16x32_bf16 v[24:27], v[162:165], v[206:209], v[24:27]
	v_mfma_f32_16x16x32_bf16 v[20:23], v[166:169], v[194:197], v[20:23]
	v_mfma_f32_16x16x32_bf16 v[16:19], v[166:169], v[198:201], v[16:19]
	v_mfma_f32_16x16x32_bf16 v[12:15], v[166:169], v[202:205], v[12:15]
	v_mfma_f32_16x16x32_bf16 v[8:11], v[166:169], v[206:209], v[8:11]
	v_mfma_f32_16x16x32_bf16 v[4:7], v[170:173], v[194:197], v[4:7]
	v_mfma_f32_16x16x32_bf16 v[0:3], v[170:173], v[198:201], v[0:3]
	v_mfma_f32_16x16x32_bf16 v[40:43], v[170:173], v[202:205], v[40:43]
	v_mfma_f32_16x16x32_bf16 v[36:39], v[170:173], v[206:209], v[36:39]
	ds_read_b128 v[158:161], v141 offset:8192
	ds_read_b128 v[162:165], v141 offset:10240
	ds_read_b128 v[166:169], v141 offset:12288
	ds_read_b128 v[170:173], v141 offset:14336
	s_waitcnt lgkmcnt(4)
	v_mfma_f32_16x16x32_bf16 v[124:127], v[142:145], v[174:177], v[124:127]
	v_mfma_f32_16x16x32_bf16 v[120:123], v[142:145], v[182:185], v[120:123]
	v_mfma_f32_16x16x32_bf16 v[116:119], v[142:145], v[186:189], v[116:119]
	v_mfma_f32_16x16x32_bf16 v[112:115], v[142:145], v[190:193], v[112:115]
	v_mfma_f32_16x16x32_bf16 v[108:111], v[146:149], v[174:177], v[108:111]
	v_mfma_f32_16x16x32_bf16 v[104:107], v[146:149], v[182:185], v[104:107]
	v_mfma_f32_16x16x32_bf16 v[100:103], v[146:149], v[186:189], v[100:103]
	v_mfma_f32_16x16x32_bf16 v[96:99], v[146:149], v[190:193], v[96:99]
	v_mfma_f32_16x16x32_bf16 v[92:95], v[150:153], v[174:177], v[92:95]
	v_mfma_f32_16x16x32_bf16 v[88:91], v[150:153], v[182:185], v[88:91]
	v_mfma_f32_16x16x32_bf16 v[84:87], v[150:153], v[186:189], v[84:87]
	v_mfma_f32_16x16x32_bf16 v[80:83], v[150:153], v[190:193], v[80:83]
	v_mfma_f32_16x16x32_bf16 v[76:79], v[154:157], v[174:177], v[76:79]
	v_mfma_f32_16x16x32_bf16 v[72:75], v[154:157], v[182:185], v[72:75]
	v_mfma_f32_16x16x32_bf16 v[68:71], v[154:157], v[186:189], v[68:71]
	v_mfma_f32_16x16x32_bf16 v[64:67], v[154:157], v[190:193], v[64:67]
	ds_read_b128 v[142:145], v180
	ds_read_b128 v[146:149], v180 offset:2048
	ds_read_b128 v[150:153], v180 offset:4096
	ds_read_b128 v[154:157], v180 offset:6144
	ds_read_b128 v[194:197], v211 offset:32768
	ds_read_b128 v[198:201], v211 offset:34816
	ds_read_b128 v[202:205], v211 offset:36864
	ds_read_b128 v[206:209], v211 offset:38912
	s_waitcnt lgkmcnt(8)
	v_mfma_f32_16x16x32_bf16 v[60:63], v[158:161], v[174:177], v[60:63]
	v_mfma_f32_16x16x32_bf16 v[56:59], v[158:161], v[182:185], v[56:59]
	v_mfma_f32_16x16x32_bf16 v[52:55], v[158:161], v[186:189], v[52:55]
	v_mfma_f32_16x16x32_bf16 v[48:51], v[158:161], v[190:193], v[48:51]
	v_mfma_f32_16x16x32_bf16 v[44:47], v[162:165], v[174:177], v[44:47]
	v_mfma_f32_16x16x32_bf16 v[32:35], v[162:165], v[182:185], v[32:35]
	v_mfma_f32_16x16x32_bf16 v[28:31], v[162:165], v[186:189], v[28:31]
	v_mfma_f32_16x16x32_bf16 v[24:27], v[162:165], v[190:193], v[24:27]
	v_mfma_f32_16x16x32_bf16 v[20:23], v[166:169], v[174:177], v[20:23]
	v_mfma_f32_16x16x32_bf16 v[16:19], v[166:169], v[182:185], v[16:19]
	v_mfma_f32_16x16x32_bf16 v[12:15], v[166:169], v[186:189], v[12:15]
	v_mfma_f32_16x16x32_bf16 v[8:11], v[166:169], v[190:193], v[8:11]
	v_mfma_f32_16x16x32_bf16 v[4:7], v[170:173], v[174:177], v[4:7]
	v_mfma_f32_16x16x32_bf16 v[0:3], v[170:173], v[182:185], v[0:3]
	v_mfma_f32_16x16x32_bf16 v[40:43], v[170:173], v[186:189], v[40:43]
	v_mfma_f32_16x16x32_bf16 v[36:39], v[170:173], v[190:193], v[36:39]
	ds_read_b128 v[158:161], v180 offset:8192
	ds_read_b128 v[162:165], v180 offset:10240
	ds_read_b128 v[166:169], v180 offset:12288
	ds_read_b128 v[170:173], v180 offset:14336
	s_waitcnt lgkmcnt(4)
	v_mfma_f32_16x16x32_bf16 v[124:127], v[142:145], v[194:197], v[124:127]
	v_mfma_f32_16x16x32_bf16 v[120:123], v[142:145], v[198:201], v[120:123]
	v_mfma_f32_16x16x32_bf16 v[116:119], v[142:145], v[202:205], v[116:119]
	v_mfma_f32_16x16x32_bf16 v[112:115], v[142:145], v[206:209], v[112:115]
	v_mfma_f32_16x16x32_bf16 v[108:111], v[146:149], v[194:197], v[108:111]
	v_mfma_f32_16x16x32_bf16 v[104:107], v[146:149], v[198:201], v[104:107]
	v_mfma_f32_16x16x32_bf16 v[100:103], v[146:149], v[202:205], v[100:103]
	v_mfma_f32_16x16x32_bf16 v[96:99], v[146:149], v[206:209], v[96:99]
	v_mfma_f32_16x16x32_bf16 v[92:95], v[150:153], v[194:197], v[92:95]
	v_mfma_f32_16x16x32_bf16 v[88:91], v[150:153], v[198:201], v[88:91]
	v_mfma_f32_16x16x32_bf16 v[84:87], v[150:153], v[202:205], v[84:87]
	v_mfma_f32_16x16x32_bf16 v[80:83], v[150:153], v[206:209], v[80:83]
	v_mfma_f32_16x16x32_bf16 v[76:79], v[154:157], v[194:197], v[76:79]
	v_mfma_f32_16x16x32_bf16 v[72:75], v[154:157], v[198:201], v[72:75]
	v_mfma_f32_16x16x32_bf16 v[68:71], v[154:157], v[202:205], v[68:71]
	v_mfma_f32_16x16x32_bf16 v[64:67], v[154:157], v[206:209], v[64:67]
	s_add_u32 s36, s36, 0x80
	s_addc_u32 s37, s37, 0
	s_add_i32 s31, s31, 1
	s_waitcnt lgkmcnt(0)
	s_waitcnt vmcnt(0)
	s_barrier
	v_mfma_f32_16x16x32_bf16 v[60:63], v[158:161], v[194:197], v[60:63]
	v_mfma_f32_16x16x32_bf16 v[56:59], v[158:161], v[198:201], v[56:59]
	v_mfma_f32_16x16x32_bf16 v[52:55], v[158:161], v[202:205], v[52:55]
	v_mfma_f32_16x16x32_bf16 v[48:51], v[158:161], v[206:209], v[48:51]
	v_mfma_f32_16x16x32_bf16 v[44:47], v[162:165], v[194:197], v[44:47]
	v_mfma_f32_16x16x32_bf16 v[32:35], v[162:165], v[198:201], v[32:35]
	v_mfma_f32_16x16x32_bf16 v[28:31], v[162:165], v[202:205], v[28:31]
	v_mfma_f32_16x16x32_bf16 v[24:27], v[162:165], v[206:209], v[24:27]
	v_mfma_f32_16x16x32_bf16 v[20:23], v[166:169], v[194:197], v[20:23]
	v_mfma_f32_16x16x32_bf16 v[16:19], v[166:169], v[198:201], v[16:19]
	v_mfma_f32_16x16x32_bf16 v[12:15], v[166:169], v[202:205], v[12:15]
	v_mfma_f32_16x16x32_bf16 v[8:11], v[166:169], v[206:209], v[8:11]
	v_mfma_f32_16x16x32_bf16 v[4:7], v[170:173], v[194:197], v[4:7]
	v_mfma_f32_16x16x32_bf16 v[0:3], v[170:173], v[198:201], v[0:3]
	v_mfma_f32_16x16x32_bf16 v[40:43], v[170:173], v[202:205], v[40:43]
	v_mfma_f32_16x16x32_bf16 v[36:39], v[170:173], v[206:209], v[36:39]
	s_nop 7
	s_nop 7
	s_sub_u32 s36, s36, s34
	s_subb_u32 s37, s37, s35
	s_mov_b32 s45, 0x100000
	s_mov_b32 s46, 0x100000
	s_mov_b64 s[38:39], 0
	s_mov_b64 vcc, exec
	s_branch .LBB0_1635
